# K^T/V^T epilogue stores widened via in-quad DPP transpose; first down-GEMM residual loads pipelined two iterations ahead
# speedup vs baseline: 1.0035x; 1.0035x over previous
; #define PG8_STAGE(bufoff, gbase, voff) do { _Pragma("unroll") for (int _i = 0; _i < 2; ++_i) \
;         __builtin_amdgcn_global_load_lds((const unsigned*)((const char*)(gbase) + (voff)[_i]), (LAS unsigned*)(lds + (bufoff) + ldsw + _i * 8192), 16, 0, 0); } while (0)
; #define PG8_LDA(dst, b, h) do { _Pragma("unroll") for (int m = 0; m < 4; ++m) _Pragma("unroll") for (int k = 0; k < 2; ++k) dst[m][k] = *(const LAS bf16x8*)(lds + PG8_SA(b, h) + aoff + m * 2048 + k * 1024); } while (0)
; #define PG8_LDB(dst, b, h) do { _Pragma("unroll") for (int n = 0; n < 2; ++n) _Pragma("unroll") for (int k = 0; k < 2; ++k) dst[n][k] = *(const LAS bf16x8*)(lds + PG8_SB(b, h) + boff + n * 2048 + k * 1024); } while (0)
; #define PG8_MMA(ai, bj, At, Bt) do { __builtin_amdgcn_s_setprio(1); _Pragma("unroll") for (int m = 0; m < 4; ++m) _Pragma("unroll") for (int n = 0; n < 2; ++n) _Pragma("unroll") for (int k = 0; k < 2; ++k) \
;         acc[ai][bj][m][n] = __builtin_amdgcn_mfma_f32_16x16x32_bf16(Bt[n][k], At[m][k], acc[ai][bj][m][n], 0, 0, 0); __builtin_amdgcn_s_setprio(0); } while (0)
; #define PG8_WAIT_L(n) asm volatile("s_waitcnt lgkmcnt(" #n ")" ::: "memory")
; #define PG8_BAR __builtin_amdgcn_s_barrier()
; #define PG8_SCHED __builtin_amdgcn_sched_barrier(0)
; template <class Epi>
; __device__ __forceinline__ void gemm_phase(LAS unsigned char* lds, const Gemm g, const Order& S, KP kp, int code, int wv) {
;     ...
;             PG8_LDB(B0, 0, 0); PG8_SCHED; PG8_LDA(At, 0, 0); PG8_STAGE(PG8_SA(1, 1), a1 + hstepA, voffA);
;             PG8_WAIT_L(8); PG8_BAR; PG8_WAIT_L(0); PG8_MMA(0, 0, At, B0); PG8_BAR; PG8_SCHED;
;             PG8_LDB(B1, 0, 1); PG8_STAGE(PG8_SB(0, 0), b2, voffB);
;             PG8_BAR; PG8_WAIT_L(0); PG8_MMA(0, 1, At, B1); PG8_BAR;
;             PG8_LDA(At, 0, 1); PG8_STAGE(PG8_SA(0, 0), a2, voffA);
;             PG8_BAR; PG8_WAIT_L(0); PG8_MMA(1, 0, At, B0); PG8_BAR; PG8_SCHED;
.LBB0_136:
	s_add_u32 s6, s4, 0xfff80080
	s_addc_u32 s7, s5, -1
	s_add_i32 s19, 0, 0x10000
	v_add_u32_e32 v0, s19, v145
	ds_read_b128 v[130:133], v0
	ds_read_b128 v[134:137], v0 offset:1024
	ds_read_b128 v[154:157], v0 offset:2048
	ds_read_b128 v[158:161], v0 offset:3072
	s_cmp_eq_u32 s17, 28
	s_cselect_b32 s9, s0, s7
	s_cselect_b32 s8, s1, s6
	s_cselect_b32 s7, s12, s15
	s_cselect_b32 s6, s13, s14
	v_lshl_add_u64 v[212:213], s[4:5], 0, v[150:151]
	s_add_i32 m0, s30, 0xc000
	ds_read_b128 v[184:187], v149
	ds_read_b128 v[188:191], v149 offset:1024
	ds_read_b128 v[192:195], v149 offset:2048
	ds_read_b128 v[196:199], v149 offset:3072
	ds_read_b128 v[200:203], v149 offset:4096
	ds_read_b128 v[204:207], v149 offset:5120
	ds_read_b128 v[208:211], v149 offset:6144
	ds_read_b128 v[224:227], v149 offset:7168
	global_load_lds_dwordx4 v[212:213], off
	v_lshl_add_u64 v[212:213], s[4:5], 0, v[152:153]
	s_add_i32 m0, s30, 0xe000
	s_nop 0
	global_load_lds_dwordx4 v[212:213], off
	s_waitcnt lgkmcnt(8)
	s_barrier
	s_waitcnt lgkmcnt(0)
	s_setprio 1
	s_waitcnt lgkmcnt(0)
	v_mfma_f32_16x16x32_bf16 v[122:125], v[130:133], v[184:187], v[122:125]
	v_mfma_f32_16x16x32_bf16 v[126:129], v[154:157], v[184:187], v[126:129]
	v_mfma_f32_16x16x32_bf16 v[110:113], v[130:133], v[192:195], v[110:113]
	v_mfma_f32_16x16x32_bf16 v[106:109], v[154:157], v[192:195], v[106:109]
	v_mfma_f32_16x16x32_bf16 v[94:97], v[130:133], v[200:203], v[94:97]
	v_mfma_f32_16x16x32_bf16 v[90:93], v[154:157], v[200:203], v[90:93]
	v_mfma_f32_16x16x32_bf16 v[78:81], v[130:133], v[208:211], v[78:81]
	v_mfma_f32_16x16x32_bf16 v[74:77], v[154:157], v[208:211], v[74:77]
	v_mfma_f32_16x16x32_bf16 v[122:125], v[134:137], v[188:191], v[122:125]
	v_mfma_f32_16x16x32_bf16 v[126:129], v[158:161], v[188:191], v[126:129]
	v_mfma_f32_16x16x32_bf16 v[110:113], v[134:137], v[196:199], v[110:113]
	v_mfma_f32_16x16x32_bf16 v[106:109], v[158:161], v[196:199], v[106:109]
	v_mfma_f32_16x16x32_bf16 v[94:97], v[134:137], v[204:207], v[94:97]
	v_mfma_f32_16x16x32_bf16 v[90:93], v[158:161], v[204:207], v[90:93]
	v_mfma_f32_16x16x32_bf16 v[78:81], v[134:137], v[224:227], v[78:81]
	v_mfma_f32_16x16x32_bf16 v[74:77], v[158:161], v[224:227], v[74:77]
	s_setprio 0
	s_barrier
	s_add_i32 s26, 0, 0x14000
	s_add_i32 s19, s19, s29
	v_add_u32_e32 v0, s26, v145
	v_lshl_add_u64 v[212:213], s[6:7], 0, v[140:141]
	s_mov_b32 m0, s19
	ds_read_b128 v[228:231], v0
	ds_read_b128 v[232:235], v0 offset:1024
	ds_read_b128 v[236:239], v0 offset:2048
	ds_read_b128 v[240:243], v0 offset:3072
	global_load_lds_dwordx4 v[212:213], off
	v_lshl_add_u64 v[214:215], s[6:7], 0, v[138:139]
	s_add_i32 m0, s19, 0x2000
	s_nop 0
	global_load_lds_dwordx4 v[214:215], off
	s_barrier
	s_waitcnt lgkmcnt(0)
	s_setprio 1
	s_waitcnt lgkmcnt(0)
	v_mfma_f32_16x16x32_bf16 v[118:121], v[228:231], v[184:187], v[118:121]
	v_mfma_f32_16x16x32_bf16 v[114:117], v[236:239], v[184:187], v[114:117]
	v_mfma_f32_16x16x32_bf16 v[102:105], v[228:231], v[192:195], v[102:105]
	v_mfma_f32_16x16x32_bf16 v[98:101], v[236:239], v[192:195], v[98:101]
	v_mfma_f32_16x16x32_bf16 v[86:89], v[228:231], v[200:203], v[86:89]
	v_mfma_f32_16x16x32_bf16 v[82:85], v[236:239], v[200:203], v[82:85]
	v_mfma_f32_16x16x32_bf16 v[70:73], v[228:231], v[208:211], v[70:73]
	v_mfma_f32_16x16x32_bf16 v[66:69], v[236:239], v[208:211], v[66:69]
	v_mfma_f32_16x16x32_bf16 v[118:121], v[232:235], v[188:191], v[118:121]
	v_mfma_f32_16x16x32_bf16 v[114:117], v[240:243], v[188:191], v[114:117]
	v_mfma_f32_16x16x32_bf16 v[102:105], v[232:235], v[196:199], v[102:105]
	v_mfma_f32_16x16x32_bf16 v[98:101], v[240:243], v[196:199], v[98:101]
	v_mfma_f32_16x16x32_bf16 v[86:89], v[232:235], v[204:207], v[86:89]
	v_mfma_f32_16x16x32_bf16 v[82:85], v[240:243], v[204:207], v[82:85]
	v_mfma_f32_16x16x32_bf16 v[70:73], v[232:235], v[224:227], v[70:73]
	v_mfma_f32_16x16x32_bf16 v[66:69], v[240:243], v[224:227], v[66:69]
	s_setprio 0
	s_mov_b32 m0, s30
	v_lshl_add_u64 v[218:219], s[8:9], 0, v[140:141]
	s_barrier
	ds_read_b128 v[184:187], v149 offset:16384
	ds_read_b128 v[188:191], v149 offset:17408
	ds_read_b128 v[192:195], v149 offset:18432
	ds_read_b128 v[196:199], v149 offset:19456
	ds_read_b128 v[200:203], v149 offset:20480
	ds_read_b128 v[204:207], v149 offset:21504
	ds_read_b128 v[208:211], v149 offset:22528
	ds_read_b128 v[224:227], v149 offset:23552
	global_load_lds_dwordx4 v[218:219], off
	v_lshl_add_u64 v[244:245], s[8:9], 0, v[138:139]
	s_mov_b32 m0, s31
	s_nop 0
	global_load_lds_dwordx4 v[244:245], off
	s_barrier
	s_waitcnt lgkmcnt(0)
	s_setprio 1
	s_waitcnt lgkmcnt(0)
	v_mfma_f32_16x16x32_bf16 v[62:65], v[130:133], v[184:187], v[62:65]
	v_mfma_f32_16x16x32_bf16 v[58:61], v[154:157], v[184:187], v[58:61]
	v_mfma_f32_16x16x32_bf16 v[46:49], v[130:133], v[192:195], v[46:49]
	v_mfma_f32_16x16x32_bf16 v[42:45], v[154:157], v[192:195], v[42:45]
	v_mfma_f32_16x16x32_bf16 v[30:33], v[130:133], v[200:203], v[30:33]
	v_mfma_f32_16x16x32_bf16 v[26:29], v[154:157], v[200:203], v[26:29]
	v_mfma_f32_16x16x32_bf16 v[14:17], v[130:133], v[208:211], v[14:17]
	v_mfma_f32_16x16x32_bf16 v[10:13], v[154:157], v[208:211], v[10:13]
	v_mfma_f32_16x16x32_bf16 v[62:65], v[134:137], v[188:191], v[62:65]
	v_mfma_f32_16x16x32_bf16 v[58:61], v[158:161], v[188:191], v[58:61]
	v_mfma_f32_16x16x32_bf16 v[46:49], v[134:137], v[196:199], v[46:49]
	v_mfma_f32_16x16x32_bf16 v[42:45], v[158:161], v[196:199], v[42:45]
	v_mfma_f32_16x16x32_bf16 v[30:33], v[134:137], v[204:207], v[30:33]
	v_mfma_f32_16x16x32_bf16 v[26:29], v[158:161], v[204:207], v[26:29]
	v_mfma_f32_16x16x32_bf16 v[14:17], v[134:137], v[224:227], v[14:17]
	v_mfma_f32_16x16x32_bf16 v[10:13], v[158:161], v[224:227], v[10:13]
	s_setprio 0
	s_barrier
; #define PG8_STAGE(bufoff, gbase, voff) do { _Pragma("unroll") for (int _i = 0; _i < 2; ++_i) \
;         __builtin_amdgcn_global_load_lds((const unsigned*)((const char*)(gbase) + (voff)[_i]), (LAS unsigned*)(lds + (bufoff) + ldsw + _i * 8192), 16, 0, 0); } while (0)
; #define PG8_LDA(dst, b, h) do { _Pragma("unroll") for (int m = 0; m < 4; ++m) _Pragma("unroll") for (int k = 0; k < 2; ++k) dst[m][k] = *(const LAS bf16x8*)(lds + PG8_SA(b, h) + aoff + m * 2048 + k * 1024); } while (0)
; #define PG8_LDB(dst, b, h) do { _Pragma("unroll") for (int n = 0; n < 2; ++n) _Pragma("unroll") for (int k = 0; k < 2; ++k) dst[n][k] = *(const LAS bf16x8*)(lds + PG8_SB(b, h) + boff + n * 2048 + k * 1024); } while (0)
; #define PG8_MMA(ai, bj, At, Bt) do { __builtin_amdgcn_s_setprio(1); _Pragma("unroll") for (int m = 0; m < 4; ++m) _Pragma("unroll") for (int n = 0; n < 2; ++n) _Pragma("unroll") for (int k = 0; k < 2; ++k) \
;         acc[ai][bj][m][n] = __builtin_amdgcn_mfma_f32_16x16x32_bf16(Bt[n][k], At[m][k], acc[ai][bj][m][n], 0, 0, 0); __builtin_amdgcn_s_setprio(0); } while (0)
; #define PG8_WAIT_V(n) asm volatile("s_waitcnt vmcnt(" #n ")" ::: "memory")
; #define PG8_WAIT_L(n) asm volatile("s_waitcnt lgkmcnt(" #n ")" ::: "memory")
; #define PG8_BAR __builtin_amdgcn_s_barrier()
; #define PG8_SCHED __builtin_amdgcn_sched_barrier(0)
; template <class Epi>
; __device__ __forceinline__ void gemm_phase(LAS unsigned char* lds, const Gemm g, const Order& S, KP kp, int code, int wv) {
;     ...
;             PG8_BAR; PG8_WAIT_L(0); PG8_MMA(1, 0, At, B0); PG8_BAR; PG8_SCHED;
;             PG8_STAGE(PG8_SB(0, 1), b2 + hstepB, voffB);
;             PG8_WAIT_V(6); PG8_BAR; PG8_MMA(1, 1, At, B1); PG8_BAR;
;             PG8_LDB(B0, 1, 0); PG8_SCHED; PG8_LDA(At, 1, 0); PG8_STAGE(PG8_SA(0, 1), a2 + hstepA, voffA);
;             PG8_WAIT_L(8); PG8_BAR; PG8_WAIT_L(0); PG8_MMA(0, 0, At, B0); PG8_BAR; PG8_SCHED;
;             PG8_LDB(B1, 1, 1); PG8_STAGE(PG8_SB(1, 0), b3, voffB);
;             PG8_BAR; PG8_WAIT_L(0); PG8_MMA(0, 1, At, B1); PG8_BAR;
;             PG8_LDA(At, 1, 1); PG8_STAGE(PG8_SA(1, 0), a3, voffA);
;             PG8_BAR; PG8_WAIT_L(0); PG8_MMA(1, 0, At, B0); PG8_BAR; PG8_SCHED;
	s_add_u32 s24, s6, 0x80000
	s_addc_u32 s25, s7, 0
	s_add_i32 s19, s26, s29
	v_lshl_add_u64 v[130:131], s[24:25], 0, v[140:141]
	s_mov_b32 m0, s19
	s_nop 0
	global_load_lds_dwordx4 v[130:131], off
	v_lshl_add_u64 v[130:131], s[24:25], 0, v[138:139]
	s_add_i32 m0, s19, 0x2000
	s_nop 0
	global_load_lds_dwordx4 v[130:131], off
	s_waitcnt vmcnt(6)
	s_barrier
	s_setprio 1
	v_mfma_f32_16x16x32_bf16 v[54:57], v[228:231], v[184:187], v[54:57]
	v_mfma_f32_16x16x32_bf16 v[50:53], v[236:239], v[184:187], v[50:53]
	v_mfma_f32_16x16x32_bf16 v[38:41], v[228:231], v[192:195], v[38:41]
	v_mfma_f32_16x16x32_bf16 v[34:37], v[236:239], v[192:195], v[34:37]
	v_mfma_f32_16x16x32_bf16 v[22:25], v[228:231], v[200:203], v[22:25]
	v_mfma_f32_16x16x32_bf16 v[18:21], v[236:239], v[200:203], v[18:21]
	v_mfma_f32_16x16x32_bf16 v[6:9], v[228:231], v[208:211], v[6:9]
	v_mfma_f32_16x16x32_bf16 v[2:5], v[236:239], v[208:211], v[2:5]
	v_mfma_f32_16x16x32_bf16 v[54:57], v[232:235], v[188:191], v[54:57]
	v_mfma_f32_16x16x32_bf16 v[50:53], v[240:243], v[188:191], v[50:53]
	v_mfma_f32_16x16x32_bf16 v[38:41], v[232:235], v[196:199], v[38:41]
	v_mfma_f32_16x16x32_bf16 v[34:37], v[240:243], v[196:199], v[34:37]
	v_mfma_f32_16x16x32_bf16 v[22:25], v[232:235], v[204:207], v[22:25]
	v_mfma_f32_16x16x32_bf16 v[18:21], v[240:243], v[204:207], v[18:21]
	v_mfma_f32_16x16x32_bf16 v[6:9], v[232:235], v[224:227], v[6:9]
	v_mfma_f32_16x16x32_bf16 v[2:5], v[240:243], v[224:227], v[2:5]
	s_setprio 0
	s_add_i32 s19, 0, 0x18000
	v_add_u32_e32 v0, s19, v145
	s_barrier
	ds_read_b128 v[130:133], v0
	ds_read_b128 v[134:137], v0 offset:1024
	ds_read_b128 v[154:157], v0 offset:2048
	ds_read_b128 v[158:161], v0 offset:3072
	s_add_u32 s8, s8, 0x80000
	s_addc_u32 s9, s9, 0
	s_mov_b32 m0, s34
	v_lshl_add_u64 v[228:229], s[8:9], 0, v[140:141]
	ds_read_b128 v[184:187], v149 offset:32768
	ds_read_b128 v[188:191], v149 offset:33792
	ds_read_b128 v[192:195], v149 offset:34816
	ds_read_b128 v[196:199], v149 offset:35840
	ds_read_b128 v[200:203], v149 offset:36864
	ds_read_b128 v[204:207], v149 offset:37888
	ds_read_b128 v[208:211], v149 offset:38912
	ds_read_b128 v[224:227], v149 offset:39936
	global_load_lds_dwordx4 v[228:229], off
	v_lshl_add_u64 v[228:229], s[8:9], 0, v[138:139]
	s_mov_b32 m0, s35
	s_nop 0
	global_load_lds_dwordx4 v[228:229], off
	s_waitcnt lgkmcnt(8)
	s_barrier
	s_waitcnt lgkmcnt(0)
	s_setprio 1
	s_waitcnt lgkmcnt(0)
	v_mfma_f32_16x16x32_bf16 v[122:125], v[130:133], v[184:187], v[122:125]
	v_mfma_f32_16x16x32_bf16 v[126:129], v[154:157], v[184:187], v[126:129]
	v_mfma_f32_16x16x32_bf16 v[110:113], v[130:133], v[192:195], v[110:113]
	v_mfma_f32_16x16x32_bf16 v[106:109], v[154:157], v[192:195], v[106:109]
	v_mfma_f32_16x16x32_bf16 v[94:97], v[130:133], v[200:203], v[94:97]
	v_mfma_f32_16x16x32_bf16 v[90:93], v[154:157], v[200:203], v[90:93]
	v_mfma_f32_16x16x32_bf16 v[78:81], v[130:133], v[208:211], v[78:81]
	v_mfma_f32_16x16x32_bf16 v[74:77], v[154:157], v[208:211], v[74:77]
	v_mfma_f32_16x16x32_bf16 v[122:125], v[134:137], v[188:191], v[122:125]
	v_mfma_f32_16x16x32_bf16 v[126:129], v[158:161], v[188:191], v[126:129]
	v_mfma_f32_16x16x32_bf16 v[110:113], v[134:137], v[196:199], v[110:113]
	v_mfma_f32_16x16x32_bf16 v[106:109], v[158:161], v[196:199], v[106:109]
	v_mfma_f32_16x16x32_bf16 v[94:97], v[134:137], v[204:207], v[94:97]
	v_mfma_f32_16x16x32_bf16 v[90:93], v[158:161], v[204:207], v[90:93]
	v_mfma_f32_16x16x32_bf16 v[78:81], v[134:137], v[224:227], v[78:81]
	v_mfma_f32_16x16x32_bf16 v[74:77], v[158:161], v[224:227], v[74:77]
	s_setprio 0
	s_barrier
	s_add_i32 s8, 0, 0x1c000
	s_add_i32 s9, s19, s29
	v_add_u32_e32 v0, s8, v145
	v_lshl_add_u64 v[212:213], v[212:213], 0, s[70:71]
	s_mov_b32 m0, s9
	ds_read_b128 v[228:231], v0
	ds_read_b128 v[232:235], v0 offset:1024
	ds_read_b128 v[236:239], v0 offset:2048
	ds_read_b128 v[240:243], v0 offset:3072
	global_load_lds_dwordx4 v[212:213], off
	v_lshl_add_u64 v[212:213], v[214:215], 0, s[70:71]
	s_add_i32 m0, s9, 0x2000
	s_nop 0
	global_load_lds_dwordx4 v[212:213], off
	s_barrier
	s_waitcnt lgkmcnt(0)
	s_setprio 1
	s_waitcnt lgkmcnt(0)
	v_mfma_f32_16x16x32_bf16 v[118:121], v[228:231], v[184:187], v[118:121]
	v_mfma_f32_16x16x32_bf16 v[114:117], v[236:239], v[184:187], v[114:117]
	v_mfma_f32_16x16x32_bf16 v[102:105], v[228:231], v[192:195], v[102:105]
	v_mfma_f32_16x16x32_bf16 v[98:101], v[236:239], v[192:195], v[98:101]
	v_mfma_f32_16x16x32_bf16 v[86:89], v[228:231], v[200:203], v[86:89]
	v_mfma_f32_16x16x32_bf16 v[82:85], v[236:239], v[200:203], v[82:85]
	v_mfma_f32_16x16x32_bf16 v[70:73], v[228:231], v[208:211], v[70:73]
	v_mfma_f32_16x16x32_bf16 v[66:69], v[236:239], v[208:211], v[66:69]
	v_mfma_f32_16x16x32_bf16 v[118:121], v[232:235], v[188:191], v[118:121]
	v_mfma_f32_16x16x32_bf16 v[114:117], v[240:243], v[188:191], v[114:117]
	v_mfma_f32_16x16x32_bf16 v[102:105], v[232:235], v[196:199], v[102:105]
	v_mfma_f32_16x16x32_bf16 v[98:101], v[240:243], v[196:199], v[98:101]
	v_mfma_f32_16x16x32_bf16 v[86:89], v[232:235], v[204:207], v[86:89]
	v_mfma_f32_16x16x32_bf16 v[82:85], v[240:243], v[204:207], v[82:85]
	v_mfma_f32_16x16x32_bf16 v[70:73], v[232:235], v[224:227], v[70:73]
	v_mfma_f32_16x16x32_bf16 v[66:69], v[240:243], v[224:227], v[66:69]
	s_setprio 0
	s_mov_b32 m0, s36
	v_lshl_add_u64 v[212:213], v[218:219], 0, s[70:71]
	s_barrier
	ds_read_b128 v[184:187], v149 offset:49152
	ds_read_b128 v[188:191], v149 offset:50176
	ds_read_b128 v[192:195], v149 offset:51200
	ds_read_b128 v[196:199], v149 offset:52224
	ds_read_b128 v[200:203], v149 offset:53248
	ds_read_b128 v[204:207], v149 offset:54272
	ds_read_b128 v[208:211], v149 offset:55296
	ds_read_b128 v[224:227], v149 offset:56320
	global_load_lds_dwordx4 v[212:213], off
	v_lshl_add_u64 v[212:213], v[244:245], 0, s[70:71]
	s_mov_b32 m0, s37
	s_nop 0
	global_load_lds_dwordx4 v[212:213], off
	s_barrier
; __device__ __forceinline__ unsigned cvt_pk_bf16(float lo, float hi) { unsigned r; asm("v_cvt_pk_bf16_f32 %0, %1, %2" : "=v"(r) : "v"(lo), "v"(hi)); return r; }
; #define PG8_STAGE(bufoff, gbase, voff) do { _Pragma("unroll") for (int _i = 0; _i < 2; ++_i) \
;         __builtin_amdgcn_global_load_lds((const unsigned*)((const char*)(gbase) + (voff)[_i]), (LAS unsigned*)(lds + (bufoff) + ldsw + _i * 8192), 16, 0, 0); } while (0)
; #define PG8_LDA(dst, b, h) do { _Pragma("unroll") for (int m = 0; m < 4; ++m) _Pragma("unroll") for (int k = 0; k < 2; ++k) dst[m][k] = *(const LAS bf16x8*)(lds + PG8_SA(b, h) + aoff + m * 2048 + k * 1024); } while (0)
; #define PG8_BAR __builtin_amdgcn_s_barrier()
;     __device__ __forceinline__ void operator()(const f32x4 (&acc)[2][2][4][2], const Unit& u, int wr, int wc, int fr, int fq) const {
;     ...
;             const int col0 = (pn - 12) * BM + wc * 32 + 4 * fq;
; #pragma unroll
;             for (int ai = 0; ai < 2; ++ai)
; #pragma unroll
;                 for (int m = 0; m < 4; ++m) {
;                     bf16_t* rowp = pr + (size_t)(rbase + ai * HALF + m * 16) * 4096 + col0;
; #pragma unroll
;                     for (int bj = 0; bj < 2; ++bj)
; #pragma unroll
;                         for (int n = 0; n < 2; ++n) {
;                             const f32x4 x = acc[ai][bj][m][n];
;                             u32x2 w; w.x = cvt_pk_bf16(x[0], x[1]); w.y = cvt_pk_bf16(x[2], x[3]);
;                             *(u32x2*)(rowp + bj * HALF + n * 16) = w;
;                         }
; template <class Epi>
; __device__ __forceinline__ void gemm_phase(LAS unsigned char* lds, const Gemm g, const Order& S, KP kp, int code, int wv) {
;     ...
;             PG8_WAIT_V(6); PG8_BAR; PG8_MMA(1, 1, At, B1); PG8_BAR;
;             PG8_LDB(B0, 1, 0); PG8_SCHED; PG8_LDA(At, 1, 0); PG8_STAGE(PG8_SA(0, 1), a2 + hstepA, voffA);
;             PG8_WAIT_L(8); PG8_BAR; PG8_WAIT_L(0); PG8_MMA(0, 0, At, B0); PG8_BAR; PG8_SCHED;
;             PG8_LDB(B1, 1, 1); PG8_STAGE(PG8_SB(1, 0), b3, voffB);
;             PG8_BAR; PG8_WAIT_L(0); PG8_MMA(0, 1, At, B1); PG8_BAR;
;             PG8_LDA(At, 1, 1); PG8_STAGE(PG8_SA(1, 0), a3, voffA);
;             PG8_BAR; PG8_WAIT_L(0); PG8_MMA(1, 0, At, B0); PG8_BAR; PG8_SCHED;
;             PG8_STAGE(PG8_SB(1, 1), b3 + hstepB, voffB);
;             PG8_WAIT_V(6); PG8_BAR; PG8_MMA(1, 1, At, B1); PG8_BAR;
	s_waitcnt lgkmcnt(0)
	s_setprio 1
	s_waitcnt lgkmcnt(0)
	v_mfma_f32_16x16x32_bf16 v[62:65], v[130:133], v[184:187], v[62:65]
	v_mfma_f32_16x16x32_bf16 v[58:61], v[154:157], v[184:187], v[58:61]
	v_mfma_f32_16x16x32_bf16 v[46:49], v[130:133], v[192:195], v[46:49]
	v_mfma_f32_16x16x32_bf16 v[42:45], v[154:157], v[192:195], v[42:45]
	v_mfma_f32_16x16x32_bf16 v[30:33], v[130:133], v[200:203], v[30:33]
	v_mfma_f32_16x16x32_bf16 v[26:29], v[154:157], v[200:203], v[26:29]
	v_mfma_f32_16x16x32_bf16 v[14:17], v[130:133], v[208:211], v[14:17]
	v_mfma_f32_16x16x32_bf16 v[10:13], v[154:157], v[208:211], v[10:13]
	v_mfma_f32_16x16x32_bf16 v[62:65], v[134:137], v[188:191], v[62:65]
	v_mfma_f32_16x16x32_bf16 v[58:61], v[158:161], v[188:191], v[58:61]
	v_mfma_f32_16x16x32_bf16 v[46:49], v[134:137], v[196:199], v[46:49]
	v_mfma_f32_16x16x32_bf16 v[42:45], v[158:161], v[196:199], v[42:45]
	v_mfma_f32_16x16x32_bf16 v[30:33], v[134:137], v[204:207], v[30:33]
	v_mfma_f32_16x16x32_bf16 v[26:29], v[158:161], v[204:207], v[26:29]
	v_mfma_f32_16x16x32_bf16 v[14:17], v[134:137], v[224:227], v[14:17]
	v_mfma_f32_16x16x32_bf16 v[10:13], v[158:161], v[224:227], v[10:13]
	s_setprio 0
	s_barrier
	s_add_u32 s6, s6, 0x80080
	s_addc_u32 s7, s7, 0
	s_add_i32 s8, s8, s29
	v_lshl_add_u64 v[130:131], s[6:7], 0, v[140:141]
	s_mov_b32 m0, s8
	s_nop 0
	global_load_lds_dwordx4 v[130:131], off
	v_lshl_add_u64 v[130:131], s[6:7], 0, v[138:139]
	s_add_i32 m0, s8, 0x2000
	s_nop 0
	global_load_lds_dwordx4 v[130:131], off
	s_waitcnt vmcnt(6)
	s_barrier
	s_setprio 1
	v_mfma_f32_16x16x32_bf16 v[54:57], v[228:231], v[184:187], v[54:57]
	v_mfma_f32_16x16x32_bf16 v[50:53], v[236:239], v[184:187], v[50:53]
	v_mfma_f32_16x16x32_bf16 v[38:41], v[228:231], v[192:195], v[38:41]
	v_mfma_f32_16x16x32_bf16 v[34:37], v[236:239], v[192:195], v[34:37]
	v_mfma_f32_16x16x32_bf16 v[22:25], v[228:231], v[200:203], v[22:25]
	v_mfma_f32_16x16x32_bf16 v[18:21], v[236:239], v[200:203], v[18:21]
	v_mfma_f32_16x16x32_bf16 v[6:9], v[228:231], v[208:211], v[6:9]
	v_mfma_f32_16x16x32_bf16 v[2:5], v[236:239], v[208:211], v[2:5]
	v_mfma_f32_16x16x32_bf16 v[54:57], v[232:235], v[188:191], v[54:57]
	v_mfma_f32_16x16x32_bf16 v[50:53], v[240:243], v[188:191], v[50:53]
	v_mfma_f32_16x16x32_bf16 v[38:41], v[232:235], v[196:199], v[38:41]
	v_mfma_f32_16x16x32_bf16 v[34:37], v[240:243], v[196:199], v[34:37]
	v_mfma_f32_16x16x32_bf16 v[22:25], v[232:235], v[204:207], v[22:25]
	v_mfma_f32_16x16x32_bf16 v[18:21], v[240:243], v[204:207], v[18:21]
	v_mfma_f32_16x16x32_bf16 v[6:9], v[232:235], v[224:227], v[6:9]
	v_mfma_f32_16x16x32_bf16 v[2:5], v[240:243], v[224:227], v[2:5]
	s_setprio 0
	s_add_i32 s17, s17, 2
	s_add_u32 s4, s4, 0x100
	s_addc_u32 s5, s5, 0
	s_add_u32 s14, s14, 0x100
	s_addc_u32 s15, s15, 0
	s_cmp_gt_u32 s17, 29
	s_barrier
	s_cbranch_scc0 .LBB0_136
	v_mbcnt_lo_u32_b32 v164, -1, 0
	v_mbcnt_hi_u32_b32 v164, -1, v164
	v_and_b32_e32 v166, 3, v164
	v_mul_u32_u24_e32 v166, 0xfe, v166
	v_mov_b32_e32 v167, 0
	v_and_b32_e32 v164, 1, v164
	v_cmp_eq_u32_e64 s[98:99], 0, v164
	v_mov_b32_e32 v165, 0x3020706
	v_mov_b32_e32 v170, 0x5040100
	s_nop 1
	v_cndmask_b32_e64 v165, v165, v170, s[98:99]
	s_mov_b32 s98, 0xcccccccc
	s_mov_b32 s99, 0xcccccccc
	s_mov_b64 s[0:1], s[78:79]
	s_cmp_lt_i32 s10, 32
	s_load_dwordx2 s[24:25], s[0:1], 0xc0
	s_cselect_b64 s[6:7], -1, 0
	s_lshl_b32 s4, s10, 1
	s_and_b32 s4, s4, 14
	s_sub_i32 s0, s10, 32
	s_ashr_i32 s1, s10, 3
	s_add_i32 s4, s4, 2
	s_cmp_gt_i32 s10, 31
	v_lshl_add_u32 v154, s10, 8, v142
	s_cselect_b32 s8, s0, s1
	s_cselect_b32 s10, 0, s4
	s_cmp_gt_i32 s11, 7
	s_mov_b64 s[0:1], -1
	s_cbranch_scc0 .LBB0_143
	s_cmp_gt_u32 s11, 11
	s_cbranch_scc0 .LBB0_140
	s_waitcnt lgkmcnt(0)
	s_add_u32 s4, s24, 0x242b4000
	v_ashrrev_i32_e32 v155, 31, v154
	s_addc_u32 s5, s25, 0
	v_lshl_add_u32 v0, s11, 8, v147
	v_lshlrev_b64 v[130:131], 13, v[154:155]
	v_lshl_add_u64 v[130:131], s[4:5], 0, v[130:131]
	v_lshlrev_b64 v[132:133], 1, v[0:1]
	v_lshl_add_u64 v[130:131], v[130:131], 0, v[132:133]
	v_cvt_pk_bf16_f32 v134, v122, v123
	v_cvt_pk_bf16_f32 v135, v124, v125
	global_store_dwordx2 v[130:131], v[134:135], off
	v_cvt_pk_bf16_f32 v134, v126, v127
	v_cvt_pk_bf16_f32 v135, v128, v129
	global_store_dwordx2 v[130:131], v[134:135], off offset:32
	v_cvt_pk_bf16_f32 v134, v118, v119
	v_cvt_pk_bf16_f32 v135, v120, v121
	global_store_dwordx2 v[130:131], v[134:135], off offset:256
	v_cvt_pk_bf16_f32 v134, v114, v115
	v_cvt_pk_bf16_f32 v135, v116, v117
	global_store_dwordx2 v[130:131], v[134:135], off offset:288
	v_or_b32_e32 v134, 16, v154
	v_ashrrev_i32_e32 v135, 31, v134
	v_lshlrev_b64 v[134:135], 13, v[134:135]
	v_lshl_add_u64 v[134:135], s[4:5], 0, v[134:135]
	v_lshl_add_u64 v[134:135], v[134:135], 0, v[132:133]
	v_cvt_pk_bf16_f32 v136, v110, v111
	v_cvt_pk_bf16_f32 v137, v112, v113
	global_store_dwordx2 v[134:135], v[136:137], off
	v_cvt_pk_bf16_f32 v136, v106, v107
	v_cvt_pk_bf16_f32 v137, v108, v109
	global_store_dwordx2 v[134:135], v[136:137], off offset:32
	v_cvt_pk_bf16_f32 v136, v102, v103
	v_cvt_pk_bf16_f32 v137, v104, v105
	global_store_dwordx2 v[134:135], v[136:137], off offset:256
	v_cvt_pk_bf16_f32 v136, v98, v99
	v_cvt_pk_bf16_f32 v137, v100, v101
	global_store_dwordx2 v[134:135], v[136:137], off offset:288
	v_or_b32_e32 v134, 32, v154
	v_ashrrev_i32_e32 v135, 31, v134
	v_lshlrev_b64 v[134:135], 13, v[134:135]
	v_lshl_add_u64 v[134:135], s[4:5], 0, v[134:135]
	v_lshl_add_u64 v[134:135], v[134:135], 0, v[132:133]
	v_cvt_pk_bf16_f32 v136, v94, v95
	v_cvt_pk_bf16_f32 v137, v96, v97
	global_store_dwordx2 v[134:135], v[136:137], off
	v_cvt_pk_bf16_f32 v136, v90, v91
	v_cvt_pk_bf16_f32 v137, v92, v93
; __device__ __forceinline__ unsigned cvt_pk_bf16(float lo, float hi) { unsigned r; asm("v_cvt_pk_bf16_f32 %0, %1, %2" : "=v"(r) : "v"(lo), "v"(hi)); return r; }
;     __device__ __forceinline__ void operator()(const f32x4 (&acc)[2][2][4][2], const Unit& u, int wr, int wc, int fr, int fq) const {
;     ...
;         } else if (pn < 12) {
; #pragma unroll
;             for (int ai = 0; ai < 2; ++ai)
; #pragma unroll
;                 for (int m = 0; m < 4; ++m) {
;                     const int tt = wr * 64 + m * 16 + fr, cc = ccb + ai;
; #pragma unroll
;                     for (int bj = 0; bj < 2; ++bj) {
;                         const int head = 2 * (pn - 8) + bj;
; #pragma unroll
;                         for (int n = 0; n < 2; ++n) {
;                             const f32x4 x = acc[ai][bj][m][n];
;                             const unsigned a = cvt_pk_bf16(x[0], x[1]), c2 = cvt_pk_bf16(x[2], x[3]);
;                             bf16_t* tp = vT + ((size_t)((b * 8 + head) * 18 + cc) * 128 + 32 * wc + 16 * n + 4 * fq) * 128 + tt;
;                             tp[0] = (bf16_t)(a & 0xffffu); tp[128] = (bf16_t)(a >> 16); tp[256] = (bf16_t)(c2 & 0xffffu); tp[384] = (bf16_t)(c2 >> 16);
;                         }
;     ...
;             const int col0 = (pn - 12) * BM + wc * 32 + 4 * fq;
; #pragma unroll
;             for (int ai = 0; ai < 2; ++ai)
; #pragma unroll
;                 for (int m = 0; m < 4; ++m) {
;                     bf16_t* rowp = pr + (size_t)(rbase + ai * HALF + m * 16) * 4096 + col0;
; #pragma unroll
;                     for (int bj = 0; bj < 2; ++bj)
; #pragma unroll
;                         for (int n = 0; n < 2; ++n) {
;                             const f32x4 x = acc[ai][bj][m][n];
;                             u32x2 w; w.x = cvt_pk_bf16(x[0], x[1]); w.y = cvt_pk_bf16(x[2], x[3]);
;                             *(u32x2*)(rowp + bj * HALF + n * 16) = w;
;                         }
	global_store_dwordx2 v[134:135], v[136:137], off offset:32
	v_cvt_pk_bf16_f32 v136, v86, v87
	v_cvt_pk_bf16_f32 v137, v88, v89
	global_store_dwordx2 v[134:135], v[136:137], off offset:256
	v_cvt_pk_bf16_f32 v136, v82, v83
	v_cvt_pk_bf16_f32 v137, v84, v85
	global_store_dwordx2 v[134:135], v[136:137], off offset:288
	v_or_b32_e32 v134, 48, v154
	v_ashrrev_i32_e32 v135, 31, v134
	v_lshlrev_b64 v[134:135], 13, v[134:135]
	v_lshl_add_u64 v[134:135], s[4:5], 0, v[134:135]
	v_lshl_add_u64 v[132:133], v[134:135], 0, v[132:133]
	v_cvt_pk_bf16_f32 v134, v78, v79
	v_cvt_pk_bf16_f32 v135, v80, v81
	global_store_dwordx2 v[132:133], v[134:135], off
	v_cvt_pk_bf16_f32 v134, v74, v75
	v_cvt_pk_bf16_f32 v135, v76, v77
	global_store_dwordx2 v[132:133], v[134:135], off offset:32
	v_cvt_pk_bf16_f32 v134, v70, v71
	v_cvt_pk_bf16_f32 v135, v72, v73
	s_mov_b64 s[0:1], 0x100000
	global_store_dwordx2 v[132:133], v[134:135], off offset:256
	v_cvt_pk_bf16_f32 v134, v66, v67
	v_cvt_pk_bf16_f32 v135, v68, v69
	global_store_dwordx2 v[132:133], v[134:135], off offset:288
	v_lshl_add_u64 v[132:133], v[130:131], 0, s[0:1]
	s_mov_b32 s0, 0x100000
	v_add_co_u32_e32 v136, vcc, s0, v130
	v_cvt_pk_bf16_f32 v134, v62, v63
	v_cvt_pk_bf16_f32 v135, v64, v65
	s_mov_b32 s0, 0x120000
	s_nop 0
	v_addc_co_u32_e32 v137, vcc, 0, v131, vcc
	global_store_dwordx2 v[136:137], v[134:135], off
	v_cvt_pk_bf16_f32 v134, v58, v59
	v_cvt_pk_bf16_f32 v135, v60, v61
	global_store_dwordx2 v[132:133], v[134:135], off offset:32
	v_cvt_pk_bf16_f32 v134, v54, v55
	v_cvt_pk_bf16_f32 v135, v56, v57
	global_store_dwordx2 v[132:133], v[134:135], off offset:256
	v_cvt_pk_bf16_f32 v134, v50, v51
	v_cvt_pk_bf16_f32 v135, v52, v53
	v_add_co_u32_e32 v136, vcc, s0, v130
	global_store_dwordx2 v[132:133], v[134:135], off offset:288
	v_cvt_pk_bf16_f32 v134, v46, v47
	v_cvt_pk_bf16_f32 v135, v48, v49
	s_nop 0
	v_addc_co_u32_e32 v137, vcc, 0, v131, vcc
	v_lshl_add_u64 v[132:133], v[130:131], 0, s[74:75]
	global_store_dwordx2 v[136:137], v[134:135], off
	v_cvt_pk_bf16_f32 v134, v42, v43
	v_cvt_pk_bf16_f32 v135, v44, v45
	global_store_dwordx2 v[132:133], v[134:135], off offset:32
	v_cvt_pk_bf16_f32 v134, v38, v39
	v_cvt_pk_bf16_f32 v135, v40, v41
	s_mov_b64 s[0:1], 0x140000
	global_store_dwordx2 v[132:133], v[134:135], off offset:256
	v_cvt_pk_bf16_f32 v134, v34, v35
	v_cvt_pk_bf16_f32 v135, v36, v37
	global_store_dwordx2 v[132:133], v[134:135], off offset:288
	v_lshl_add_u64 v[132:133], v[130:131], 0, s[0:1]
	s_mov_b32 s0, 0x140000
	v_add_co_u32_e32 v136, vcc, s0, v130
	v_cvt_pk_bf16_f32 v134, v30, v31
	v_cvt_pk_bf16_f32 v135, v32, v33
	s_mov_b64 s[0:1], 0x160000
	s_nop 0
	v_addc_co_u32_e32 v137, vcc, 0, v131, vcc
	global_store_dwordx2 v[136:137], v[134:135], off
	v_cvt_pk_bf16_f32 v134, v26, v27
	v_cvt_pk_bf16_f32 v135, v28, v29
	global_store_dwordx2 v[132:133], v[134:135], off offset:32
	v_cvt_pk_bf16_f32 v134, v22, v23
	v_cvt_pk_bf16_f32 v135, v24, v25
	global_store_dwordx2 v[132:133], v[134:135], off offset:256
	v_cvt_pk_bf16_f32 v134, v18, v19
	v_cvt_pk_bf16_f32 v135, v20, v21
	global_store_dwordx2 v[132:133], v[134:135], off offset:288
	v_lshl_add_u64 v[132:133], v[130:131], 0, s[0:1]
	s_mov_b32 s0, 0x160000
	v_add_co_u32_e32 v130, vcc, s0, v130
	v_cvt_pk_bf16_f32 v134, v14, v15
	v_cvt_pk_bf16_f32 v135, v16, v17
	s_mov_b64 s[0:1], 0
	s_nop 0
	v_addc_co_u32_e32 v131, vcc, 0, v131, vcc
	global_store_dwordx2 v[130:131], v[134:135], off
	v_cvt_pk_bf16_f32 v130, v10, v11
	v_cvt_pk_bf16_f32 v131, v12, v13
	global_store_dwordx2 v[132:133], v[130:131], off offset:32
	v_cvt_pk_bf16_f32 v130, v6, v7
	v_cvt_pk_bf16_f32 v131, v8, v9
	global_store_dwordx2 v[132:133], v[130:131], off offset:256
	v_cvt_pk_bf16_f32 v130, v2, v3
	v_cvt_pk_bf16_f32 v131, v4, v5
	global_store_dwordx2 v[132:133], v[130:131], off offset:288
.LBB0_140:
	s_andn2_b64 vcc, exec, s[0:1]
	s_cbranch_vccnz .LBB0_142
	s_lshl_b32 s0, s11, 1
	s_lshl_b32 s1, s8, 3
	s_add_i32 s0, s0, s1
	s_mul_i32 s1, s0, 18
	s_add_i32 s0, s1, 0xfffffee0
	s_add_i32 s4, s0, s10
	s_ashr_i32 s5, s4, 31
	s_waitcnt lgkmcnt(0)
	v_lshl_add_u64 v[132:133], v[142:143], 1, s[24:25]
	s_mov_b64 s[12:13], 0x230b4000
	s_lshl_b64 s[4:5], s[4:5], 15
	s_addk_i32 s1, 0xfef2
	v_lshl_add_u64 v[130:131], v[132:133], 0, s[12:13]
	v_mov_b32_e32 v135, s5
	v_or_b32_e32 v134, s4, v144
	s_add_i32 s4, s1, s10
	v_cvt_pk_bf16_f32 v0, v122, v123
	v_lshl_add_u64 v[136:137], v[130:131], 0, v[134:135]
	v_or_b32_e32 v134, 0x1000, v134
	s_ashr_i32 s5, s4, 31
	v_cvt_pk_bf16_f32 v155, v124, v125
	s_nop 1
	v_mov_b32_dpp v168, v0 quad_perm:[1,0,3,2] row_mask:0xf bank_mask:0xf
	v_mov_b32_dpp v169, v155 quad_perm:[1,0,3,2] row_mask:0xf bank_mask:0xf
	v_lshl_add_u64 v[172:173], v[136:137], 0, v[166:167]
	v_perm_b32 v168, v168, v0, v165
	v_perm_b32 v169, v169, v155, v165
	s_nop 1
	v_mov_b32_dpp v170, v168 quad_perm:[2,3,0,1] row_mask:0xf bank_mask:0xf
	v_mov_b32_dpp v171, v169 quad_perm:[2,3,0,1] row_mask:0xf bank_mask:0xf
	s_nop 1
	v_cndmask_b32_e64 v168, v168, v171, s[98:99]
	v_cndmask_b32_e64 v169, v170, v169, s[98:99]
	global_store_dwordx2 v[172:173], v[168:169], off
	v_cvt_pk_bf16_f32 v0, v126, v127
	v_lshl_add_u64 v[156:157], v[130:131], 0, v[134:135]
	s_lshl_b64 s[4:5], s[4:5], 15
	v_cvt_pk_bf16_f32 v155, v128, v129
	s_nop 1
	v_mov_b32_dpp v168, v0 quad_perm:[1,0,3,2] row_mask:0xf bank_mask:0xf
	v_mov_b32_dpp v169, v155 quad_perm:[1,0,3,2] row_mask:0xf bank_mask:0xf
	v_lshl_add_u64 v[172:173], v[156:157], 0, v[166:167]
	v_perm_b32 v168, v168, v0, v165
	v_perm_b32 v169, v169, v155, v165
	s_nop 1
	v_mov_b32_dpp v170, v168 quad_perm:[2,3,0,1] row_mask:0xf bank_mask:0xf
	v_mov_b32_dpp v171, v169 quad_perm:[2,3,0,1] row_mask:0xf bank_mask:0xf
; __device__ __forceinline__ unsigned cvt_pk_bf16(float lo, float hi) { unsigned r; asm("v_cvt_pk_bf16_f32 %0, %1, %2" : "=v"(r) : "v"(lo), "v"(hi)); return r; }
;     __device__ __forceinline__ void operator()(const f32x4 (&acc)[2][2][4][2], const Unit& u, int wr, int wc, int fr, int fq) const {
;     ...
;         } else if (pn < 12) {
; #pragma unroll
;             for (int ai = 0; ai < 2; ++ai)
; #pragma unroll
;                 for (int m = 0; m < 4; ++m) {
;                     const int tt = wr * 64 + m * 16 + fr, cc = ccb + ai;
; #pragma unroll
;                     for (int bj = 0; bj < 2; ++bj) {
;                         const int head = 2 * (pn - 8) + bj;
; #pragma unroll
;                         for (int n = 0; n < 2; ++n) {
;                             const f32x4 x = acc[ai][bj][m][n];
;                             const unsigned a = cvt_pk_bf16(x[0], x[1]), c2 = cvt_pk_bf16(x[2], x[3]);
;                             bf16_t* tp = vT + ((size_t)((b * 8 + head) * 18 + cc) * 128 + 32 * wc + 16 * n + 4 * fq) * 128 + tt;
;                             tp[0] = (bf16_t)(a & 0xffffu); tp[128] = (bf16_t)(a >> 16); tp[256] = (bf16_t)(c2 & 0xffffu); tp[384] = (bf16_t)(c2 >> 16);
;                         }
	s_nop 1
	v_cndmask_b32_e64 v168, v168, v171, s[98:99]
	v_cndmask_b32_e64 v169, v170, v169, s[98:99]
	global_store_dwordx2 v[172:173], v[168:169], off
	v_mov_b32_e32 v157, s5
	v_or_b32_e32 v156, s4, v144
	v_cvt_pk_bf16_f32 v0, v118, v119
	v_lshl_add_u64 v[158:159], v[130:131], 0, v[156:157]
	v_or_b32_e32 v156, 0x1000, v156
	v_cvt_pk_bf16_f32 v155, v120, v121
	s_nop 1
	v_mov_b32_dpp v168, v0 quad_perm:[1,0,3,2] row_mask:0xf bank_mask:0xf
	v_mov_b32_dpp v169, v155 quad_perm:[1,0,3,2] row_mask:0xf bank_mask:0xf
	v_lshl_add_u64 v[172:173], v[158:159], 0, v[166:167]
	v_perm_b32 v168, v168, v0, v165
	v_perm_b32 v169, v169, v155, v165
	s_nop 1
	v_mov_b32_dpp v170, v168 quad_perm:[2,3,0,1] row_mask:0xf bank_mask:0xf
	v_mov_b32_dpp v171, v169 quad_perm:[2,3,0,1] row_mask:0xf bank_mask:0xf
	s_nop 1
	v_cndmask_b32_e64 v168, v168, v171, s[98:99]
	v_cndmask_b32_e64 v169, v170, v169, s[98:99]
	global_store_dwordx2 v[172:173], v[168:169], off
	v_cvt_pk_bf16_f32 v0, v114, v115
	v_lshl_add_u64 v[160:161], v[130:131], 0, v[156:157]
	s_mov_b64 s[4:5], 0x230b4020
	v_cvt_pk_bf16_f32 v155, v116, v117
	s_nop 1
	v_mov_b32_dpp v168, v0 quad_perm:[1,0,3,2] row_mask:0xf bank_mask:0xf
	v_mov_b32_dpp v169, v155 quad_perm:[1,0,3,2] row_mask:0xf bank_mask:0xf
	v_lshl_add_u64 v[172:173], v[160:161], 0, v[166:167]
	v_perm_b32 v168, v168, v0, v165
	v_perm_b32 v169, v169, v155, v165
	s_nop 1
	v_mov_b32_dpp v170, v168 quad_perm:[2,3,0,1] row_mask:0xf bank_mask:0xf
	v_mov_b32_dpp v171, v169 quad_perm:[2,3,0,1] row_mask:0xf bank_mask:0xf
	s_nop 1
	v_cndmask_b32_e64 v168, v168, v171, s[98:99]
	v_cndmask_b32_e64 v169, v170, v169, s[98:99]
	global_store_dwordx2 v[172:173], v[168:169], off
	v_lshl_add_u64 v[160:161], v[132:133], 0, s[4:5]
	v_cvt_pk_bf16_f32 v0, v110, v111
	v_cvt_pk_bf16_f32 v155, v112, v113
	s_nop 1
	v_mov_b32_dpp v168, v0 quad_perm:[1,0,3,2] row_mask:0xf bank_mask:0xf
	v_mov_b32_dpp v169, v155 quad_perm:[1,0,3,2] row_mask:0xf bank_mask:0xf
	v_lshl_add_u64 v[172:173], v[136:137], 0, v[166:167]
	v_perm_b32 v168, v168, v0, v165
	v_perm_b32 v169, v169, v155, v165
	s_nop 1
	v_mov_b32_dpp v170, v168 quad_perm:[2,3,0,1] row_mask:0xf bank_mask:0xf
	v_mov_b32_dpp v171, v169 quad_perm:[2,3,0,1] row_mask:0xf bank_mask:0xf
	s_nop 1
	v_cndmask_b32_e64 v168, v168, v171, s[98:99]
	v_cndmask_b32_e64 v169, v170, v169, s[98:99]
	global_store_dwordx2 v[172:173], v[168:169], off offset:32
	v_cvt_pk_bf16_f32 v0, v106, v107
	v_lshl_add_u64 v[184:185], v[160:161], 0, v[134:135]
	v_cvt_pk_bf16_f32 v155, v108, v109
	s_nop 1
	v_mov_b32_dpp v168, v0 quad_perm:[1,0,3,2] row_mask:0xf bank_mask:0xf
	v_mov_b32_dpp v169, v155 quad_perm:[1,0,3,2] row_mask:0xf bank_mask:0xf
	v_lshl_add_u64 v[172:173], v[184:185], 0, v[166:167]
	v_perm_b32 v168, v168, v0, v165
	v_perm_b32 v169, v169, v155, v165
	s_nop 1
	v_mov_b32_dpp v170, v168 quad_perm:[2,3,0,1] row_mask:0xf bank_mask:0xf
	v_mov_b32_dpp v171, v169 quad_perm:[2,3,0,1] row_mask:0xf bank_mask:0xf
	s_nop 1
	v_cndmask_b32_e64 v168, v168, v171, s[98:99]
	v_cndmask_b32_e64 v169, v170, v169, s[98:99]
	global_store_dwordx2 v[172:173], v[168:169], off
	v_cvt_pk_bf16_f32 v0, v102, v103
	v_cvt_pk_bf16_f32 v155, v104, v105
	s_nop 1
	v_mov_b32_dpp v168, v0 quad_perm:[1,0,3,2] row_mask:0xf bank_mask:0xf
	v_mov_b32_dpp v169, v155 quad_perm:[1,0,3,2] row_mask:0xf bank_mask:0xf
	v_lshl_add_u64 v[172:173], v[158:159], 0, v[166:167]
	v_perm_b32 v168, v168, v0, v165
	v_perm_b32 v169, v169, v155, v165
	s_nop 1
	v_mov_b32_dpp v170, v168 quad_perm:[2,3,0,1] row_mask:0xf bank_mask:0xf
	v_mov_b32_dpp v171, v169 quad_perm:[2,3,0,1] row_mask:0xf bank_mask:0xf
	s_nop 1
	v_cndmask_b32_e64 v168, v168, v171, s[98:99]
	v_cndmask_b32_e64 v169, v170, v169, s[98:99]
	global_store_dwordx2 v[172:173], v[168:169], off offset:32
	v_cvt_pk_bf16_f32 v0, v98, v99
	v_lshl_add_u64 v[184:185], v[160:161], 0, v[156:157]
	s_mov_b64 s[4:5], 0x230b4040
	v_cvt_pk_bf16_f32 v155, v100, v101
	s_nop 1
	v_mov_b32_dpp v168, v0 quad_perm:[1,0,3,2] row_mask:0xf bank_mask:0xf
	v_mov_b32_dpp v169, v155 quad_perm:[1,0,3,2] row_mask:0xf bank_mask:0xf
	v_lshl_add_u64 v[172:173], v[184:185], 0, v[166:167]
	v_perm_b32 v168, v168, v0, v165
	v_perm_b32 v169, v169, v155, v165
	s_nop 1
	v_mov_b32_dpp v170, v168 quad_perm:[2,3,0,1] row_mask:0xf bank_mask:0xf
	v_mov_b32_dpp v171, v169 quad_perm:[2,3,0,1] row_mask:0xf bank_mask:0xf
	s_nop 1
	v_cndmask_b32_e64 v168, v168, v171, s[98:99]
	v_cndmask_b32_e64 v169, v170, v169, s[98:99]
	global_store_dwordx2 v[172:173], v[168:169], off
	v_lshl_add_u64 v[184:185], v[132:133], 0, s[4:5]
	v_cvt_pk_bf16_f32 v0, v94, v95
	v_cvt_pk_bf16_f32 v155, v96, v97
	s_nop 1
	v_mov_b32_dpp v168, v0 quad_perm:[1,0,3,2] row_mask:0xf bank_mask:0xf
	v_mov_b32_dpp v169, v155 quad_perm:[1,0,3,2] row_mask:0xf bank_mask:0xf
	v_lshl_add_u64 v[172:173], v[136:137], 0, v[166:167]
	v_perm_b32 v168, v168, v0, v165
	v_perm_b32 v169, v169, v155, v165
	s_nop 1
	v_mov_b32_dpp v170, v168 quad_perm:[2,3,0,1] row_mask:0xf bank_mask:0xf
	v_mov_b32_dpp v171, v169 quad_perm:[2,3,0,1] row_mask:0xf bank_mask:0xf
	s_nop 1
	v_cndmask_b32_e64 v168, v168, v171, s[98:99]
	v_cndmask_b32_e64 v169, v170, v169, s[98:99]
	global_store_dwordx2 v[172:173], v[168:169], off offset:64
	v_cvt_pk_bf16_f32 v0, v90, v91
	v_lshl_add_u64 v[186:187], v[184:185], 0, v[134:135]
	v_cvt_pk_bf16_f32 v155, v92, v93
	s_nop 1
	v_mov_b32_dpp v168, v0 quad_perm:[1,0,3,2] row_mask:0xf bank_mask:0xf
	v_mov_b32_dpp v169, v155 quad_perm:[1,0,3,2] row_mask:0xf bank_mask:0xf
	v_lshl_add_u64 v[172:173], v[186:187], 0, v[166:167]
	v_perm_b32 v168, v168, v0, v165
	v_perm_b32 v169, v169, v155, v165
	s_nop 1
	v_mov_b32_dpp v170, v168 quad_perm:[2,3,0,1] row_mask:0xf bank_mask:0xf
; __device__ __forceinline__ unsigned cvt_pk_bf16(float lo, float hi) { unsigned r; asm("v_cvt_pk_bf16_f32 %0, %1, %2" : "=v"(r) : "v"(lo), "v"(hi)); return r; }
;     __device__ __forceinline__ void operator()(const f32x4 (&acc)[2][2][4][2], const Unit& u, int wr, int wc, int fr, int fq) const {
;     ...
;         } else if (pn < 12) {
; #pragma unroll
;             for (int ai = 0; ai < 2; ++ai)
; #pragma unroll
;                 for (int m = 0; m < 4; ++m) {
;                     const int tt = wr * 64 + m * 16 + fr, cc = ccb + ai;
; #pragma unroll
;                     for (int bj = 0; bj < 2; ++bj) {
;                         const int head = 2 * (pn - 8) + bj;
; #pragma unroll
;                         for (int n = 0; n < 2; ++n) {
;                             const f32x4 x = acc[ai][bj][m][n];
;                             const unsigned a = cvt_pk_bf16(x[0], x[1]), c2 = cvt_pk_bf16(x[2], x[3]);
;                             bf16_t* tp = vT + ((size_t)((b * 8 + head) * 18 + cc) * 128 + 32 * wc + 16 * n + 4 * fq) * 128 + tt;
;                             tp[0] = (bf16_t)(a & 0xffffu); tp[128] = (bf16_t)(a >> 16); tp[256] = (bf16_t)(c2 & 0xffffu); tp[384] = (bf16_t)(c2 >> 16);
;                         }
	v_mov_b32_dpp v171, v169 quad_perm:[2,3,0,1] row_mask:0xf bank_mask:0xf
	s_nop 1
	v_cndmask_b32_e64 v168, v168, v171, s[98:99]
	v_cndmask_b32_e64 v169, v170, v169, s[98:99]
	global_store_dwordx2 v[172:173], v[168:169], off
	v_cvt_pk_bf16_f32 v0, v86, v87
	v_cvt_pk_bf16_f32 v155, v88, v89
	s_nop 1
	v_mov_b32_dpp v168, v0 quad_perm:[1,0,3,2] row_mask:0xf bank_mask:0xf
	v_mov_b32_dpp v169, v155 quad_perm:[1,0,3,2] row_mask:0xf bank_mask:0xf
	v_lshl_add_u64 v[172:173], v[158:159], 0, v[166:167]
	v_perm_b32 v168, v168, v0, v165
	v_perm_b32 v169, v169, v155, v165
	s_nop 1
	v_mov_b32_dpp v170, v168 quad_perm:[2,3,0,1] row_mask:0xf bank_mask:0xf
	v_mov_b32_dpp v171, v169 quad_perm:[2,3,0,1] row_mask:0xf bank_mask:0xf
	s_nop 1
	v_cndmask_b32_e64 v168, v168, v171, s[98:99]
	v_cndmask_b32_e64 v169, v170, v169, s[98:99]
	global_store_dwordx2 v[172:173], v[168:169], off offset:64
	v_cvt_pk_bf16_f32 v0, v82, v83
	v_lshl_add_u64 v[186:187], v[184:185], 0, v[156:157]
	s_mov_b64 s[4:5], 0x230b4060
	v_cvt_pk_bf16_f32 v155, v84, v85
	s_nop 1
	v_mov_b32_dpp v168, v0 quad_perm:[1,0,3,2] row_mask:0xf bank_mask:0xf
	v_mov_b32_dpp v169, v155 quad_perm:[1,0,3,2] row_mask:0xf bank_mask:0xf
	v_lshl_add_u64 v[172:173], v[186:187], 0, v[166:167]
	v_perm_b32 v168, v168, v0, v165
	v_perm_b32 v169, v169, v155, v165
	s_nop 1
	v_mov_b32_dpp v170, v168 quad_perm:[2,3,0,1] row_mask:0xf bank_mask:0xf
	v_mov_b32_dpp v171, v169 quad_perm:[2,3,0,1] row_mask:0xf bank_mask:0xf
	s_nop 1
	v_cndmask_b32_e64 v168, v168, v171, s[98:99]
	v_cndmask_b32_e64 v169, v170, v169, s[98:99]
	global_store_dwordx2 v[172:173], v[168:169], off
	v_lshl_add_u64 v[132:133], v[132:133], 0, s[4:5]
	v_cvt_pk_bf16_f32 v0, v78, v79
	s_or_b32 s9, s10, 1
	v_cvt_pk_bf16_f32 v155, v80, v81
	s_nop 1
	v_mov_b32_dpp v168, v0 quad_perm:[1,0,3,2] row_mask:0xf bank_mask:0xf
	v_mov_b32_dpp v169, v155 quad_perm:[1,0,3,2] row_mask:0xf bank_mask:0xf
	v_lshl_add_u64 v[172:173], v[136:137], 0, v[166:167]
	v_perm_b32 v168, v168, v0, v165
	v_perm_b32 v169, v169, v155, v165
	s_nop 1
	v_mov_b32_dpp v170, v168 quad_perm:[2,3,0,1] row_mask:0xf bank_mask:0xf
	v_mov_b32_dpp v171, v169 quad_perm:[2,3,0,1] row_mask:0xf bank_mask:0xf
	s_nop 1
	v_cndmask_b32_e64 v168, v168, v171, s[98:99]
	v_cndmask_b32_e64 v169, v170, v169, s[98:99]
	global_store_dwordx2 v[172:173], v[168:169], off offset:96
	v_cvt_pk_bf16_f32 v0, v74, v75
	v_lshl_add_u64 v[134:135], v[132:133], 0, v[134:135]
	s_add_i32 s4, s9, s0
	v_cvt_pk_bf16_f32 v136, v76, v77
	s_nop 1
	v_mov_b32_dpp v168, v0 quad_perm:[1,0,3,2] row_mask:0xf bank_mask:0xf
	v_mov_b32_dpp v169, v136 quad_perm:[1,0,3,2] row_mask:0xf bank_mask:0xf
	v_lshl_add_u64 v[172:173], v[134:135], 0, v[166:167]
	v_perm_b32 v168, v168, v0, v165
	v_perm_b32 v169, v169, v136, v165
	s_nop 1
	v_mov_b32_dpp v170, v168 quad_perm:[2,3,0,1] row_mask:0xf bank_mask:0xf
	v_mov_b32_dpp v171, v169 quad_perm:[2,3,0,1] row_mask:0xf bank_mask:0xf
	s_nop 1
	v_cndmask_b32_e64 v168, v168, v171, s[98:99]
	v_cndmask_b32_e64 v169, v170, v169, s[98:99]
	global_store_dwordx2 v[172:173], v[168:169], off
	v_cvt_pk_bf16_f32 v0, v70, v71
	v_cvt_pk_bf16_f32 v134, v72, v73
	s_ashr_i32 s5, s4, 31
	s_nop 1
	v_mov_b32_dpp v168, v0 quad_perm:[1,0,3,2] row_mask:0xf bank_mask:0xf
	v_mov_b32_dpp v169, v134 quad_perm:[1,0,3,2] row_mask:0xf bank_mask:0xf
	v_lshl_add_u64 v[172:173], v[158:159], 0, v[166:167]
	v_perm_b32 v168, v168, v0, v165
	v_perm_b32 v169, v169, v134, v165
	s_nop 1
	v_mov_b32_dpp v170, v168 quad_perm:[2,3,0,1] row_mask:0xf bank_mask:0xf
	v_mov_b32_dpp v171, v169 quad_perm:[2,3,0,1] row_mask:0xf bank_mask:0xf
	s_nop 1
	v_cndmask_b32_e64 v168, v168, v171, s[98:99]
	v_cndmask_b32_e64 v169, v170, v169, s[98:99]
	global_store_dwordx2 v[172:173], v[168:169], off offset:96
	v_cvt_pk_bf16_f32 v0, v66, v67
	v_lshl_add_u64 v[134:135], v[132:133], 0, v[156:157]
	s_lshl_b64 s[4:5], s[4:5], 15
	v_cvt_pk_bf16_f32 v136, v68, v69
	s_nop 1
	v_mov_b32_dpp v168, v0 quad_perm:[1,0,3,2] row_mask:0xf bank_mask:0xf
	v_mov_b32_dpp v169, v136 quad_perm:[1,0,3,2] row_mask:0xf bank_mask:0xf
	v_lshl_add_u64 v[172:173], v[134:135], 0, v[166:167]
	v_perm_b32 v168, v168, v0, v165
	v_perm_b32 v169, v169, v136, v165
	s_nop 1
	v_mov_b32_dpp v170, v168 quad_perm:[2,3,0,1] row_mask:0xf bank_mask:0xf
	v_mov_b32_dpp v171, v169 quad_perm:[2,3,0,1] row_mask:0xf bank_mask:0xf
	s_nop 1
	v_cndmask_b32_e64 v168, v168, v171, s[98:99]
	v_cndmask_b32_e64 v169, v170, v169, s[98:99]
	global_store_dwordx2 v[172:173], v[168:169], off
	v_mov_b32_e32 v135, s5
	v_or_b32_e32 v134, s4, v144
	s_add_i32 s0, s1, s9
	v_cvt_pk_bf16_f32 v0, v62, v63
	v_lshl_add_u64 v[136:137], v[130:131], 0, v[134:135]
	v_or_b32_e32 v134, 0x1000, v134
	s_ashr_i32 s1, s0, 31
	v_cvt_pk_bf16_f32 v155, v64, v65
	s_nop 1
	v_mov_b32_dpp v168, v0 quad_perm:[1,0,3,2] row_mask:0xf bank_mask:0xf
	v_mov_b32_dpp v169, v155 quad_perm:[1,0,3,2] row_mask:0xf bank_mask:0xf
	v_lshl_add_u64 v[172:173], v[136:137], 0, v[166:167]
	v_perm_b32 v168, v168, v0, v165
	v_perm_b32 v169, v169, v155, v165
	s_nop 1
	v_mov_b32_dpp v170, v168 quad_perm:[2,3,0,1] row_mask:0xf bank_mask:0xf
	v_mov_b32_dpp v171, v169 quad_perm:[2,3,0,1] row_mask:0xf bank_mask:0xf
	s_nop 1
	v_cndmask_b32_e64 v168, v168, v171, s[98:99]
	v_cndmask_b32_e64 v169, v170, v169, s[98:99]
	global_store_dwordx2 v[172:173], v[168:169], off
	v_cvt_pk_bf16_f32 v0, v58, v59
	v_lshl_add_u64 v[156:157], v[130:131], 0, v[134:135]
	s_lshl_b64 s[0:1], s[0:1], 15
	v_cvt_pk_bf16_f32 v155, v60, v61
	s_nop 1
	v_mov_b32_dpp v168, v0 quad_perm:[1,0,3,2] row_mask:0xf bank_mask:0xf
	v_mov_b32_dpp v169, v155 quad_perm:[1,0,3,2] row_mask:0xf bank_mask:0xf
	v_lshl_add_u64 v[172:173], v[156:157], 0, v[166:167]
; __device__ __forceinline__ unsigned cvt_pk_bf16(float lo, float hi) { unsigned r; asm("v_cvt_pk_bf16_f32 %0, %1, %2" : "=v"(r) : "v"(lo), "v"(hi)); return r; }
;     __device__ __forceinline__ void operator()(const f32x4 (&acc)[2][2][4][2], const Unit& u, int wr, int wc, int fr, int fq) const {
;     ...
;         } else if (pn < 12) {
; #pragma unroll
;             for (int ai = 0; ai < 2; ++ai)
; #pragma unroll
;                 for (int m = 0; m < 4; ++m) {
;                     const int tt = wr * 64 + m * 16 + fr, cc = ccb + ai;
; #pragma unroll
;                     for (int bj = 0; bj < 2; ++bj) {
;                         const int head = 2 * (pn - 8) + bj;
; #pragma unroll
;                         for (int n = 0; n < 2; ++n) {
;                             const f32x4 x = acc[ai][bj][m][n];
;                             const unsigned a = cvt_pk_bf16(x[0], x[1]), c2 = cvt_pk_bf16(x[2], x[3]);
;                             bf16_t* tp = vT + ((size_t)((b * 8 + head) * 18 + cc) * 128 + 32 * wc + 16 * n + 4 * fq) * 128 + tt;
;                             tp[0] = (bf16_t)(a & 0xffffu); tp[128] = (bf16_t)(a >> 16); tp[256] = (bf16_t)(c2 & 0xffffu); tp[384] = (bf16_t)(c2 >> 16);
;                         }
	v_perm_b32 v168, v168, v0, v165
	v_perm_b32 v169, v169, v155, v165
	s_nop 1
	v_mov_b32_dpp v170, v168 quad_perm:[2,3,0,1] row_mask:0xf bank_mask:0xf
	v_mov_b32_dpp v171, v169 quad_perm:[2,3,0,1] row_mask:0xf bank_mask:0xf
	s_nop 1
	v_cndmask_b32_e64 v168, v168, v171, s[98:99]
	v_cndmask_b32_e64 v169, v170, v169, s[98:99]
	global_store_dwordx2 v[172:173], v[168:169], off
	v_mov_b32_e32 v157, s1
	v_or_b32_e32 v156, s0, v144
	v_cvt_pk_bf16_f32 v0, v54, v55
	v_lshl_add_u64 v[158:159], v[130:131], 0, v[156:157]
	v_or_b32_e32 v156, 0x1000, v156
	v_cvt_pk_bf16_f32 v155, v56, v57
	s_nop 1
	v_mov_b32_dpp v168, v0 quad_perm:[1,0,3,2] row_mask:0xf bank_mask:0xf
	v_mov_b32_dpp v169, v155 quad_perm:[1,0,3,2] row_mask:0xf bank_mask:0xf
	v_lshl_add_u64 v[172:173], v[158:159], 0, v[166:167]
	v_perm_b32 v168, v168, v0, v165
	v_perm_b32 v169, v169, v155, v165
	s_nop 1
	v_mov_b32_dpp v170, v168 quad_perm:[2,3,0,1] row_mask:0xf bank_mask:0xf
	v_mov_b32_dpp v171, v169 quad_perm:[2,3,0,1] row_mask:0xf bank_mask:0xf
	s_nop 1
	v_cndmask_b32_e64 v168, v168, v171, s[98:99]
	v_cndmask_b32_e64 v169, v170, v169, s[98:99]
	global_store_dwordx2 v[172:173], v[168:169], off
	v_cvt_pk_bf16_f32 v0, v50, v51
	v_lshl_add_u64 v[130:131], v[130:131], 0, v[156:157]
	v_cvt_pk_bf16_f32 v155, v52, v53
	s_nop 1
	v_mov_b32_dpp v168, v0 quad_perm:[1,0,3,2] row_mask:0xf bank_mask:0xf
	v_mov_b32_dpp v169, v155 quad_perm:[1,0,3,2] row_mask:0xf bank_mask:0xf
	v_lshl_add_u64 v[172:173], v[130:131], 0, v[166:167]
	v_perm_b32 v168, v168, v0, v165
	v_perm_b32 v169, v169, v155, v165
	s_nop 1
	v_mov_b32_dpp v170, v168 quad_perm:[2,3,0,1] row_mask:0xf bank_mask:0xf
	v_mov_b32_dpp v171, v169 quad_perm:[2,3,0,1] row_mask:0xf bank_mask:0xf
	s_nop 1
	v_cndmask_b32_e64 v168, v168, v171, s[98:99]
	v_cndmask_b32_e64 v169, v170, v169, s[98:99]
	global_store_dwordx2 v[172:173], v[168:169], off
	v_cvt_pk_bf16_f32 v0, v46, v47
	v_cvt_pk_bf16_f32 v130, v48, v49
	s_nop 1
	v_mov_b32_dpp v168, v0 quad_perm:[1,0,3,2] row_mask:0xf bank_mask:0xf
	v_mov_b32_dpp v169, v130 quad_perm:[1,0,3,2] row_mask:0xf bank_mask:0xf
	v_lshl_add_u64 v[172:173], v[136:137], 0, v[166:167]
	v_perm_b32 v168, v168, v0, v165
	v_perm_b32 v169, v169, v130, v165
	s_nop 1
	v_mov_b32_dpp v170, v168 quad_perm:[2,3,0,1] row_mask:0xf bank_mask:0xf
	v_mov_b32_dpp v171, v169 quad_perm:[2,3,0,1] row_mask:0xf bank_mask:0xf
	s_nop 1
	v_cndmask_b32_e64 v168, v168, v171, s[98:99]
	v_cndmask_b32_e64 v169, v170, v169, s[98:99]
	global_store_dwordx2 v[172:173], v[168:169], off offset:32
	v_cvt_pk_bf16_f32 v0, v42, v43
	v_lshl_add_u64 v[130:131], v[160:161], 0, v[134:135]
	v_cvt_pk_bf16_f32 v155, v44, v45
	s_nop 1
	v_mov_b32_dpp v168, v0 quad_perm:[1,0,3,2] row_mask:0xf bank_mask:0xf
	v_mov_b32_dpp v169, v155 quad_perm:[1,0,3,2] row_mask:0xf bank_mask:0xf
	v_lshl_add_u64 v[172:173], v[130:131], 0, v[166:167]
	v_perm_b32 v168, v168, v0, v165
	v_perm_b32 v169, v169, v155, v165
	s_nop 1
	v_mov_b32_dpp v170, v168 quad_perm:[2,3,0,1] row_mask:0xf bank_mask:0xf
	v_mov_b32_dpp v171, v169 quad_perm:[2,3,0,1] row_mask:0xf bank_mask:0xf
	s_nop 1
	v_cndmask_b32_e64 v168, v168, v171, s[98:99]
	v_cndmask_b32_e64 v169, v170, v169, s[98:99]
	global_store_dwordx2 v[172:173], v[168:169], off
	v_cvt_pk_bf16_f32 v0, v38, v39
	v_cvt_pk_bf16_f32 v130, v40, v41
	s_nop 1
	v_mov_b32_dpp v168, v0 quad_perm:[1,0,3,2] row_mask:0xf bank_mask:0xf
	v_mov_b32_dpp v169, v130 quad_perm:[1,0,3,2] row_mask:0xf bank_mask:0xf
	v_lshl_add_u64 v[172:173], v[158:159], 0, v[166:167]
	v_perm_b32 v168, v168, v0, v165
	v_perm_b32 v169, v169, v130, v165
	s_nop 1
	v_mov_b32_dpp v170, v168 quad_perm:[2,3,0,1] row_mask:0xf bank_mask:0xf
	v_mov_b32_dpp v171, v169 quad_perm:[2,3,0,1] row_mask:0xf bank_mask:0xf
	s_nop 1
	v_cndmask_b32_e64 v168, v168, v171, s[98:99]
	v_cndmask_b32_e64 v169, v170, v169, s[98:99]
	global_store_dwordx2 v[172:173], v[168:169], off offset:32
	v_cvt_pk_bf16_f32 v0, v34, v35
	v_lshl_add_u64 v[130:131], v[160:161], 0, v[156:157]
	v_cvt_pk_bf16_f32 v155, v36, v37
	s_nop 1
	v_mov_b32_dpp v168, v0 quad_perm:[1,0,3,2] row_mask:0xf bank_mask:0xf
	v_mov_b32_dpp v169, v155 quad_perm:[1,0,3,2] row_mask:0xf bank_mask:0xf
	v_lshl_add_u64 v[172:173], v[130:131], 0, v[166:167]
	v_perm_b32 v168, v168, v0, v165
	v_perm_b32 v169, v169, v155, v165
	s_nop 1
	v_mov_b32_dpp v170, v168 quad_perm:[2,3,0,1] row_mask:0xf bank_mask:0xf
	v_mov_b32_dpp v171, v169 quad_perm:[2,3,0,1] row_mask:0xf bank_mask:0xf
	s_nop 1
	v_cndmask_b32_e64 v168, v168, v171, s[98:99]
	v_cndmask_b32_e64 v169, v170, v169, s[98:99]
	global_store_dwordx2 v[172:173], v[168:169], off
	v_cvt_pk_bf16_f32 v0, v30, v31
	v_cvt_pk_bf16_f32 v130, v32, v33
	s_nop 1
	v_mov_b32_dpp v168, v0 quad_perm:[1,0,3,2] row_mask:0xf bank_mask:0xf
	v_mov_b32_dpp v169, v130 quad_perm:[1,0,3,2] row_mask:0xf bank_mask:0xf
	v_lshl_add_u64 v[172:173], v[136:137], 0, v[166:167]
	v_perm_b32 v168, v168, v0, v165
	v_perm_b32 v169, v169, v130, v165
	s_nop 1
	v_mov_b32_dpp v170, v168 quad_perm:[2,3,0,1] row_mask:0xf bank_mask:0xf
; __device__ __forceinline__ unsigned cvt_pk_bf16(float lo, float hi) { unsigned r; asm("v_cvt_pk_bf16_f32 %0, %1, %2" : "=v"(r) : "v"(lo), "v"(hi)); return r; }
;     __device__ __forceinline__ void operator()(const f32x4 (&acc)[2][2][4][2], const Unit& u, int wr, int wc, int fr, int fq) const {
;     ...
;         } else if (pn < 12) {
; #pragma unroll
;             for (int ai = 0; ai < 2; ++ai)
; #pragma unroll
;                 for (int m = 0; m < 4; ++m) {
;                     const int tt = wr * 64 + m * 16 + fr, cc = ccb + ai;
; #pragma unroll
;                     for (int bj = 0; bj < 2; ++bj) {
;                         const int head = 2 * (pn - 8) + bj;
; #pragma unroll
;                         for (int n = 0; n < 2; ++n) {
;                             const f32x4 x = acc[ai][bj][m][n];
;                             const unsigned a = cvt_pk_bf16(x[0], x[1]), c2 = cvt_pk_bf16(x[2], x[3]);
;                             bf16_t* tp = vT + ((size_t)((b * 8 + head) * 18 + cc) * 128 + 32 * wc + 16 * n + 4 * fq) * 128 + tt;
;                             tp[0] = (bf16_t)(a & 0xffffu); tp[128] = (bf16_t)(a >> 16); tp[256] = (bf16_t)(c2 & 0xffffu); tp[384] = (bf16_t)(c2 >> 16);
;                         }
	v_mov_b32_dpp v171, v169 quad_perm:[2,3,0,1] row_mask:0xf bank_mask:0xf
	s_nop 1
	v_cndmask_b32_e64 v168, v168, v171, s[98:99]
	v_cndmask_b32_e64 v169, v170, v169, s[98:99]
	global_store_dwordx2 v[172:173], v[168:169], off offset:64
	v_cvt_pk_bf16_f32 v0, v26, v27
	v_lshl_add_u64 v[130:131], v[184:185], 0, v[134:135]
	v_cvt_pk_bf16_f32 v155, v28, v29
	s_nop 1
	v_mov_b32_dpp v168, v0 quad_perm:[1,0,3,2] row_mask:0xf bank_mask:0xf
	v_mov_b32_dpp v169, v155 quad_perm:[1,0,3,2] row_mask:0xf bank_mask:0xf
	v_lshl_add_u64 v[172:173], v[130:131], 0, v[166:167]
	v_perm_b32 v168, v168, v0, v165
	v_perm_b32 v169, v169, v155, v165
	s_nop 1
	v_mov_b32_dpp v170, v168 quad_perm:[2,3,0,1] row_mask:0xf bank_mask:0xf
	v_mov_b32_dpp v171, v169 quad_perm:[2,3,0,1] row_mask:0xf bank_mask:0xf
	s_nop 1
	v_cndmask_b32_e64 v168, v168, v171, s[98:99]
	v_cndmask_b32_e64 v169, v170, v169, s[98:99]
	global_store_dwordx2 v[172:173], v[168:169], off
	v_cvt_pk_bf16_f32 v0, v22, v23
	v_cvt_pk_bf16_f32 v130, v24, v25
	s_nop 1
	v_mov_b32_dpp v168, v0 quad_perm:[1,0,3,2] row_mask:0xf bank_mask:0xf
	v_mov_b32_dpp v169, v130 quad_perm:[1,0,3,2] row_mask:0xf bank_mask:0xf
	v_lshl_add_u64 v[172:173], v[158:159], 0, v[166:167]
	v_perm_b32 v168, v168, v0, v165
	v_perm_b32 v169, v169, v130, v165
	s_nop 1
	v_mov_b32_dpp v170, v168 quad_perm:[2,3,0,1] row_mask:0xf bank_mask:0xf
	v_mov_b32_dpp v171, v169 quad_perm:[2,3,0,1] row_mask:0xf bank_mask:0xf
	s_nop 1
	v_cndmask_b32_e64 v168, v168, v171, s[98:99]
	v_cndmask_b32_e64 v169, v170, v169, s[98:99]
	global_store_dwordx2 v[172:173], v[168:169], off offset:64
	v_cvt_pk_bf16_f32 v0, v18, v19
	v_lshl_add_u64 v[130:131], v[184:185], 0, v[156:157]
	v_cvt_pk_bf16_f32 v155, v20, v21
	s_nop 1
	v_mov_b32_dpp v168, v0 quad_perm:[1,0,3,2] row_mask:0xf bank_mask:0xf
	v_mov_b32_dpp v169, v155 quad_perm:[1,0,3,2] row_mask:0xf bank_mask:0xf
	v_lshl_add_u64 v[172:173], v[130:131], 0, v[166:167]
	v_perm_b32 v168, v168, v0, v165
	v_perm_b32 v169, v169, v155, v165
	s_nop 1
	v_mov_b32_dpp v170, v168 quad_perm:[2,3,0,1] row_mask:0xf bank_mask:0xf
	v_mov_b32_dpp v171, v169 quad_perm:[2,3,0,1] row_mask:0xf bank_mask:0xf
	s_nop 1
	v_cndmask_b32_e64 v168, v168, v171, s[98:99]
	v_cndmask_b32_e64 v169, v170, v169, s[98:99]
	global_store_dwordx2 v[172:173], v[168:169], off
	v_cvt_pk_bf16_f32 v0, v14, v15
	v_cvt_pk_bf16_f32 v130, v16, v17
	s_nop 1
	v_mov_b32_dpp v168, v0 quad_perm:[1,0,3,2] row_mask:0xf bank_mask:0xf
	v_mov_b32_dpp v169, v130 quad_perm:[1,0,3,2] row_mask:0xf bank_mask:0xf
	v_lshl_add_u64 v[172:173], v[136:137], 0, v[166:167]
	v_perm_b32 v168, v168, v0, v165
	v_perm_b32 v169, v169, v130, v165
	s_nop 1
	v_mov_b32_dpp v170, v168 quad_perm:[2,3,0,1] row_mask:0xf bank_mask:0xf
	v_mov_b32_dpp v171, v169 quad_perm:[2,3,0,1] row_mask:0xf bank_mask:0xf
	s_nop 1
	v_cndmask_b32_e64 v168, v168, v171, s[98:99]
	v_cndmask_b32_e64 v169, v170, v169, s[98:99]
	global_store_dwordx2 v[172:173], v[168:169], off offset:96
	v_cvt_pk_bf16_f32 v0, v10, v11
	v_lshl_add_u64 v[130:131], v[132:133], 0, v[134:135]
	v_cvt_pk_bf16_f32 v136, v12, v13
	s_nop 1
	v_mov_b32_dpp v168, v0 quad_perm:[1,0,3,2] row_mask:0xf bank_mask:0xf
	v_mov_b32_dpp v169, v136 quad_perm:[1,0,3,2] row_mask:0xf bank_mask:0xf
	v_lshl_add_u64 v[172:173], v[130:131], 0, v[166:167]
	v_perm_b32 v168, v168, v0, v165
	v_perm_b32 v169, v169, v136, v165
	s_nop 1
	v_mov_b32_dpp v170, v168 quad_perm:[2,3,0,1] row_mask:0xf bank_mask:0xf
	v_mov_b32_dpp v171, v169 quad_perm:[2,3,0,1] row_mask:0xf bank_mask:0xf
	s_nop 1
	v_cndmask_b32_e64 v168, v168, v171, s[98:99]
	v_cndmask_b32_e64 v169, v170, v169, s[98:99]
	global_store_dwordx2 v[172:173], v[168:169], off
	v_cvt_pk_bf16_f32 v0, v6, v7
	v_cvt_pk_bf16_f32 v130, v8, v9
	s_nop 1
	v_mov_b32_dpp v168, v0 quad_perm:[1,0,3,2] row_mask:0xf bank_mask:0xf
	v_mov_b32_dpp v169, v130 quad_perm:[1,0,3,2] row_mask:0xf bank_mask:0xf
	v_lshl_add_u64 v[172:173], v[158:159], 0, v[166:167]
	v_perm_b32 v168, v168, v0, v165
	v_perm_b32 v169, v169, v130, v165
	s_nop 1
	v_mov_b32_dpp v170, v168 quad_perm:[2,3,0,1] row_mask:0xf bank_mask:0xf
	v_mov_b32_dpp v171, v169 quad_perm:[2,3,0,1] row_mask:0xf bank_mask:0xf
	s_nop 1
	v_cndmask_b32_e64 v168, v168, v171, s[98:99]
	v_cndmask_b32_e64 v169, v170, v169, s[98:99]
	global_store_dwordx2 v[172:173], v[168:169], off offset:96
	v_cvt_pk_bf16_f32 v0, v2, v3
	v_lshl_add_u64 v[130:131], v[132:133], 0, v[156:157]
	v_cvt_pk_bf16_f32 v134, v4, v5
	s_nop 1
	v_mov_b32_dpp v168, v0 quad_perm:[1,0,3,2] row_mask:0xf bank_mask:0xf
	v_mov_b32_dpp v169, v134 quad_perm:[1,0,3,2] row_mask:0xf bank_mask:0xf
	v_lshl_add_u64 v[172:173], v[130:131], 0, v[166:167]
	v_perm_b32 v168, v168, v0, v165
	v_perm_b32 v169, v169, v134, v165
	s_nop 1
	v_mov_b32_dpp v170, v168 quad_perm:[2,3,0,1] row_mask:0xf bank_mask:0xf
	v_mov_b32_dpp v171, v169 quad_perm:[2,3,0,1] row_mask:0xf bank_mask:0xf
	s_nop 1
	v_cndmask_b32_e64 v168, v168, v171, s[98:99]
	v_cndmask_b32_e64 v169, v170, v169, s[98:99]
	global_store_dwordx2 v[172:173], v[168:169], off

; __device__ __forceinline__ unsigned cvt_pk_bf16(float lo, float hi) { unsigned r; asm("v_cvt_pk_bf16_f32 %0, %1, %2" : "=v"(r) : "v"(lo), "v"(hi)); return r; }
;     __device__ __forceinline__ void operator()(const f32x4 (&acc)[2][2][4][2], const Unit& u, int wr, int wc, int fr, int fq) const {
;     ...
;                     for (int bj = 0; bj < 2; ++bj) {
;                         const int head = 2 * (pn & 3) + bj;
;                         const f32x4 x1 = acc[ai][bj][m][0], x2 = acc[ai][bj][m][1];
;                         f32x4 o1 = x1 * cs - x2 * sn, o2 = x1 * sn + x2 * cs;
;                         if (isk) { o1 = o1 * KSCALE; o2 = o2 * KSCALE; }
;                         u32x2 w1, w2; w1.x = cvt_pk_bf16(o1[0], o1[1]); w1.y = cvt_pk_bf16(o1[2], o1[3]); w2.x = cvt_pk_bf16(o2[0], o2[1]); w2.y = cvt_pk_bf16(o2[2], o2[3]);
;                         if (!ctx) { bf16_t* dp = (isk ? k : q) + (size_t)row * 1024 + head * 128 + d0; *(u32x2*)dp = w1; *(u32x2*)(dp + 64) = w2; }
;                         if (isk) {
;                             bf16_t* tp = kT + ((size_t)((b * 8 + head) * 18 + cc) * 128 + d0) * 128 + tt;
;                             tp[0] = (bf16_t)(w1.x & 0xffffu); tp[128] = (bf16_t)(w1.x >> 16); tp[256] = (bf16_t)(w1.y & 0xffffu); tp[384] = (bf16_t)(w1.y >> 16);
;                             tp += 64 * 128;
;                             tp[0] = (bf16_t)(w2.x & 0xffffu); tp[128] = (bf16_t)(w2.x >> 16); tp[256] = (bf16_t)(w2.y & 0xffffu); tp[384] = (bf16_t)(w2.y >> 16);
;                         }
.LBB0_149:
	s_lshl_b32 s39, s8, 3
	s_add_u32 s17, s24, 0x21eb4000
	v_cndmask_b32_e64 v122, 0, 1, s[6:7]
	s_addc_u32 s19, s25, 0
	s_mov_b64 s[0:1], 0x1feb4000
	v_cmp_ne_u32_e64 s[8:9], 1, v122
	s_andn2_b64 vcc, exec, s[6:7]
	v_lshlrev_b32_e32 v122, 1, v148
	s_cbranch_vccnz .LBB0_151
	s_or_b32 s0, s11, s39
	s_mul_i32 s0, s0, 18
	s_add_i32 s0, s0, s10
	s_ashr_i32 s1, s0, 31
	s_lshl_b64 s[0:1], s[0:1], 15
	s_add_u32 s0, s17, s0
	s_addc_u32 s1, s19, s1
	v_mov_b32_e32 v123, v1
	v_lshl_add_u64 v[128:129], s[0:1], 0, v[122:123]
	v_lshl_add_u64 v[128:129], v[142:143], 1, v[128:129]
	s_nop 1
	v_mov_b32_dpp v168, v126 quad_perm:[1,0,3,2] row_mask:0xf bank_mask:0xf
	v_mov_b32_dpp v169, v127 quad_perm:[1,0,3,2] row_mask:0xf bank_mask:0xf
	v_lshl_add_u64 v[172:173], v[128:129], 0, v[166:167]
	v_perm_b32 v168, v168, v126, v165
	v_perm_b32 v169, v169, v127, v165
	s_nop 1
	v_mov_b32_dpp v170, v168 quad_perm:[2,3,0,1] row_mask:0xf bank_mask:0xf
	v_mov_b32_dpp v171, v169 quad_perm:[2,3,0,1] row_mask:0xf bank_mask:0xf
	s_nop 1
	v_cndmask_b32_e64 v168, v168, v171, s[98:99]
	v_cndmask_b32_e64 v169, v170, v169, s[98:99]
	global_store_dwordx2 v[172:173], v[168:169], off
	v_add_co_u32_e32 v126, vcc, 0x4000, v128
	s_mov_b64 s[0:1], 0x20eb4000
	s_nop 0
	v_addc_co_u32_e32 v127, vcc, 0, v129, vcc
	s_nop 1
	v_mov_b32_dpp v168, v124 quad_perm:[1,0,3,2] row_mask:0xf bank_mask:0xf
	v_mov_b32_dpp v169, v125 quad_perm:[1,0,3,2] row_mask:0xf bank_mask:0xf
	v_lshl_add_u64 v[172:173], v[126:127], 0, v[166:167]
	v_perm_b32 v168, v168, v124, v165
	v_perm_b32 v169, v169, v125, v165
	s_nop 1
	v_mov_b32_dpp v170, v168 quad_perm:[2,3,0,1] row_mask:0xf bank_mask:0xf
	v_mov_b32_dpp v171, v169 quad_perm:[2,3,0,1] row_mask:0xf bank_mask:0xf
	s_nop 1
	v_cndmask_b32_e64 v168, v168, v171, s[98:99]
	v_cndmask_b32_e64 v169, v170, v169, s[98:99]
	global_store_dwordx2 v[172:173], v[168:169], off

; __device__ __forceinline__ unsigned cvt_pk_bf16(float lo, float hi) { unsigned r; asm("v_cvt_pk_bf16_f32 %0, %1, %2" : "=v"(r) : "v"(lo), "v"(hi)); return r; }
;     __device__ __forceinline__ void operator()(const f32x4 (&acc)[2][2][4][2], const Unit& u, int wr, int wc, int fr, int fq) const {
;     ...
;                     for (int bj = 0; bj < 2; ++bj) {
;                         const int head = 2 * (pn & 3) + bj;
;                         const f32x4 x1 = acc[ai][bj][m][0], x2 = acc[ai][bj][m][1];
;                         f32x4 o1 = x1 * cs - x2 * sn, o2 = x1 * sn + x2 * cs;
;                         if (isk) { o1 = o1 * KSCALE; o2 = o2 * KSCALE; }
;                         u32x2 w1, w2; w1.x = cvt_pk_bf16(o1[0], o1[1]); w1.y = cvt_pk_bf16(o1[2], o1[3]); w2.x = cvt_pk_bf16(o2[0], o2[1]); w2.y = cvt_pk_bf16(o2[2], o2[3]);
;                         if (!ctx) { bf16_t* dp = (isk ? k : q) + (size_t)row * 1024 + head * 128 + d0; *(u32x2*)dp = w1; *(u32x2*)(dp + 64) = w2; }
;                         if (isk) {
;                             bf16_t* tp = kT + ((size_t)((b * 8 + head) * 18 + cc) * 128 + d0) * 128 + tt;
;                             tp[0] = (bf16_t)(w1.x & 0xffffu); tp[128] = (bf16_t)(w1.x >> 16); tp[256] = (bf16_t)(w1.y & 0xffffu); tp[384] = (bf16_t)(w1.y >> 16);
;                             tp += 64 * 128;
;                             tp[0] = (bf16_t)(w2.x & 0xffffu); tp[128] = (bf16_t)(w2.x >> 16); tp[256] = (bf16_t)(w2.y & 0xffffu); tp[384] = (bf16_t)(w2.y >> 16);
;                         }
.LBB0_156:
	s_or_b32 s0, s40, s39
	s_mul_i32 s0, s0, 18
	s_add_i32 s0, s0, s10
	s_ashr_i32 s1, s0, 31
	s_lshl_b64 s[0:1], s[0:1], 15
	s_add_u32 s0, s17, s0
	s_addc_u32 s1, s19, s1
	v_mov_b32_e32 v123, v1
	v_lshl_add_u64 v[118:119], s[0:1], 0, v[122:123]
	v_lshl_add_u64 v[118:119], v[142:143], 1, v[118:119]
	s_nop 1
	v_mov_b32_dpp v168, v116 quad_perm:[1,0,3,2] row_mask:0xf bank_mask:0xf
	v_mov_b32_dpp v169, v117 quad_perm:[1,0,3,2] row_mask:0xf bank_mask:0xf
	v_lshl_add_u64 v[172:173], v[118:119], 0, v[166:167]
	v_perm_b32 v168, v168, v116, v165
	v_perm_b32 v169, v169, v117, v165
	s_nop 1
	v_mov_b32_dpp v170, v168 quad_perm:[2,3,0,1] row_mask:0xf bank_mask:0xf
	v_mov_b32_dpp v171, v169 quad_perm:[2,3,0,1] row_mask:0xf bank_mask:0xf
	s_nop 1
	v_cndmask_b32_e64 v168, v168, v171, s[98:99]
	v_cndmask_b32_e64 v169, v170, v169, s[98:99]
	global_store_dwordx2 v[172:173], v[168:169], off
	v_add_co_u32_e32 v116, vcc, 0x4000, v118
	s_nop 1
	v_addc_co_u32_e32 v117, vcc, 0, v119, vcc
	s_nop 1
	v_mov_b32_dpp v168, v114 quad_perm:[1,0,3,2] row_mask:0xf bank_mask:0xf
	v_mov_b32_dpp v169, v115 quad_perm:[1,0,3,2] row_mask:0xf bank_mask:0xf
	v_lshl_add_u64 v[172:173], v[116:117], 0, v[166:167]
	v_perm_b32 v168, v168, v114, v165
	v_perm_b32 v169, v169, v115, v165
	s_nop 1
	v_mov_b32_dpp v170, v168 quad_perm:[2,3,0,1] row_mask:0xf bank_mask:0xf
	v_mov_b32_dpp v171, v169 quad_perm:[2,3,0,1] row_mask:0xf bank_mask:0xf
	s_nop 1
	v_cndmask_b32_e64 v168, v168, v171, s[98:99]
	v_cndmask_b32_e64 v169, v170, v169, s[98:99]
	global_store_dwordx2 v[172:173], v[168:169], off
	s_and_b64 vcc, exec, s[4:5]
	v_or_b32_e32 v124, 16, v154
	s_cbranch_vccz .LBB0_154

; __device__ __forceinline__ unsigned cvt_pk_bf16(float lo, float hi) { unsigned r; asm("v_cvt_pk_bf16_f32 %0, %1, %2" : "=v"(r) : "v"(lo), "v"(hi)); return r; }
;     __device__ __forceinline__ void operator()(const f32x4 (&acc)[2][2][4][2], const Unit& u, int wr, int wc, int fr, int fq) const {
;     ...
;                     for (int bj = 0; bj < 2; ++bj) {
;                         const int head = 2 * (pn & 3) + bj;
;                         const f32x4 x1 = acc[ai][bj][m][0], x2 = acc[ai][bj][m][1];
;                         f32x4 o1 = x1 * cs - x2 * sn, o2 = x1 * sn + x2 * cs;
;                         if (isk) { o1 = o1 * KSCALE; o2 = o2 * KSCALE; }
;                         u32x2 w1, w2; w1.x = cvt_pk_bf16(o1[0], o1[1]); w1.y = cvt_pk_bf16(o1[2], o1[3]); w2.x = cvt_pk_bf16(o2[0], o2[1]); w2.y = cvt_pk_bf16(o2[2], o2[3]);
;                         if (!ctx) { bf16_t* dp = (isk ? k : q) + (size_t)row * 1024 + head * 128 + d0; *(u32x2*)dp = w1; *(u32x2*)(dp + 64) = w2; }
;                         if (isk) {
;                             bf16_t* tp = kT + ((size_t)((b * 8 + head) * 18 + cc) * 128 + d0) * 128 + tt;
;                             tp[0] = (bf16_t)(w1.x & 0xffffu); tp[128] = (bf16_t)(w1.x >> 16); tp[256] = (bf16_t)(w1.y & 0xffffu); tp[384] = (bf16_t)(w1.y >> 16);
;                             tp += 64 * 128;
;                             tp[0] = (bf16_t)(w2.x & 0xffffu); tp[128] = (bf16_t)(w2.x >> 16); tp[256] = (bf16_t)(w2.y & 0xffffu); tp[384] = (bf16_t)(w2.y >> 16);
;                         }
.LBB0_160:
	s_and_b64 vcc, exec, s[8:9]
	s_mov_b64 s[0:1], 0x1feb4000
	s_cbranch_vccnz .LBB0_162
	s_or_b32 s0, s11, s39
	s_mul_i32 s0, s0, 18
	s_add_i32 s0, s0, s10
	s_ashr_i32 s1, s0, 31
	s_lshl_b64 s[0:1], s[0:1], 15
	s_add_u32 s0, s17, s0
	s_addc_u32 s1, s19, s1
	v_mov_b32_e32 v123, v1
	v_lshl_add_u64 v[110:111], s[0:1], 0, v[122:123]
	v_lshl_add_u64 v[110:111], v[142:143], 1, v[110:111]
	s_nop 1
	v_mov_b32_dpp v168, v108 quad_perm:[1,0,3,2] row_mask:0xf bank_mask:0xf
	v_mov_b32_dpp v169, v109 quad_perm:[1,0,3,2] row_mask:0xf bank_mask:0xf
	v_lshl_add_u64 v[172:173], v[110:111], 0, v[166:167]
	v_perm_b32 v168, v168, v108, v165
	v_perm_b32 v169, v169, v109, v165
	s_nop 1
	v_mov_b32_dpp v170, v168 quad_perm:[2,3,0,1] row_mask:0xf bank_mask:0xf
	v_mov_b32_dpp v171, v169 quad_perm:[2,3,0,1] row_mask:0xf bank_mask:0xf
	s_nop 1
	v_cndmask_b32_e64 v168, v168, v171, s[98:99]
	v_cndmask_b32_e64 v169, v170, v169, s[98:99]
	global_store_dwordx2 v[172:173], v[168:169], off offset:32
	v_add_co_u32_e32 v108, vcc, 0x4000, v110
	s_mov_b64 s[0:1], 0x20eb4000
	s_nop 0
	v_addc_co_u32_e32 v109, vcc, 0, v111, vcc
	s_nop 1
	v_mov_b32_dpp v168, v106 quad_perm:[1,0,3,2] row_mask:0xf bank_mask:0xf
	v_mov_b32_dpp v169, v107 quad_perm:[1,0,3,2] row_mask:0xf bank_mask:0xf
	v_lshl_add_u64 v[172:173], v[108:109], 0, v[166:167]
	v_perm_b32 v168, v168, v106, v165
	v_perm_b32 v169, v169, v107, v165
	s_nop 1
	v_mov_b32_dpp v170, v168 quad_perm:[2,3,0,1] row_mask:0xf bank_mask:0xf
	v_mov_b32_dpp v171, v169 quad_perm:[2,3,0,1] row_mask:0xf bank_mask:0xf
	s_nop 1
	v_cndmask_b32_e64 v168, v168, v171, s[98:99]
	v_cndmask_b32_e64 v169, v170, v169, s[98:99]
	global_store_dwordx2 v[172:173], v[168:169], off offset:32

; __device__ __forceinline__ unsigned cvt_pk_bf16(float lo, float hi) { unsigned r; asm("v_cvt_pk_bf16_f32 %0, %1, %2" : "=v"(r) : "v"(lo), "v"(hi)); return r; }
;     __device__ __forceinline__ void operator()(const f32x4 (&acc)[2][2][4][2], const Unit& u, int wr, int wc, int fr, int fq) const {
;     ...
;                     for (int bj = 0; bj < 2; ++bj) {
;                         const int head = 2 * (pn & 3) + bj;
;                         const f32x4 x1 = acc[ai][bj][m][0], x2 = acc[ai][bj][m][1];
;                         f32x4 o1 = x1 * cs - x2 * sn, o2 = x1 * sn + x2 * cs;
;                         if (isk) { o1 = o1 * KSCALE; o2 = o2 * KSCALE; }
;                         u32x2 w1, w2; w1.x = cvt_pk_bf16(o1[0], o1[1]); w1.y = cvt_pk_bf16(o1[2], o1[3]); w2.x = cvt_pk_bf16(o2[0], o2[1]); w2.y = cvt_pk_bf16(o2[2], o2[3]);
;                         if (!ctx) { bf16_t* dp = (isk ? k : q) + (size_t)row * 1024 + head * 128 + d0; *(u32x2*)dp = w1; *(u32x2*)(dp + 64) = w2; }
;                         if (isk) {
;                             bf16_t* tp = kT + ((size_t)((b * 8 + head) * 18 + cc) * 128 + d0) * 128 + tt;
;                             tp[0] = (bf16_t)(w1.x & 0xffffu); tp[128] = (bf16_t)(w1.x >> 16); tp[256] = (bf16_t)(w1.y & 0xffffu); tp[384] = (bf16_t)(w1.y >> 16);
;                             tp += 64 * 128;
;                             tp[0] = (bf16_t)(w2.x & 0xffffu); tp[128] = (bf16_t)(w2.x >> 16); tp[256] = (bf16_t)(w2.y & 0xffffu); tp[384] = (bf16_t)(w2.y >> 16);
;                         }
.LBB0_167:
	s_or_b32 s0, s40, s39
	s_mul_i32 s0, s0, 18
	s_add_i32 s0, s0, s10
	s_ashr_i32 s1, s0, 31
	s_lshl_b64 s[0:1], s[0:1], 15
	s_add_u32 s0, s17, s0
	s_addc_u32 s1, s19, s1
	v_mov_b32_e32 v123, v1
	v_lshl_add_u64 v[102:103], s[0:1], 0, v[122:123]
	v_lshl_add_u64 v[102:103], v[142:143], 1, v[102:103]
	s_nop 1
	v_mov_b32_dpp v168, v100 quad_perm:[1,0,3,2] row_mask:0xf bank_mask:0xf
	v_mov_b32_dpp v169, v101 quad_perm:[1,0,3,2] row_mask:0xf bank_mask:0xf
	v_lshl_add_u64 v[172:173], v[102:103], 0, v[166:167]
	v_perm_b32 v168, v168, v100, v165
	v_perm_b32 v169, v169, v101, v165
	s_nop 1
	v_mov_b32_dpp v170, v168 quad_perm:[2,3,0,1] row_mask:0xf bank_mask:0xf
	v_mov_b32_dpp v171, v169 quad_perm:[2,3,0,1] row_mask:0xf bank_mask:0xf
	s_nop 1
	v_cndmask_b32_e64 v168, v168, v171, s[98:99]
	v_cndmask_b32_e64 v169, v170, v169, s[98:99]
	global_store_dwordx2 v[172:173], v[168:169], off offset:32
	v_add_co_u32_e32 v100, vcc, 0x4000, v102
	s_nop 1
	v_addc_co_u32_e32 v101, vcc, 0, v103, vcc
	s_nop 1
	v_mov_b32_dpp v168, v98 quad_perm:[1,0,3,2] row_mask:0xf bank_mask:0xf
	v_mov_b32_dpp v169, v99 quad_perm:[1,0,3,2] row_mask:0xf bank_mask:0xf
	v_lshl_add_u64 v[172:173], v[100:101], 0, v[166:167]
	v_perm_b32 v168, v168, v98, v165
	v_perm_b32 v169, v169, v99, v165
	s_nop 1
	v_mov_b32_dpp v170, v168 quad_perm:[2,3,0,1] row_mask:0xf bank_mask:0xf
	v_mov_b32_dpp v171, v169 quad_perm:[2,3,0,1] row_mask:0xf bank_mask:0xf
	s_nop 1
	v_cndmask_b32_e64 v168, v168, v171, s[98:99]
	v_cndmask_b32_e64 v169, v170, v169, s[98:99]
	global_store_dwordx2 v[172:173], v[168:169], off offset:32
	s_and_b64 vcc, exec, s[4:5]
	v_or_b32_e32 v106, 32, v154
	s_cbranch_vccz .LBB0_165

; __device__ __forceinline__ unsigned cvt_pk_bf16(float lo, float hi) { unsigned r; asm("v_cvt_pk_bf16_f32 %0, %1, %2" : "=v"(r) : "v"(lo), "v"(hi)); return r; }
;     __device__ __forceinline__ void operator()(const f32x4 (&acc)[2][2][4][2], const Unit& u, int wr, int wc, int fr, int fq) const {
;     ...
;                     for (int bj = 0; bj < 2; ++bj) {
;                         const int head = 2 * (pn & 3) + bj;
;                         const f32x4 x1 = acc[ai][bj][m][0], x2 = acc[ai][bj][m][1];
;                         f32x4 o1 = x1 * cs - x2 * sn, o2 = x1 * sn + x2 * cs;
;                         if (isk) { o1 = o1 * KSCALE; o2 = o2 * KSCALE; }
;                         u32x2 w1, w2; w1.x = cvt_pk_bf16(o1[0], o1[1]); w1.y = cvt_pk_bf16(o1[2], o1[3]); w2.x = cvt_pk_bf16(o2[0], o2[1]); w2.y = cvt_pk_bf16(o2[2], o2[3]);
;                         if (!ctx) { bf16_t* dp = (isk ? k : q) + (size_t)row * 1024 + head * 128 + d0; *(u32x2*)dp = w1; *(u32x2*)(dp + 64) = w2; }
;                         if (isk) {
;                             bf16_t* tp = kT + ((size_t)((b * 8 + head) * 18 + cc) * 128 + d0) * 128 + tt;
;                             tp[0] = (bf16_t)(w1.x & 0xffffu); tp[128] = (bf16_t)(w1.x >> 16); tp[256] = (bf16_t)(w1.y & 0xffffu); tp[384] = (bf16_t)(w1.y >> 16);
;                             tp += 64 * 128;
;                             tp[0] = (bf16_t)(w2.x & 0xffffu); tp[128] = (bf16_t)(w2.x >> 16); tp[256] = (bf16_t)(w2.y & 0xffffu); tp[384] = (bf16_t)(w2.y >> 16);
;                         }
.LBB0_171:
	s_and_b64 vcc, exec, s[8:9]
	s_mov_b64 s[0:1], 0x1feb4000
	s_cbranch_vccnz .LBB0_173
	s_or_b32 s0, s11, s39
	s_mul_i32 s0, s0, 18
	s_add_i32 s0, s0, s10
	s_ashr_i32 s1, s0, 31
	s_lshl_b64 s[0:1], s[0:1], 15
	s_add_u32 s0, s17, s0
	s_addc_u32 s1, s19, s1
	v_mov_b32_e32 v123, v1
	v_lshl_add_u64 v[94:95], s[0:1], 0, v[122:123]
	v_lshl_add_u64 v[94:95], v[142:143], 1, v[94:95]
	s_nop 1
	v_mov_b32_dpp v168, v92 quad_perm:[1,0,3,2] row_mask:0xf bank_mask:0xf
	v_mov_b32_dpp v169, v93 quad_perm:[1,0,3,2] row_mask:0xf bank_mask:0xf
	v_lshl_add_u64 v[172:173], v[94:95], 0, v[166:167]
	v_perm_b32 v168, v168, v92, v165
	v_perm_b32 v169, v169, v93, v165
	s_nop 1
	v_mov_b32_dpp v170, v168 quad_perm:[2,3,0,1] row_mask:0xf bank_mask:0xf
	v_mov_b32_dpp v171, v169 quad_perm:[2,3,0,1] row_mask:0xf bank_mask:0xf
	s_nop 1
	v_cndmask_b32_e64 v168, v168, v171, s[98:99]
	v_cndmask_b32_e64 v169, v170, v169, s[98:99]
	global_store_dwordx2 v[172:173], v[168:169], off offset:64
	v_add_co_u32_e32 v92, vcc, 0x4000, v94
	s_mov_b64 s[0:1], 0x20eb4000
	s_nop 0
	v_addc_co_u32_e32 v93, vcc, 0, v95, vcc
	s_nop 1
	v_mov_b32_dpp v168, v90 quad_perm:[1,0,3,2] row_mask:0xf bank_mask:0xf
	v_mov_b32_dpp v169, v91 quad_perm:[1,0,3,2] row_mask:0xf bank_mask:0xf
	v_lshl_add_u64 v[172:173], v[92:93], 0, v[166:167]
	v_perm_b32 v168, v168, v90, v165
	v_perm_b32 v169, v169, v91, v165
	s_nop 1
	v_mov_b32_dpp v170, v168 quad_perm:[2,3,0,1] row_mask:0xf bank_mask:0xf
	v_mov_b32_dpp v171, v169 quad_perm:[2,3,0,1] row_mask:0xf bank_mask:0xf
	s_nop 1
	v_cndmask_b32_e64 v168, v168, v171, s[98:99]
	v_cndmask_b32_e64 v169, v170, v169, s[98:99]
	global_store_dwordx2 v[172:173], v[168:169], off offset:64

; __device__ __forceinline__ unsigned cvt_pk_bf16(float lo, float hi) { unsigned r; asm("v_cvt_pk_bf16_f32 %0, %1, %2" : "=v"(r) : "v"(lo), "v"(hi)); return r; }
;     __device__ __forceinline__ void operator()(const f32x4 (&acc)[2][2][4][2], const Unit& u, int wr, int wc, int fr, int fq) const {
;     ...
;                     for (int bj = 0; bj < 2; ++bj) {
;                         const int head = 2 * (pn & 3) + bj;
;                         const f32x4 x1 = acc[ai][bj][m][0], x2 = acc[ai][bj][m][1];
;                         f32x4 o1 = x1 * cs - x2 * sn, o2 = x1 * sn + x2 * cs;
;                         if (isk) { o1 = o1 * KSCALE; o2 = o2 * KSCALE; }
;                         u32x2 w1, w2; w1.x = cvt_pk_bf16(o1[0], o1[1]); w1.y = cvt_pk_bf16(o1[2], o1[3]); w2.x = cvt_pk_bf16(o2[0], o2[1]); w2.y = cvt_pk_bf16(o2[2], o2[3]);
;                         if (!ctx) { bf16_t* dp = (isk ? k : q) + (size_t)row * 1024 + head * 128 + d0; *(u32x2*)dp = w1; *(u32x2*)(dp + 64) = w2; }
;                         if (isk) {
;                             bf16_t* tp = kT + ((size_t)((b * 8 + head) * 18 + cc) * 128 + d0) * 128 + tt;
;                             tp[0] = (bf16_t)(w1.x & 0xffffu); tp[128] = (bf16_t)(w1.x >> 16); tp[256] = (bf16_t)(w1.y & 0xffffu); tp[384] = (bf16_t)(w1.y >> 16);
;                             tp += 64 * 128;
;                             tp[0] = (bf16_t)(w2.x & 0xffffu); tp[128] = (bf16_t)(w2.x >> 16); tp[256] = (bf16_t)(w2.y & 0xffffu); tp[384] = (bf16_t)(w2.y >> 16);
;                         }
.LBB0_178:
	s_or_b32 s0, s40, s39
	s_mul_i32 s0, s0, 18
	s_add_i32 s0, s0, s10
	s_ashr_i32 s1, s0, 31
	s_lshl_b64 s[0:1], s[0:1], 15
	s_add_u32 s0, s17, s0
	s_addc_u32 s1, s19, s1
	v_mov_b32_e32 v123, v1
	v_lshl_add_u64 v[86:87], s[0:1], 0, v[122:123]
	v_lshl_add_u64 v[86:87], v[142:143], 1, v[86:87]
	s_nop 1
	v_mov_b32_dpp v168, v84 quad_perm:[1,0,3,2] row_mask:0xf bank_mask:0xf
	v_mov_b32_dpp v169, v85 quad_perm:[1,0,3,2] row_mask:0xf bank_mask:0xf
	v_lshl_add_u64 v[172:173], v[86:87], 0, v[166:167]
	v_perm_b32 v168, v168, v84, v165
	v_perm_b32 v169, v169, v85, v165
	s_nop 1
	v_mov_b32_dpp v170, v168 quad_perm:[2,3,0,1] row_mask:0xf bank_mask:0xf
	v_mov_b32_dpp v171, v169 quad_perm:[2,3,0,1] row_mask:0xf bank_mask:0xf
	s_nop 1
	v_cndmask_b32_e64 v168, v168, v171, s[98:99]
	v_cndmask_b32_e64 v169, v170, v169, s[98:99]
	global_store_dwordx2 v[172:173], v[168:169], off offset:64
	v_add_co_u32_e32 v84, vcc, 0x4000, v86
	s_nop 1
	v_addc_co_u32_e32 v85, vcc, 0, v87, vcc
	s_nop 1
	v_mov_b32_dpp v168, v82 quad_perm:[1,0,3,2] row_mask:0xf bank_mask:0xf
	v_mov_b32_dpp v169, v83 quad_perm:[1,0,3,2] row_mask:0xf bank_mask:0xf
	v_lshl_add_u64 v[172:173], v[84:85], 0, v[166:167]
	v_perm_b32 v168, v168, v82, v165
	v_perm_b32 v169, v169, v83, v165
	s_nop 1
	v_mov_b32_dpp v170, v168 quad_perm:[2,3,0,1] row_mask:0xf bank_mask:0xf
	v_mov_b32_dpp v171, v169 quad_perm:[2,3,0,1] row_mask:0xf bank_mask:0xf
	s_nop 1
	v_cndmask_b32_e64 v168, v168, v171, s[98:99]
	v_cndmask_b32_e64 v169, v170, v169, s[98:99]
	global_store_dwordx2 v[172:173], v[168:169], off offset:64
	s_and_b64 vcc, exec, s[4:5]
	v_or_b32_e32 v90, 48, v154
	s_cbranch_vccz .LBB0_176

; __device__ __forceinline__ unsigned cvt_pk_bf16(float lo, float hi) { unsigned r; asm("v_cvt_pk_bf16_f32 %0, %1, %2" : "=v"(r) : "v"(lo), "v"(hi)); return r; }
;     __device__ __forceinline__ void operator()(const f32x4 (&acc)[2][2][4][2], const Unit& u, int wr, int wc, int fr, int fq) const {
;     ...
;                     for (int bj = 0; bj < 2; ++bj) {
;                         const int head = 2 * (pn & 3) + bj;
;                         const f32x4 x1 = acc[ai][bj][m][0], x2 = acc[ai][bj][m][1];
;                         f32x4 o1 = x1 * cs - x2 * sn, o2 = x1 * sn + x2 * cs;
;                         if (isk) { o1 = o1 * KSCALE; o2 = o2 * KSCALE; }
;                         u32x2 w1, w2; w1.x = cvt_pk_bf16(o1[0], o1[1]); w1.y = cvt_pk_bf16(o1[2], o1[3]); w2.x = cvt_pk_bf16(o2[0], o2[1]); w2.y = cvt_pk_bf16(o2[2], o2[3]);
;                         if (!ctx) { bf16_t* dp = (isk ? k : q) + (size_t)row * 1024 + head * 128 + d0; *(u32x2*)dp = w1; *(u32x2*)(dp + 64) = w2; }
;                         if (isk) {
;                             bf16_t* tp = kT + ((size_t)((b * 8 + head) * 18 + cc) * 128 + d0) * 128 + tt;
;                             tp[0] = (bf16_t)(w1.x & 0xffffu); tp[128] = (bf16_t)(w1.x >> 16); tp[256] = (bf16_t)(w1.y & 0xffffu); tp[384] = (bf16_t)(w1.y >> 16);
;                             tp += 64 * 128;
;                             tp[0] = (bf16_t)(w2.x & 0xffffu); tp[128] = (bf16_t)(w2.x >> 16); tp[256] = (bf16_t)(w2.y & 0xffffu); tp[384] = (bf16_t)(w2.y >> 16);
;                         }
.LBB0_182:
	s_and_b64 vcc, exec, s[8:9]
	s_mov_b64 s[0:1], 0x1feb4000
	s_cbranch_vccnz .LBB0_184
	s_or_b32 s0, s11, s39
	s_mul_i32 s0, s0, 18
	s_add_i32 s0, s0, s10
	s_ashr_i32 s1, s0, 31
	s_lshl_b64 s[0:1], s[0:1], 15
	s_add_u32 s0, s17, s0
	s_addc_u32 s1, s19, s1
	v_mov_b32_e32 v123, v1
	v_lshl_add_u64 v[78:79], s[0:1], 0, v[122:123]
	v_lshl_add_u64 v[78:79], v[142:143], 1, v[78:79]
	s_nop 1
	v_mov_b32_dpp v168, v76 quad_perm:[1,0,3,2] row_mask:0xf bank_mask:0xf
	v_mov_b32_dpp v169, v77 quad_perm:[1,0,3,2] row_mask:0xf bank_mask:0xf
	v_lshl_add_u64 v[172:173], v[78:79], 0, v[166:167]
	v_perm_b32 v168, v168, v76, v165
	v_perm_b32 v169, v169, v77, v165
	s_nop 1
	v_mov_b32_dpp v170, v168 quad_perm:[2,3,0,1] row_mask:0xf bank_mask:0xf
	v_mov_b32_dpp v171, v169 quad_perm:[2,3,0,1] row_mask:0xf bank_mask:0xf
	s_nop 1
	v_cndmask_b32_e64 v168, v168, v171, s[98:99]
	v_cndmask_b32_e64 v169, v170, v169, s[98:99]
	global_store_dwordx2 v[172:173], v[168:169], off offset:96
	v_add_co_u32_e32 v76, vcc, 0x4000, v78
	s_mov_b64 s[0:1], 0x20eb4000
	s_nop 0
	v_addc_co_u32_e32 v77, vcc, 0, v79, vcc
	s_nop 1
	v_mov_b32_dpp v168, v74 quad_perm:[1,0,3,2] row_mask:0xf bank_mask:0xf
	v_mov_b32_dpp v169, v75 quad_perm:[1,0,3,2] row_mask:0xf bank_mask:0xf
	v_lshl_add_u64 v[172:173], v[76:77], 0, v[166:167]
	v_perm_b32 v168, v168, v74, v165
	v_perm_b32 v169, v169, v75, v165
	s_nop 1
	v_mov_b32_dpp v170, v168 quad_perm:[2,3,0,1] row_mask:0xf bank_mask:0xf
	v_mov_b32_dpp v171, v169 quad_perm:[2,3,0,1] row_mask:0xf bank_mask:0xf
	s_nop 1
	v_cndmask_b32_e64 v168, v168, v171, s[98:99]
	v_cndmask_b32_e64 v169, v170, v169, s[98:99]
	global_store_dwordx2 v[172:173], v[168:169], off offset:96

; __device__ __forceinline__ unsigned cvt_pk_bf16(float lo, float hi) { unsigned r; asm("v_cvt_pk_bf16_f32 %0, %1, %2" : "=v"(r) : "v"(lo), "v"(hi)); return r; }
;     __device__ __forceinline__ void operator()(const f32x4 (&acc)[2][2][4][2], const Unit& u, int wr, int wc, int fr, int fq) const {
;     ...
;                     for (int bj = 0; bj < 2; ++bj) {
;                         const int head = 2 * (pn & 3) + bj;
;                         const f32x4 x1 = acc[ai][bj][m][0], x2 = acc[ai][bj][m][1];
;                         f32x4 o1 = x1 * cs - x2 * sn, o2 = x1 * sn + x2 * cs;
;                         if (isk) { o1 = o1 * KSCALE; o2 = o2 * KSCALE; }
;                         u32x2 w1, w2; w1.x = cvt_pk_bf16(o1[0], o1[1]); w1.y = cvt_pk_bf16(o1[2], o1[3]); w2.x = cvt_pk_bf16(o2[0], o2[1]); w2.y = cvt_pk_bf16(o2[2], o2[3]);
;                         if (!ctx) { bf16_t* dp = (isk ? k : q) + (size_t)row * 1024 + head * 128 + d0; *(u32x2*)dp = w1; *(u32x2*)(dp + 64) = w2; }
;                         if (isk) {
;                             bf16_t* tp = kT + ((size_t)((b * 8 + head) * 18 + cc) * 128 + d0) * 128 + tt;
;                             tp[0] = (bf16_t)(w1.x & 0xffffu); tp[128] = (bf16_t)(w1.x >> 16); tp[256] = (bf16_t)(w1.y & 0xffffu); tp[384] = (bf16_t)(w1.y >> 16);
;                             tp += 64 * 128;
;                             tp[0] = (bf16_t)(w2.x & 0xffffu); tp[128] = (bf16_t)(w2.x >> 16); tp[256] = (bf16_t)(w2.y & 0xffffu); tp[384] = (bf16_t)(w2.y >> 16);
;                         }
.LBB0_189:
	s_or_b32 s0, s40, s39
	s_mul_i32 s0, s0, 18
	s_add_i32 s0, s0, s10
	s_ashr_i32 s1, s0, 31
	s_lshl_b64 s[0:1], s[0:1], 15
	s_add_u32 s0, s17, s0
	s_addc_u32 s1, s19, s1
	v_mov_b32_e32 v123, v1
	v_lshl_add_u64 v[70:71], s[0:1], 0, v[122:123]
	v_lshl_add_u64 v[70:71], v[142:143], 1, v[70:71]
	s_nop 1
	v_mov_b32_dpp v168, v68 quad_perm:[1,0,3,2] row_mask:0xf bank_mask:0xf
	v_mov_b32_dpp v169, v69 quad_perm:[1,0,3,2] row_mask:0xf bank_mask:0xf
	v_lshl_add_u64 v[172:173], v[70:71], 0, v[166:167]
	v_perm_b32 v168, v168, v68, v165
	v_perm_b32 v169, v169, v69, v165
	s_nop 1
	v_mov_b32_dpp v170, v168 quad_perm:[2,3,0,1] row_mask:0xf bank_mask:0xf
	v_mov_b32_dpp v171, v169 quad_perm:[2,3,0,1] row_mask:0xf bank_mask:0xf
	s_nop 1
	v_cndmask_b32_e64 v168, v168, v171, s[98:99]
	v_cndmask_b32_e64 v169, v170, v169, s[98:99]
	global_store_dwordx2 v[172:173], v[168:169], off offset:96
	v_add_co_u32_e32 v68, vcc, 0x4000, v70
	s_nop 1
	v_addc_co_u32_e32 v69, vcc, 0, v71, vcc
	s_nop 1
	v_mov_b32_dpp v168, v66 quad_perm:[1,0,3,2] row_mask:0xf bank_mask:0xf
	v_mov_b32_dpp v169, v67 quad_perm:[1,0,3,2] row_mask:0xf bank_mask:0xf
	v_lshl_add_u64 v[172:173], v[68:69], 0, v[166:167]
	v_perm_b32 v168, v168, v66, v165
	v_perm_b32 v169, v169, v67, v165
	s_nop 1
	v_mov_b32_dpp v170, v168 quad_perm:[2,3,0,1] row_mask:0xf bank_mask:0xf
	v_mov_b32_dpp v171, v169 quad_perm:[2,3,0,1] row_mask:0xf bank_mask:0xf
	s_nop 1
	v_cndmask_b32_e64 v168, v168, v171, s[98:99]
	v_cndmask_b32_e64 v169, v170, v169, s[98:99]
	global_store_dwordx2 v[172:173], v[168:169], off offset:96
	s_and_b64 vcc, exec, s[4:5]
	v_add_u32_e32 v74, 0x80, v154
	s_cbranch_vccz .LBB0_187

; __device__ __forceinline__ unsigned cvt_pk_bf16(float lo, float hi) { unsigned r; asm("v_cvt_pk_bf16_f32 %0, %1, %2" : "=v"(r) : "v"(lo), "v"(hi)); return r; }
;     __device__ __forceinline__ void operator()(const f32x4 (&acc)[2][2][4][2], const Unit& u, int wr, int wc, int fr, int fq) const {
;     ...
;                     for (int bj = 0; bj < 2; ++bj) {
;                         const int head = 2 * (pn & 3) + bj;
;                         const f32x4 x1 = acc[ai][bj][m][0], x2 = acc[ai][bj][m][1];
;                         f32x4 o1 = x1 * cs - x2 * sn, o2 = x1 * sn + x2 * cs;
;                         if (isk) { o1 = o1 * KSCALE; o2 = o2 * KSCALE; }
;                         u32x2 w1, w2; w1.x = cvt_pk_bf16(o1[0], o1[1]); w1.y = cvt_pk_bf16(o1[2], o1[3]); w2.x = cvt_pk_bf16(o2[0], o2[1]); w2.y = cvt_pk_bf16(o2[2], o2[3]);
;                         if (!ctx) { bf16_t* dp = (isk ? k : q) + (size_t)row * 1024 + head * 128 + d0; *(u32x2*)dp = w1; *(u32x2*)(dp + 64) = w2; }
;                         if (isk) {
;                             bf16_t* tp = kT + ((size_t)((b * 8 + head) * 18 + cc) * 128 + d0) * 128 + tt;
;                             tp[0] = (bf16_t)(w1.x & 0xffffu); tp[128] = (bf16_t)(w1.x >> 16); tp[256] = (bf16_t)(w1.y & 0xffffu); tp[384] = (bf16_t)(w1.y >> 16);
;                             tp += 64 * 128;
;                             tp[0] = (bf16_t)(w2.x & 0xffffu); tp[128] = (bf16_t)(w2.x >> 16); tp[256] = (bf16_t)(w2.y & 0xffffu); tp[384] = (bf16_t)(w2.y >> 16);
;                         }
.LBB0_193:
	s_or_b32 s10, s10, 1
	s_and_b64 vcc, exec, s[8:9]
	s_mov_b64 s[0:1], 0x1feb4000
	s_cbranch_vccnz .LBB0_195
	s_or_b32 s0, s11, s39
	s_mul_i32 s0, s0, 18
	s_add_i32 s0, s10, s0
	s_ashr_i32 s1, s0, 31
	s_lshl_b64 s[0:1], s[0:1], 15
	s_add_u32 s0, s17, s0
	s_addc_u32 s1, s19, s1
	v_mov_b32_e32 v123, v1
	v_lshl_add_u64 v[62:63], s[0:1], 0, v[122:123]
	v_lshl_add_u64 v[62:63], v[142:143], 1, v[62:63]
	s_nop 1
	v_mov_b32_dpp v168, v60 quad_perm:[1,0,3,2] row_mask:0xf bank_mask:0xf
	v_mov_b32_dpp v169, v61 quad_perm:[1,0,3,2] row_mask:0xf bank_mask:0xf
	v_lshl_add_u64 v[172:173], v[62:63], 0, v[166:167]
	v_perm_b32 v168, v168, v60, v165
	v_perm_b32 v169, v169, v61, v165
	s_nop 1
	v_mov_b32_dpp v170, v168 quad_perm:[2,3,0,1] row_mask:0xf bank_mask:0xf
	v_mov_b32_dpp v171, v169 quad_perm:[2,3,0,1] row_mask:0xf bank_mask:0xf
	s_nop 1
	v_cndmask_b32_e64 v168, v168, v171, s[98:99]
	v_cndmask_b32_e64 v169, v170, v169, s[98:99]
	global_store_dwordx2 v[172:173], v[168:169], off
	v_add_co_u32_e32 v60, vcc, 0x4000, v62
	s_mov_b64 s[0:1], 0x20eb4000
	s_nop 0
	v_addc_co_u32_e32 v61, vcc, 0, v63, vcc
	s_nop 1
	v_mov_b32_dpp v168, v58 quad_perm:[1,0,3,2] row_mask:0xf bank_mask:0xf
	v_mov_b32_dpp v169, v59 quad_perm:[1,0,3,2] row_mask:0xf bank_mask:0xf
	v_lshl_add_u64 v[172:173], v[60:61], 0, v[166:167]
	v_perm_b32 v168, v168, v58, v165
	v_perm_b32 v169, v169, v59, v165
	s_nop 1
	v_mov_b32_dpp v170, v168 quad_perm:[2,3,0,1] row_mask:0xf bank_mask:0xf
	v_mov_b32_dpp v171, v169 quad_perm:[2,3,0,1] row_mask:0xf bank_mask:0xf
	s_nop 1
	v_cndmask_b32_e64 v168, v168, v171, s[98:99]
	v_cndmask_b32_e64 v169, v170, v169, s[98:99]
	global_store_dwordx2 v[172:173], v[168:169], off

; __device__ __forceinline__ unsigned cvt_pk_bf16(float lo, float hi) { unsigned r; asm("v_cvt_pk_bf16_f32 %0, %1, %2" : "=v"(r) : "v"(lo), "v"(hi)); return r; }
;     __device__ __forceinline__ void operator()(const f32x4 (&acc)[2][2][4][2], const Unit& u, int wr, int wc, int fr, int fq) const {
;     ...
;                     for (int bj = 0; bj < 2; ++bj) {
;                         const int head = 2 * (pn & 3) + bj;
;                         const f32x4 x1 = acc[ai][bj][m][0], x2 = acc[ai][bj][m][1];
;                         f32x4 o1 = x1 * cs - x2 * sn, o2 = x1 * sn + x2 * cs;
;                         if (isk) { o1 = o1 * KSCALE; o2 = o2 * KSCALE; }
;                         u32x2 w1, w2; w1.x = cvt_pk_bf16(o1[0], o1[1]); w1.y = cvt_pk_bf16(o1[2], o1[3]); w2.x = cvt_pk_bf16(o2[0], o2[1]); w2.y = cvt_pk_bf16(o2[2], o2[3]);
;                         if (!ctx) { bf16_t* dp = (isk ? k : q) + (size_t)row * 1024 + head * 128 + d0; *(u32x2*)dp = w1; *(u32x2*)(dp + 64) = w2; }
;                         if (isk) {
;                             bf16_t* tp = kT + ((size_t)((b * 8 + head) * 18 + cc) * 128 + d0) * 128 + tt;
;                             tp[0] = (bf16_t)(w1.x & 0xffffu); tp[128] = (bf16_t)(w1.x >> 16); tp[256] = (bf16_t)(w1.y & 0xffffu); tp[384] = (bf16_t)(w1.y >> 16);
;                             tp += 64 * 128;
;                             tp[0] = (bf16_t)(w2.x & 0xffffu); tp[128] = (bf16_t)(w2.x >> 16); tp[256] = (bf16_t)(w2.y & 0xffffu); tp[384] = (bf16_t)(w2.y >> 16);
;                         }
.LBB0_200:
	s_or_b32 s0, s40, s39
	s_mul_i32 s0, s0, 18
	s_add_i32 s0, s0, s10
	s_ashr_i32 s1, s0, 31
	s_lshl_b64 s[0:1], s[0:1], 15
	s_add_u32 s0, s17, s0
	s_addc_u32 s1, s19, s1
	v_mov_b32_e32 v123, v1
	v_lshl_add_u64 v[54:55], s[0:1], 0, v[122:123]
	v_lshl_add_u64 v[54:55], v[142:143], 1, v[54:55]
	s_nop 1
	v_mov_b32_dpp v168, v52 quad_perm:[1,0,3,2] row_mask:0xf bank_mask:0xf
	v_mov_b32_dpp v169, v53 quad_perm:[1,0,3,2] row_mask:0xf bank_mask:0xf
	v_lshl_add_u64 v[172:173], v[54:55], 0, v[166:167]
	v_perm_b32 v168, v168, v52, v165
	v_perm_b32 v169, v169, v53, v165
	s_nop 1
	v_mov_b32_dpp v170, v168 quad_perm:[2,3,0,1] row_mask:0xf bank_mask:0xf
	v_mov_b32_dpp v171, v169 quad_perm:[2,3,0,1] row_mask:0xf bank_mask:0xf
	s_nop 1
	v_cndmask_b32_e64 v168, v168, v171, s[98:99]
	v_cndmask_b32_e64 v169, v170, v169, s[98:99]
	global_store_dwordx2 v[172:173], v[168:169], off
	v_add_co_u32_e32 v52, vcc, 0x4000, v54
	s_nop 1
	v_addc_co_u32_e32 v53, vcc, 0, v55, vcc
	s_nop 1
	v_mov_b32_dpp v168, v50 quad_perm:[1,0,3,2] row_mask:0xf bank_mask:0xf
	v_mov_b32_dpp v169, v51 quad_perm:[1,0,3,2] row_mask:0xf bank_mask:0xf
	v_lshl_add_u64 v[172:173], v[52:53], 0, v[166:167]
	v_perm_b32 v168, v168, v50, v165
	v_perm_b32 v169, v169, v51, v165
	s_nop 1
	v_mov_b32_dpp v170, v168 quad_perm:[2,3,0,1] row_mask:0xf bank_mask:0xf
	v_mov_b32_dpp v171, v169 quad_perm:[2,3,0,1] row_mask:0xf bank_mask:0xf
	s_nop 1
	v_cndmask_b32_e64 v168, v168, v171, s[98:99]
	v_cndmask_b32_e64 v169, v170, v169, s[98:99]
	global_store_dwordx2 v[172:173], v[168:169], off
	s_and_b64 vcc, exec, s[4:5]
	v_add_u32_e32 v58, 0x90, v154
	s_cbranch_vccz .LBB0_198

; __device__ __forceinline__ unsigned cvt_pk_bf16(float lo, float hi) { unsigned r; asm("v_cvt_pk_bf16_f32 %0, %1, %2" : "=v"(r) : "v"(lo), "v"(hi)); return r; }
;     __device__ __forceinline__ void operator()(const f32x4 (&acc)[2][2][4][2], const Unit& u, int wr, int wc, int fr, int fq) const {
;     ...
;                     for (int bj = 0; bj < 2; ++bj) {
;                         const int head = 2 * (pn & 3) + bj;
;                         const f32x4 x1 = acc[ai][bj][m][0], x2 = acc[ai][bj][m][1];
;                         f32x4 o1 = x1 * cs - x2 * sn, o2 = x1 * sn + x2 * cs;
;                         if (isk) { o1 = o1 * KSCALE; o2 = o2 * KSCALE; }
;                         u32x2 w1, w2; w1.x = cvt_pk_bf16(o1[0], o1[1]); w1.y = cvt_pk_bf16(o1[2], o1[3]); w2.x = cvt_pk_bf16(o2[0], o2[1]); w2.y = cvt_pk_bf16(o2[2], o2[3]);
;                         if (!ctx) { bf16_t* dp = (isk ? k : q) + (size_t)row * 1024 + head * 128 + d0; *(u32x2*)dp = w1; *(u32x2*)(dp + 64) = w2; }
;                         if (isk) {
;                             bf16_t* tp = kT + ((size_t)((b * 8 + head) * 18 + cc) * 128 + d0) * 128 + tt;
;                             tp[0] = (bf16_t)(w1.x & 0xffffu); tp[128] = (bf16_t)(w1.x >> 16); tp[256] = (bf16_t)(w1.y & 0xffffu); tp[384] = (bf16_t)(w1.y >> 16);
;                             tp += 64 * 128;
;                             tp[0] = (bf16_t)(w2.x & 0xffffu); tp[128] = (bf16_t)(w2.x >> 16); tp[256] = (bf16_t)(w2.y & 0xffffu); tp[384] = (bf16_t)(w2.y >> 16);
;                         }
.LBB0_204:
	s_and_b64 vcc, exec, s[8:9]
	s_mov_b64 s[0:1], 0x1feb4000
	s_cbranch_vccnz .LBB0_206
	s_or_b32 s0, s11, s39
	s_mul_i32 s0, s0, 18
	s_add_i32 s0, s10, s0
	s_ashr_i32 s1, s0, 31
	s_lshl_b64 s[0:1], s[0:1], 15
	s_add_u32 s0, s17, s0
	s_addc_u32 s1, s19, s1
	v_mov_b32_e32 v123, v1
	v_lshl_add_u64 v[46:47], s[0:1], 0, v[122:123]
	v_lshl_add_u64 v[46:47], v[142:143], 1, v[46:47]
	s_nop 1
	v_mov_b32_dpp v168, v44 quad_perm:[1,0,3,2] row_mask:0xf bank_mask:0xf
	v_mov_b32_dpp v169, v45 quad_perm:[1,0,3,2] row_mask:0xf bank_mask:0xf
	v_lshl_add_u64 v[172:173], v[46:47], 0, v[166:167]
	v_perm_b32 v168, v168, v44, v165
	v_perm_b32 v169, v169, v45, v165
	s_nop 1
	v_mov_b32_dpp v170, v168 quad_perm:[2,3,0,1] row_mask:0xf bank_mask:0xf
	v_mov_b32_dpp v171, v169 quad_perm:[2,3,0,1] row_mask:0xf bank_mask:0xf
	s_nop 1
	v_cndmask_b32_e64 v168, v168, v171, s[98:99]
	v_cndmask_b32_e64 v169, v170, v169, s[98:99]
	global_store_dwordx2 v[172:173], v[168:169], off offset:32
	v_add_co_u32_e32 v44, vcc, 0x4000, v46
	s_mov_b64 s[0:1], 0x20eb4000
	s_nop 0
	v_addc_co_u32_e32 v45, vcc, 0, v47, vcc
	s_nop 1
	v_mov_b32_dpp v168, v42 quad_perm:[1,0,3,2] row_mask:0xf bank_mask:0xf
	v_mov_b32_dpp v169, v43 quad_perm:[1,0,3,2] row_mask:0xf bank_mask:0xf
	v_lshl_add_u64 v[172:173], v[44:45], 0, v[166:167]
	v_perm_b32 v168, v168, v42, v165
	v_perm_b32 v169, v169, v43, v165
	s_nop 1
	v_mov_b32_dpp v170, v168 quad_perm:[2,3,0,1] row_mask:0xf bank_mask:0xf
	v_mov_b32_dpp v171, v169 quad_perm:[2,3,0,1] row_mask:0xf bank_mask:0xf
	s_nop 1
	v_cndmask_b32_e64 v168, v168, v171, s[98:99]
	v_cndmask_b32_e64 v169, v170, v169, s[98:99]
	global_store_dwordx2 v[172:173], v[168:169], off offset:32

; __device__ __forceinline__ unsigned cvt_pk_bf16(float lo, float hi) { unsigned r; asm("v_cvt_pk_bf16_f32 %0, %1, %2" : "=v"(r) : "v"(lo), "v"(hi)); return r; }
;     __device__ __forceinline__ void operator()(const f32x4 (&acc)[2][2][4][2], const Unit& u, int wr, int wc, int fr, int fq) const {
;     ...
;                     for (int bj = 0; bj < 2; ++bj) {
;                         const int head = 2 * (pn & 3) + bj;
;                         const f32x4 x1 = acc[ai][bj][m][0], x2 = acc[ai][bj][m][1];
;                         f32x4 o1 = x1 * cs - x2 * sn, o2 = x1 * sn + x2 * cs;
;                         if (isk) { o1 = o1 * KSCALE; o2 = o2 * KSCALE; }
;                         u32x2 w1, w2; w1.x = cvt_pk_bf16(o1[0], o1[1]); w1.y = cvt_pk_bf16(o1[2], o1[3]); w2.x = cvt_pk_bf16(o2[0], o2[1]); w2.y = cvt_pk_bf16(o2[2], o2[3]);
;                         if (!ctx) { bf16_t* dp = (isk ? k : q) + (size_t)row * 1024 + head * 128 + d0; *(u32x2*)dp = w1; *(u32x2*)(dp + 64) = w2; }
;                         if (isk) {
;                             bf16_t* tp = kT + ((size_t)((b * 8 + head) * 18 + cc) * 128 + d0) * 128 + tt;
;                             tp[0] = (bf16_t)(w1.x & 0xffffu); tp[128] = (bf16_t)(w1.x >> 16); tp[256] = (bf16_t)(w1.y & 0xffffu); tp[384] = (bf16_t)(w1.y >> 16);
;                             tp += 64 * 128;
;                             tp[0] = (bf16_t)(w2.x & 0xffffu); tp[128] = (bf16_t)(w2.x >> 16); tp[256] = (bf16_t)(w2.y & 0xffffu); tp[384] = (bf16_t)(w2.y >> 16);
;                         }
.LBB0_211:
	s_or_b32 s0, s40, s39
	s_mul_i32 s0, s0, 18
	s_add_i32 s0, s0, s10
	s_ashr_i32 s1, s0, 31
	s_lshl_b64 s[0:1], s[0:1], 15
	s_add_u32 s0, s17, s0
	s_addc_u32 s1, s19, s1
	v_mov_b32_e32 v123, v1
	v_lshl_add_u64 v[38:39], s[0:1], 0, v[122:123]
	v_lshl_add_u64 v[38:39], v[142:143], 1, v[38:39]
	s_nop 1
	v_mov_b32_dpp v168, v36 quad_perm:[1,0,3,2] row_mask:0xf bank_mask:0xf
	v_mov_b32_dpp v169, v37 quad_perm:[1,0,3,2] row_mask:0xf bank_mask:0xf
	v_lshl_add_u64 v[172:173], v[38:39], 0, v[166:167]
	v_perm_b32 v168, v168, v36, v165
	v_perm_b32 v169, v169, v37, v165
	s_nop 1
	v_mov_b32_dpp v170, v168 quad_perm:[2,3,0,1] row_mask:0xf bank_mask:0xf
	v_mov_b32_dpp v171, v169 quad_perm:[2,3,0,1] row_mask:0xf bank_mask:0xf
	s_nop 1
	v_cndmask_b32_e64 v168, v168, v171, s[98:99]
	v_cndmask_b32_e64 v169, v170, v169, s[98:99]
	global_store_dwordx2 v[172:173], v[168:169], off offset:32
	v_add_co_u32_e32 v36, vcc, 0x4000, v38
	s_nop 1
	v_addc_co_u32_e32 v37, vcc, 0, v39, vcc
	s_nop 1
	v_mov_b32_dpp v168, v34 quad_perm:[1,0,3,2] row_mask:0xf bank_mask:0xf
	v_mov_b32_dpp v169, v35 quad_perm:[1,0,3,2] row_mask:0xf bank_mask:0xf
	v_lshl_add_u64 v[172:173], v[36:37], 0, v[166:167]
	v_perm_b32 v168, v168, v34, v165
	v_perm_b32 v169, v169, v35, v165
	s_nop 1
	v_mov_b32_dpp v170, v168 quad_perm:[2,3,0,1] row_mask:0xf bank_mask:0xf
	v_mov_b32_dpp v171, v169 quad_perm:[2,3,0,1] row_mask:0xf bank_mask:0xf
	s_nop 1
	v_cndmask_b32_e64 v168, v168, v171, s[98:99]
	v_cndmask_b32_e64 v169, v170, v169, s[98:99]
	global_store_dwordx2 v[172:173], v[168:169], off offset:32
	s_and_b64 vcc, exec, s[4:5]
	v_add_u32_e32 v42, 0xa0, v154
	s_cbranch_vccz .LBB0_209

; __device__ __forceinline__ unsigned cvt_pk_bf16(float lo, float hi) { unsigned r; asm("v_cvt_pk_bf16_f32 %0, %1, %2" : "=v"(r) : "v"(lo), "v"(hi)); return r; }
;     __device__ __forceinline__ void operator()(const f32x4 (&acc)[2][2][4][2], const Unit& u, int wr, int wc, int fr, int fq) const {
;     ...
;                     for (int bj = 0; bj < 2; ++bj) {
;                         const int head = 2 * (pn & 3) + bj;
;                         const f32x4 x1 = acc[ai][bj][m][0], x2 = acc[ai][bj][m][1];
;                         f32x4 o1 = x1 * cs - x2 * sn, o2 = x1 * sn + x2 * cs;
;                         if (isk) { o1 = o1 * KSCALE; o2 = o2 * KSCALE; }
;                         u32x2 w1, w2; w1.x = cvt_pk_bf16(o1[0], o1[1]); w1.y = cvt_pk_bf16(o1[2], o1[3]); w2.x = cvt_pk_bf16(o2[0], o2[1]); w2.y = cvt_pk_bf16(o2[2], o2[3]);
;                         if (!ctx) { bf16_t* dp = (isk ? k : q) + (size_t)row * 1024 + head * 128 + d0; *(u32x2*)dp = w1; *(u32x2*)(dp + 64) = w2; }
;                         if (isk) {
;                             bf16_t* tp = kT + ((size_t)((b * 8 + head) * 18 + cc) * 128 + d0) * 128 + tt;
;                             tp[0] = (bf16_t)(w1.x & 0xffffu); tp[128] = (bf16_t)(w1.x >> 16); tp[256] = (bf16_t)(w1.y & 0xffffu); tp[384] = (bf16_t)(w1.y >> 16);
;                             tp += 64 * 128;
;                             tp[0] = (bf16_t)(w2.x & 0xffffu); tp[128] = (bf16_t)(w2.x >> 16); tp[256] = (bf16_t)(w2.y & 0xffffu); tp[384] = (bf16_t)(w2.y >> 16);
;                         }
.LBB0_215:
	s_and_b64 vcc, exec, s[8:9]
	s_mov_b64 s[0:1], 0x1feb4000
	s_cbranch_vccnz .LBB0_217
	s_or_b32 s0, s11, s39
	s_mul_i32 s0, s0, 18
	s_add_i32 s0, s10, s0
	s_ashr_i32 s1, s0, 31
	s_lshl_b64 s[0:1], s[0:1], 15
	s_add_u32 s0, s17, s0
	s_addc_u32 s1, s19, s1
	v_mov_b32_e32 v123, v1
	v_lshl_add_u64 v[30:31], s[0:1], 0, v[122:123]
	v_lshl_add_u64 v[30:31], v[142:143], 1, v[30:31]
	s_nop 1
	v_mov_b32_dpp v168, v28 quad_perm:[1,0,3,2] row_mask:0xf bank_mask:0xf
	v_mov_b32_dpp v169, v29 quad_perm:[1,0,3,2] row_mask:0xf bank_mask:0xf
	v_lshl_add_u64 v[172:173], v[30:31], 0, v[166:167]
	v_perm_b32 v168, v168, v28, v165
	v_perm_b32 v169, v169, v29, v165
	s_nop 1
	v_mov_b32_dpp v170, v168 quad_perm:[2,3,0,1] row_mask:0xf bank_mask:0xf
	v_mov_b32_dpp v171, v169 quad_perm:[2,3,0,1] row_mask:0xf bank_mask:0xf
	s_nop 1
	v_cndmask_b32_e64 v168, v168, v171, s[98:99]
	v_cndmask_b32_e64 v169, v170, v169, s[98:99]
	global_store_dwordx2 v[172:173], v[168:169], off offset:64
	v_add_co_u32_e32 v28, vcc, 0x4000, v30
	s_mov_b64 s[0:1], 0x20eb4000
	s_nop 0
	v_addc_co_u32_e32 v29, vcc, 0, v31, vcc
	s_nop 1
	v_mov_b32_dpp v168, v26 quad_perm:[1,0,3,2] row_mask:0xf bank_mask:0xf
	v_mov_b32_dpp v169, v27 quad_perm:[1,0,3,2] row_mask:0xf bank_mask:0xf
	v_lshl_add_u64 v[172:173], v[28:29], 0, v[166:167]
	v_perm_b32 v168, v168, v26, v165
	v_perm_b32 v169, v169, v27, v165
	s_nop 1
	v_mov_b32_dpp v170, v168 quad_perm:[2,3,0,1] row_mask:0xf bank_mask:0xf
	v_mov_b32_dpp v171, v169 quad_perm:[2,3,0,1] row_mask:0xf bank_mask:0xf
	s_nop 1
	v_cndmask_b32_e64 v168, v168, v171, s[98:99]
	v_cndmask_b32_e64 v169, v170, v169, s[98:99]
	global_store_dwordx2 v[172:173], v[168:169], off offset:64

; __device__ __forceinline__ unsigned cvt_pk_bf16(float lo, float hi) { unsigned r; asm("v_cvt_pk_bf16_f32 %0, %1, %2" : "=v"(r) : "v"(lo), "v"(hi)); return r; }
;     __device__ __forceinline__ void operator()(const f32x4 (&acc)[2][2][4][2], const Unit& u, int wr, int wc, int fr, int fq) const {
;     ...
;                     for (int bj = 0; bj < 2; ++bj) {
;                         const int head = 2 * (pn & 3) + bj;
;                         const f32x4 x1 = acc[ai][bj][m][0], x2 = acc[ai][bj][m][1];
;                         f32x4 o1 = x1 * cs - x2 * sn, o2 = x1 * sn + x2 * cs;
;                         if (isk) { o1 = o1 * KSCALE; o2 = o2 * KSCALE; }
;                         u32x2 w1, w2; w1.x = cvt_pk_bf16(o1[0], o1[1]); w1.y = cvt_pk_bf16(o1[2], o1[3]); w2.x = cvt_pk_bf16(o2[0], o2[1]); w2.y = cvt_pk_bf16(o2[2], o2[3]);
;                         if (!ctx) { bf16_t* dp = (isk ? k : q) + (size_t)row * 1024 + head * 128 + d0; *(u32x2*)dp = w1; *(u32x2*)(dp + 64) = w2; }
;                         if (isk) {
;                             bf16_t* tp = kT + ((size_t)((b * 8 + head) * 18 + cc) * 128 + d0) * 128 + tt;
;                             tp[0] = (bf16_t)(w1.x & 0xffffu); tp[128] = (bf16_t)(w1.x >> 16); tp[256] = (bf16_t)(w1.y & 0xffffu); tp[384] = (bf16_t)(w1.y >> 16);
;                             tp += 64 * 128;
;                             tp[0] = (bf16_t)(w2.x & 0xffffu); tp[128] = (bf16_t)(w2.x >> 16); tp[256] = (bf16_t)(w2.y & 0xffffu); tp[384] = (bf16_t)(w2.y >> 16);
;                         }
.LBB0_222:
	s_or_b32 s0, s40, s39
	s_mul_i32 s0, s0, 18
	s_add_i32 s0, s0, s10
	s_ashr_i32 s1, s0, 31
	s_lshl_b64 s[0:1], s[0:1], 15
	s_add_u32 s0, s17, s0
	s_addc_u32 s1, s19, s1
	v_mov_b32_e32 v123, v1
	v_lshl_add_u64 v[22:23], s[0:1], 0, v[122:123]
	v_lshl_add_u64 v[22:23], v[142:143], 1, v[22:23]
	s_nop 1
	v_mov_b32_dpp v168, v20 quad_perm:[1,0,3,2] row_mask:0xf bank_mask:0xf
	v_mov_b32_dpp v169, v21 quad_perm:[1,0,3,2] row_mask:0xf bank_mask:0xf
	v_lshl_add_u64 v[172:173], v[22:23], 0, v[166:167]
	v_perm_b32 v168, v168, v20, v165
	v_perm_b32 v169, v169, v21, v165
	s_nop 1
	v_mov_b32_dpp v170, v168 quad_perm:[2,3,0,1] row_mask:0xf bank_mask:0xf
	v_mov_b32_dpp v171, v169 quad_perm:[2,3,0,1] row_mask:0xf bank_mask:0xf
	s_nop 1
	v_cndmask_b32_e64 v168, v168, v171, s[98:99]
	v_cndmask_b32_e64 v169, v170, v169, s[98:99]
	global_store_dwordx2 v[172:173], v[168:169], off offset:64
	v_add_co_u32_e32 v20, vcc, 0x4000, v22
	s_nop 1
	v_addc_co_u32_e32 v21, vcc, 0, v23, vcc
	s_nop 1
	v_mov_b32_dpp v168, v18 quad_perm:[1,0,3,2] row_mask:0xf bank_mask:0xf
	v_mov_b32_dpp v169, v19 quad_perm:[1,0,3,2] row_mask:0xf bank_mask:0xf
	v_lshl_add_u64 v[172:173], v[20:21], 0, v[166:167]
	v_perm_b32 v168, v168, v18, v165
	v_perm_b32 v169, v169, v19, v165
	s_nop 1
	v_mov_b32_dpp v170, v168 quad_perm:[2,3,0,1] row_mask:0xf bank_mask:0xf
	v_mov_b32_dpp v171, v169 quad_perm:[2,3,0,1] row_mask:0xf bank_mask:0xf
	s_nop 1
	v_cndmask_b32_e64 v168, v168, v171, s[98:99]
	v_cndmask_b32_e64 v169, v170, v169, s[98:99]
	global_store_dwordx2 v[172:173], v[168:169], off offset:64
	s_and_b64 vcc, exec, s[4:5]
	v_add_u32_e32 v26, 0xb0, v154
	s_cbranch_vccz .LBB0_220

; __device__ __forceinline__ unsigned cvt_pk_bf16(float lo, float hi) { unsigned r; asm("v_cvt_pk_bf16_f32 %0, %1, %2" : "=v"(r) : "v"(lo), "v"(hi)); return r; }
;     __device__ __forceinline__ void operator()(const f32x4 (&acc)[2][2][4][2], const Unit& u, int wr, int wc, int fr, int fq) const {
;     ...
;                     for (int bj = 0; bj < 2; ++bj) {
;                         const int head = 2 * (pn & 3) + bj;
;                         const f32x4 x1 = acc[ai][bj][m][0], x2 = acc[ai][bj][m][1];
;                         f32x4 o1 = x1 * cs - x2 * sn, o2 = x1 * sn + x2 * cs;
;                         if (isk) { o1 = o1 * KSCALE; o2 = o2 * KSCALE; }
;                         u32x2 w1, w2; w1.x = cvt_pk_bf16(o1[0], o1[1]); w1.y = cvt_pk_bf16(o1[2], o1[3]); w2.x = cvt_pk_bf16(o2[0], o2[1]); w2.y = cvt_pk_bf16(o2[2], o2[3]);
;                         if (!ctx) { bf16_t* dp = (isk ? k : q) + (size_t)row * 1024 + head * 128 + d0; *(u32x2*)dp = w1; *(u32x2*)(dp + 64) = w2; }
;                         if (isk) {
;                             bf16_t* tp = kT + ((size_t)((b * 8 + head) * 18 + cc) * 128 + d0) * 128 + tt;
;                             tp[0] = (bf16_t)(w1.x & 0xffffu); tp[128] = (bf16_t)(w1.x >> 16); tp[256] = (bf16_t)(w1.y & 0xffffu); tp[384] = (bf16_t)(w1.y >> 16);
;                             tp += 64 * 128;
;                             tp[0] = (bf16_t)(w2.x & 0xffffu); tp[128] = (bf16_t)(w2.x >> 16); tp[256] = (bf16_t)(w2.y & 0xffffu); tp[384] = (bf16_t)(w2.y >> 16);
;                         }
.LBB0_226:
	s_and_b64 vcc, exec, s[8:9]
	s_mov_b64 s[0:1], 0x1feb4000
	s_cbranch_vccnz .LBB0_228
	s_or_b32 s0, s11, s39
	s_mul_i32 s0, s0, 18
	s_add_i32 s0, s10, s0
	s_ashr_i32 s1, s0, 31
	s_lshl_b64 s[0:1], s[0:1], 15
	s_add_u32 s0, s17, s0
	s_addc_u32 s1, s19, s1
	v_mov_b32_e32 v123, v1
	v_lshl_add_u64 v[14:15], s[0:1], 0, v[122:123]
	v_lshl_add_u64 v[14:15], v[142:143], 1, v[14:15]
	s_nop 1
	v_mov_b32_dpp v168, v12 quad_perm:[1,0,3,2] row_mask:0xf bank_mask:0xf
	v_mov_b32_dpp v169, v13 quad_perm:[1,0,3,2] row_mask:0xf bank_mask:0xf
	v_lshl_add_u64 v[172:173], v[14:15], 0, v[166:167]
	v_perm_b32 v168, v168, v12, v165
	v_perm_b32 v169, v169, v13, v165
	s_nop 1
	v_mov_b32_dpp v170, v168 quad_perm:[2,3,0,1] row_mask:0xf bank_mask:0xf
	v_mov_b32_dpp v171, v169 quad_perm:[2,3,0,1] row_mask:0xf bank_mask:0xf
	s_nop 1
	v_cndmask_b32_e64 v168, v168, v171, s[98:99]
	v_cndmask_b32_e64 v169, v170, v169, s[98:99]
	global_store_dwordx2 v[172:173], v[168:169], off offset:96
	v_add_co_u32_e32 v12, vcc, 0x4000, v14
	s_mov_b64 s[0:1], 0x20eb4000
	s_nop 0
	v_addc_co_u32_e32 v13, vcc, 0, v15, vcc
	s_nop 1
	v_mov_b32_dpp v168, v10 quad_perm:[1,0,3,2] row_mask:0xf bank_mask:0xf
	v_mov_b32_dpp v169, v11 quad_perm:[1,0,3,2] row_mask:0xf bank_mask:0xf
	v_lshl_add_u64 v[172:173], v[12:13], 0, v[166:167]
	v_perm_b32 v168, v168, v10, v165
	v_perm_b32 v169, v169, v11, v165
	s_nop 1
	v_mov_b32_dpp v170, v168 quad_perm:[2,3,0,1] row_mask:0xf bank_mask:0xf
	v_mov_b32_dpp v171, v169 quad_perm:[2,3,0,1] row_mask:0xf bank_mask:0xf
	s_nop 1
	v_cndmask_b32_e64 v168, v168, v171, s[98:99]
	v_cndmask_b32_e64 v169, v170, v169, s[98:99]
	global_store_dwordx2 v[172:173], v[168:169], off offset:96

; __device__ __forceinline__ unsigned cvt_pk_bf16(float lo, float hi) { unsigned r; asm("v_cvt_pk_bf16_f32 %0, %1, %2" : "=v"(r) : "v"(lo), "v"(hi)); return r; }
;     __device__ __forceinline__ void operator()(const f32x4 (&acc)[2][2][4][2], const Unit& u, int wr, int wc, int fr, int fq) const {
;     ...
;                     for (int bj = 0; bj < 2; ++bj) {
;                         const int head = 2 * (pn & 3) + bj;
;                         const f32x4 x1 = acc[ai][bj][m][0], x2 = acc[ai][bj][m][1];
;                         f32x4 o1 = x1 * cs - x2 * sn, o2 = x1 * sn + x2 * cs;
;                         if (isk) { o1 = o1 * KSCALE; o2 = o2 * KSCALE; }
;                         u32x2 w1, w2; w1.x = cvt_pk_bf16(o1[0], o1[1]); w1.y = cvt_pk_bf16(o1[2], o1[3]); w2.x = cvt_pk_bf16(o2[0], o2[1]); w2.y = cvt_pk_bf16(o2[2], o2[3]);
;                         if (!ctx) { bf16_t* dp = (isk ? k : q) + (size_t)row * 1024 + head * 128 + d0; *(u32x2*)dp = w1; *(u32x2*)(dp + 64) = w2; }
;                         if (isk) {
;                             bf16_t* tp = kT + ((size_t)((b * 8 + head) * 18 + cc) * 128 + d0) * 128 + tt;
;                             tp[0] = (bf16_t)(w1.x & 0xffffu); tp[128] = (bf16_t)(w1.x >> 16); tp[256] = (bf16_t)(w1.y & 0xffffu); tp[384] = (bf16_t)(w1.y >> 16);
;                             tp += 64 * 128;
;                             tp[0] = (bf16_t)(w2.x & 0xffffu); tp[128] = (bf16_t)(w2.x >> 16); tp[256] = (bf16_t)(w2.y & 0xffffu); tp[384] = (bf16_t)(w2.y >> 16);
;                         }
.LBB0_230:
	s_and_b64 vcc, exec, s[8:9]
	s_cbranch_vccnz .LBB0_128
	s_or_b32 s0, s40, s39
	s_mul_i32 s0, s0, 18
	s_add_i32 s0, s0, s10
	s_ashr_i32 s1, s0, 31
	s_lshl_b64 s[0:1], s[0:1], 15
	s_add_u32 s0, s17, s0
	s_addc_u32 s1, s19, s1
	v_mov_b32_e32 v123, v1
	v_lshl_add_u64 v[6:7], s[0:1], 0, v[122:123]
	v_lshl_add_u64 v[6:7], v[142:143], 1, v[6:7]
	s_nop 1
	v_mov_b32_dpp v168, v4 quad_perm:[1,0,3,2] row_mask:0xf bank_mask:0xf
	v_mov_b32_dpp v169, v5 quad_perm:[1,0,3,2] row_mask:0xf bank_mask:0xf
	v_lshl_add_u64 v[172:173], v[6:7], 0, v[166:167]
	v_perm_b32 v168, v168, v4, v165
	v_perm_b32 v169, v169, v5, v165
	s_nop 1
	v_mov_b32_dpp v170, v168 quad_perm:[2,3,0,1] row_mask:0xf bank_mask:0xf
	v_mov_b32_dpp v171, v169 quad_perm:[2,3,0,1] row_mask:0xf bank_mask:0xf
	s_nop 1
	v_cndmask_b32_e64 v168, v168, v171, s[98:99]
	v_cndmask_b32_e64 v169, v170, v169, s[98:99]
	global_store_dwordx2 v[172:173], v[168:169], off offset:96
	v_add_co_u32_e32 v4, vcc, 0x4000, v6
	s_nop 1
	v_addc_co_u32_e32 v5, vcc, 0, v7, vcc
	s_nop 1
	v_mov_b32_dpp v168, v2 quad_perm:[1,0,3,2] row_mask:0xf bank_mask:0xf
	v_mov_b32_dpp v169, v3 quad_perm:[1,0,3,2] row_mask:0xf bank_mask:0xf
	v_lshl_add_u64 v[172:173], v[4:5], 0, v[166:167]
	v_perm_b32 v168, v168, v2, v165
	v_perm_b32 v169, v169, v3, v165
	s_nop 1
	v_mov_b32_dpp v170, v168 quad_perm:[2,3,0,1] row_mask:0xf bank_mask:0xf
	v_mov_b32_dpp v171, v169 quad_perm:[2,3,0,1] row_mask:0xf bank_mask:0xf
	s_nop 1
	v_cndmask_b32_e64 v168, v168, v171, s[98:99]
	v_cndmask_b32_e64 v169, v170, v169, s[98:99]
	global_store_dwordx2 v[172:173], v[168:169], off offset:96
	s_branch .LBB0_128

;     __device__ __forceinline__ void operator()(const f32x4 (&acc)[2][2][4][2], const Unit& u, int wr, int wc, int fr, int fq) const {
;     ...
;         const int r = u.pm >> 3;
;         const float* src = src_lat;
;         f32x4 gv[2][2];
; #pragma unroll
;         for (int bj = 0; bj < 2; ++bj)
; #pragma unroll
;             for (int n = 0; n < 2; ++n) {
;                 f32x4 g = *(const f32x4*)(gate + (size_t)r * NMODC + col0 + bj * HALF + n * 16) * coef;
;                 if (cscale) g = g * *(const f32x4*)(cscale + col0 + bj * HALF + n * 16);
;                 gv[bj][n] = g;
;             }
; #pragma unroll
;         for (int ai = 0; ai < 2; ++ai)
; #pragma unroll
;             for (int m = 0; m < 4; ++m) {
;                 const size_t ro = (size_t)(row0 + ai * HALF + m * 16) * DM + col0;
; #pragma unroll
;                 for (int bj = 0; bj < 2; ++bj)
; #pragma unroll
;                     for (int n = 0; n < 2; ++n) {
;                         const f32x4 s = *(const f32x4*)(src + ro + bj * HALF + n * 16);
;                         *(f32x4*)(dst + ro + bj * HALF + n * 16) = s + acc[ai][bj][m][n] * gv[bj][n];
;                     }
.LBB0_265:
	v_or_b32_e32 v140, s91, v184
	v_lshl_add_u32 v142, s17, 8, v178
	v_lshl_or_b32 v140, s16, 8, v140
	s_mov_b64 s[44:45], -1
	s_cmp_lt_i32 s17, 32
	v_ashrrev_i32_e32 v141, 31, v140
	v_ashrrev_i32_e32 v143, 31, v142
	s_mov_b32 s96, s65
	s_mov_b32 s97, s52
	s_cbranch_scc0 .LBB0_267
	s_ashr_i32 s1, s17, 3
	s_mul_hi_i32 s21, s1, 0x12000
	s_mul_i32 s1, s1, 0x12000
	s_add_u32 s28, s28, s1
	s_addc_u32 s29, s29, s21
	v_lshl_add_u64 v[160:161], v[140:141], 2, s[28:29]
	global_load_dwordx4 v[144:147], v[160:161], off
	global_load_dwordx4 v[188:191], v[160:161], off offset:576
	s_mov_b64 s[44:45], 0
	s_waitcnt vmcnt(0)
	v_pk_mul_f32 v[156:157], v[146:147], s[0:1] op_sel_hi:[1,0]
	v_pk_mul_f32 v[158:159], v[144:145], s[0:1] op_sel_hi:[1,0]
	global_load_dwordx4 v[144:147], v[160:161], off offset:64
	s_waitcnt vmcnt(0)
	v_pk_mul_f32 v[152:153], s[0:1], v[146:147] op_sel_hi:[0,1]
	v_pk_mul_f32 v[154:155], s[0:1], v[144:145] op_sel_hi:[0,1]
	global_load_dwordx4 v[144:147], v[160:161], off offset:512
	v_lshlrev_b64 v[160:161], 11, v[142:143]
	v_lshl_add_u64 v[160:161], v[160:161], 0, v[140:141]
	v_lshlrev_b64 v[160:161], 2, v[160:161]
	s_waitcnt lgkmcnt(0)
	v_lshl_add_u64 v[192:193], s[26:27], 0, v[160:161]
	v_lshl_add_u64 v[194:195], s[38:39], 0, v[160:161]
	s_waitcnt vmcnt(0)
	v_pk_mul_f32 v[148:149], s[0:1], v[146:147] op_sel_hi:[0,1]
	v_pk_mul_f32 v[150:151], s[0:1], v[144:145] op_sel_hi:[0,1]
	v_pk_mul_f32 v[144:145], s[0:1], v[190:191] op_sel_hi:[0,1]
	v_pk_mul_f32 v[146:147], s[0:1], v[188:189] op_sel_hi:[0,1]
	v_add_u32_e32 v224, 0x20000, v160
	v_add_u32_e32 v225, 0x40000, v160
	v_add_u32_e32 v226, 0x60000, v160
	v_add_u32_e32 v227, 0x100000, v160
	v_add_u32_e32 v228, 0x120000, v160
	v_add_u32_e32 v229, 0x140000, v160
	v_add_u32_e32 v230, 0x160000, v160
	global_load_dwordx4 v[188:191], v160, s[26:27]
	global_load_dwordx4 v[192:195], v160, s[26:27] offset:64
	global_load_dwordx4 v[196:199], v160, s[26:27] offset:512
	global_load_dwordx4 v[200:203], v160, s[26:27] offset:576
	global_load_dwordx4 v[236:239], v224, s[26:27]
	global_load_dwordx4 v[240:243], v224, s[26:27] offset:64
	global_load_dwordx4 v[232:235], v224, s[26:27] offset:512
	global_load_dwordx4 v[248:251], v224, s[26:27] offset:576
	s_waitcnt vmcnt(4)
	v_pk_fma_f32 v[190:191], v[128:129], v[156:157], v[190:191]
	v_pk_fma_f32 v[188:189], v[126:127], v[158:159], v[188:189]
	v_pk_fma_f32 v[194:195], v[124:125], v[152:153], v[194:195]
	v_pk_fma_f32 v[192:193], v[122:123], v[154:155], v[192:193]
	v_pk_fma_f32 v[198:199], v[88:89], v[148:149], v[198:199]
	v_pk_fma_f32 v[196:197], v[86:87], v[150:151], v[196:197]
	v_pk_fma_f32 v[202:203], v[44:45], v[144:145], v[202:203]
	v_pk_fma_f32 v[200:201], v[42:43], v[146:147], v[200:201]
	global_store_dwordx4 v160, v[188:191], s[38:39]
	global_store_dwordx4 v160, v[192:195], s[38:39] offset:64
	global_store_dwordx4 v160, v[196:199], s[38:39] offset:512
	global_store_dwordx4 v160, v[200:203], s[38:39] offset:576
	global_load_dwordx4 v[188:191], v225, s[26:27]
	global_load_dwordx4 v[192:195], v225, s[26:27] offset:64
	global_load_dwordx4 v[196:199], v225, s[26:27] offset:512
	global_load_dwordx4 v[200:203], v225, s[26:27] offset:576
	s_waitcnt vmcnt(8)
	v_pk_fma_f32 v[238:239], v[120:121], v[156:157], v[238:239]
	v_pk_fma_f32 v[236:237], v[118:119], v[158:159], v[236:237]
	v_pk_fma_f32 v[242:243], v[116:117], v[152:153], v[242:243]
	v_pk_fma_f32 v[240:241], v[114:115], v[154:155], v[240:241]
	v_pk_fma_f32 v[234:235], v[104:105], v[148:149], v[234:235]
	v_pk_fma_f32 v[232:233], v[102:103], v[150:151], v[232:233]
	v_pk_fma_f32 v[250:251], v[64:65], v[144:145], v[250:251]
	v_pk_fma_f32 v[248:249], v[62:63], v[146:147], v[248:249]
	global_store_dwordx4 v224, v[236:239], s[38:39]
	global_store_dwordx4 v224, v[240:243], s[38:39] offset:64
	global_store_dwordx4 v224, v[232:235], s[38:39] offset:512
	global_store_dwordx4 v224, v[248:251], s[38:39] offset:576
	global_load_dwordx4 v[236:239], v226, s[26:27]
	global_load_dwordx4 v[240:243], v226, s[26:27] offset:64
	global_load_dwordx4 v[232:235], v226, s[26:27] offset:512
	global_load_dwordx4 v[248:251], v226, s[26:27] offset:576
	s_waitcnt vmcnt(8)
	v_pk_fma_f32 v[190:191], v[112:113], v[156:157], v[190:191]
	v_pk_fma_f32 v[188:189], v[110:111], v[158:159], v[188:189]
	v_pk_fma_f32 v[194:195], v[108:109], v[152:153], v[194:195]
	v_pk_fma_f32 v[192:193], v[106:107], v[154:155], v[192:193]
	v_pk_fma_f32 v[198:199], v[100:101], v[148:149], v[198:199]
	v_pk_fma_f32 v[196:197], v[98:99], v[150:151], v[196:197]
	v_pk_fma_f32 v[202:203], v[76:77], v[144:145], v[202:203]
	v_pk_fma_f32 v[200:201], v[74:75], v[146:147], v[200:201]
	global_store_dwordx4 v225, v[188:191], s[38:39]
	global_store_dwordx4 v225, v[192:195], s[38:39] offset:64
	global_store_dwordx4 v225, v[196:199], s[38:39] offset:512
	global_store_dwordx4 v225, v[200:203], s[38:39] offset:576
	global_load_dwordx4 v[188:191], v227, s[26:27]
	global_load_dwordx4 v[192:195], v227, s[26:27] offset:64
	global_load_dwordx4 v[196:199], v227, s[26:27] offset:512
	global_load_dwordx4 v[200:203], v227, s[26:27] offset:576
	s_waitcnt vmcnt(8)
;     __device__ __forceinline__ void operator()(const f32x4 (&acc)[2][2][4][2], const Unit& u, int wr, int wc, int fr, int fq) const {
;     ...
;         const int r = u.pm >> 3;
;         const float* src = src_lat;
;         f32x4 gv[2][2];
; #pragma unroll
;         for (int bj = 0; bj < 2; ++bj)
; #pragma unroll
;             for (int n = 0; n < 2; ++n) {
;                 f32x4 g = *(const f32x4*)(gate + (size_t)r * NMODC + col0 + bj * HALF + n * 16) * coef;
;                 if (cscale) g = g * *(const f32x4*)(cscale + col0 + bj * HALF + n * 16);
;                 gv[bj][n] = g;
;             }
; #pragma unroll
;         for (int ai = 0; ai < 2; ++ai)
; #pragma unroll
;             for (int m = 0; m < 4; ++m) {
;                 const size_t ro = (size_t)(row0 + ai * HALF + m * 16) * DM + col0;
; #pragma unroll
;                 for (int bj = 0; bj < 2; ++bj)
; #pragma unroll
;                     for (int n = 0; n < 2; ++n) {
;                         const f32x4 s = *(const f32x4*)(src + ro + bj * HALF + n * 16);
;                         *(f32x4*)(dst + ro + bj * HALF + n * 16) = s + acc[ai][bj][m][n] * gv[bj][n];
;                     }
	v_pk_fma_f32 v[238:239], v[96:97], v[156:157], v[238:239]
	v_pk_fma_f32 v[236:237], v[94:95], v[158:159], v[236:237]
	v_pk_fma_f32 v[242:243], v[92:93], v[152:153], v[242:243]
	v_pk_fma_f32 v[240:241], v[90:91], v[154:155], v[240:241]
	v_pk_fma_f32 v[234:235], v[84:85], v[148:149], v[234:235]
	v_pk_fma_f32 v[232:233], v[82:83], v[150:151], v[232:233]
	v_pk_fma_f32 v[250:251], v[80:81], v[144:145], v[250:251]
	v_pk_fma_f32 v[248:249], v[78:79], v[146:147], v[248:249]
	global_store_dwordx4 v226, v[236:239], s[38:39]
	global_store_dwordx4 v226, v[240:243], s[38:39] offset:64
	global_store_dwordx4 v226, v[232:235], s[38:39] offset:512
	global_store_dwordx4 v226, v[248:251], s[38:39] offset:576
	global_load_dwordx4 v[236:239], v228, s[26:27]
	global_load_dwordx4 v[240:243], v228, s[26:27] offset:64
	global_load_dwordx4 v[232:235], v228, s[26:27] offset:512
	global_load_dwordx4 v[248:251], v228, s[26:27] offset:576
	s_waitcnt vmcnt(8)
	v_pk_fma_f32 v[190:191], v[72:73], v[156:157], v[190:191]
	v_pk_fma_f32 v[188:189], v[70:71], v[158:159], v[188:189]
	v_pk_fma_f32 v[194:195], v[68:69], v[152:153], v[194:195]
	v_pk_fma_f32 v[192:193], v[66:67], v[154:155], v[192:193]
	v_pk_fma_f32 v[198:199], v[60:61], v[148:149], v[198:199]
	v_pk_fma_f32 v[196:197], v[58:59], v[150:151], v[196:197]
	v_pk_fma_f32 v[202:203], v[56:57], v[144:145], v[202:203]
	v_pk_fma_f32 v[200:201], v[54:55], v[146:147], v[200:201]
	global_store_dwordx4 v227, v[188:191], s[38:39]
	global_store_dwordx4 v227, v[192:195], s[38:39] offset:64
	global_store_dwordx4 v227, v[196:199], s[38:39] offset:512
	global_store_dwordx4 v227, v[200:203], s[38:39] offset:576
	global_load_dwordx4 v[188:191], v229, s[26:27]
	global_load_dwordx4 v[192:195], v229, s[26:27] offset:64
	global_load_dwordx4 v[196:199], v229, s[26:27] offset:512
	global_load_dwordx4 v[200:203], v229, s[26:27] offset:576
	s_waitcnt vmcnt(8)
	v_pk_fma_f32 v[238:239], v[52:53], v[156:157], v[238:239]
	v_pk_fma_f32 v[236:237], v[50:51], v[158:159], v[236:237]
	v_pk_fma_f32 v[242:243], v[48:49], v[152:153], v[242:243]
	v_pk_fma_f32 v[240:241], v[46:47], v[154:155], v[240:241]
	v_pk_fma_f32 v[234:235], v[40:41], v[148:149], v[234:235]
	v_pk_fma_f32 v[232:233], v[38:39], v[150:151], v[232:233]
	v_pk_fma_f32 v[250:251], v[36:37], v[144:145], v[250:251]
	v_pk_fma_f32 v[248:249], v[34:35], v[146:147], v[248:249]
	global_store_dwordx4 v228, v[236:239], s[38:39]
	global_store_dwordx4 v228, v[240:243], s[38:39] offset:64
	global_store_dwordx4 v228, v[232:235], s[38:39] offset:512
	global_store_dwordx4 v228, v[248:251], s[38:39] offset:576
	global_load_dwordx4 v[236:239], v230, s[26:27]
	global_load_dwordx4 v[240:243], v230, s[26:27] offset:64
	global_load_dwordx4 v[232:235], v230, s[26:27] offset:512
	global_load_dwordx4 v[248:251], v230, s[26:27] offset:576
	s_waitcnt vmcnt(8)
	v_pk_fma_f32 v[190:191], v[32:33], v[156:157], v[190:191]
	v_pk_fma_f32 v[188:189], v[30:31], v[158:159], v[188:189]
	v_pk_fma_f32 v[194:195], v[28:29], v[152:153], v[194:195]
	v_pk_fma_f32 v[192:193], v[26:27], v[154:155], v[192:193]
	v_pk_fma_f32 v[198:199], v[24:25], v[148:149], v[198:199]
	v_pk_fma_f32 v[196:197], v[22:23], v[150:151], v[196:197]
	v_pk_fma_f32 v[202:203], v[20:21], v[144:145], v[202:203]
	v_pk_fma_f32 v[200:201], v[18:19], v[146:147], v[200:201]
	global_store_dwordx4 v229, v[188:191], s[38:39]
	global_store_dwordx4 v229, v[192:195], s[38:39] offset:64
	global_store_dwordx4 v229, v[196:199], s[38:39] offset:512
	global_store_dwordx4 v229, v[200:203], s[38:39] offset:576
	s_waitcnt vmcnt(4)
	v_pk_fma_f32 v[238:239], v[16:17], v[156:157], v[238:239]
	v_pk_fma_f32 v[236:237], v[14:15], v[158:159], v[236:237]
	v_pk_fma_f32 v[242:243], v[12:13], v[152:153], v[242:243]
	v_pk_fma_f32 v[240:241], v[10:11], v[154:155], v[240:241]
	v_pk_fma_f32 v[234:235], v[8:9], v[148:149], v[234:235]
	v_pk_fma_f32 v[232:233], v[6:7], v[150:151], v[232:233]
	v_pk_fma_f32 v[250:251], v[4:5], v[144:145], v[250:251]
	v_pk_fma_f32 v[248:249], v[2:3], v[146:147], v[248:249]
	global_store_dwordx4 v230, v[236:239], s[38:39]
	global_store_dwordx4 v230, v[240:243], s[38:39] offset:64
	global_store_dwordx4 v230, v[232:235], s[38:39] offset:512
	global_store_dwordx4 v230, v[248:251], s[38:39] offset:576

; #define PG8_STAGE(bufoff, gbase, voff) do { _Pragma("unroll") for (int _i = 0; _i < 2; ++_i) \
;         __builtin_amdgcn_global_load_lds((const unsigned*)((const char*)(gbase) + (voff)[_i]), (LAS unsigned*)(lds + (bufoff) + ldsw + _i * 8192), 16, 0, 0); } while (0)
; #define PG8_LDA(dst, b, h) do { _Pragma("unroll") for (int m = 0; m < 4; ++m) _Pragma("unroll") for (int k = 0; k < 2; ++k) dst[m][k] = *(const LAS bf16x8*)(lds + PG8_SA(b, h) + aoff + m * 2048 + k * 1024); } while (0)
; #define PG8_LDB(dst, b, h) do { _Pragma("unroll") for (int n = 0; n < 2; ++n) _Pragma("unroll") for (int k = 0; k < 2; ++k) dst[n][k] = *(const LAS bf16x8*)(lds + PG8_SB(b, h) + boff + n * 2048 + k * 1024); } while (0)
; #define PG8_WAIT_V(n) asm volatile("s_waitcnt vmcnt(" #n ")" ::: "memory")
; #define PG8_WAIT_L(n) asm volatile("s_waitcnt lgkmcnt(" #n ")" ::: "memory")
; #define PG8_BAR __builtin_amdgcn_s_barrier()
; #define PG8_SCHED __builtin_amdgcn_sched_barrier(0)
; template <class Epi>
; __device__ __forceinline__ void gemm_phase(LAS unsigned char* lds, const Gemm g, const Order& S, KP kp, int code, int wv) {
;     ...
;             PG8_LDB(B0, 0, 0); PG8_SCHED; PG8_LDA(At, 0, 0); PG8_STAGE(PG8_SA(1, 1), a1 + hstepA, voffA);
;             PG8_WAIT_L(8); PG8_BAR; PG8_WAIT_L(0); PG8_MMA(0, 0, At, B0); PG8_BAR; PG8_SCHED;
;             PG8_LDB(B1, 0, 1); PG8_STAGE(PG8_SB(0, 0), b2, voffB);
;             PG8_BAR; PG8_WAIT_L(0); PG8_MMA(0, 1, At, B1); PG8_BAR;
;             PG8_LDA(At, 0, 1); PG8_STAGE(PG8_SA(0, 0), a2, voffA);
;             PG8_BAR; PG8_WAIT_L(0); PG8_MMA(1, 0, At, B0); PG8_BAR; PG8_SCHED;
;             PG8_STAGE(PG8_SB(0, 1), b2 + hstepB, voffB);
;             PG8_WAIT_V(6); PG8_BAR; PG8_MMA(1, 1, At, B1); PG8_BAR;
;             PG8_LDB(B0, 1, 0); PG8_SCHED; PG8_LDA(At, 1, 0); PG8_STAGE(PG8_SA(0, 1), a2 + hstepA, voffA);
;             PG8_WAIT_L(8); PG8_BAR; PG8_WAIT_L(0); PG8_MMA(0, 0, At, B0); PG8_BAR; PG8_SCHED;
;             PG8_LDB(B1, 1, 1); PG8_STAGE(PG8_SB(1, 0), b3, voffB);
;             PG8_BAR; PG8_WAIT_L(0); PG8_MMA(0, 1, At, B1); PG8_BAR;
;             PG8_LDA(At, 1, 1); PG8_STAGE(PG8_SA(1, 0), a3, voffA);
;             PG8_BAR; PG8_WAIT_L(0); PG8_MMA(1, 0, At, B0); PG8_BAR; PG8_SCHED;
;             PG8_STAGE(PG8_SB(1, 1), b3 + hstepB, voffB);
;             PG8_WAIT_V(6); PG8_BAR; PG8_MMA(1, 1, At, B1); PG8_BAR;
.LBB0_550:
	s_add_u32 s18, s16, 0xfff80080
	s_addc_u32 s19, s17, -1
	s_add_i32 s38, 0, 0x10000
	v_add_u32_e32 v156, s38, v145
	ds_read_b128 v[140:143], v156
	ds_read_b128 v[148:151], v156 offset:1024
	ds_read_b128 v[152:155], v156 offset:2048
	ds_read_b128 v[156:159], v156 offset:3072
	s_cmp_eq_u32 s37, 28
	s_cselect_b32 s21, s0, s19
	s_cselect_b32 s20, s1, s18
	s_cselect_b32 s19, s5, s36
	s_cselect_b32 s18, s7, s11
	v_lshl_add_u64 v[160:161], s[16:17], 0, v[136:137]
	s_add_i32 m0, s15, 0xc000
	ds_read_b128 v[184:187], v147
	ds_read_b128 v[188:191], v147 offset:1024
	ds_read_b128 v[192:195], v147 offset:2048
	ds_read_b128 v[196:199], v147 offset:3072
	ds_read_b128 v[200:203], v147 offset:4096
	ds_read_b128 v[204:207], v147 offset:5120
	ds_read_b128 v[208:211], v147 offset:6144
	ds_read_b128 v[224:227], v147 offset:7168
	global_load_lds_dwordx4 v[160:161], off
	v_lshl_add_u64 v[160:161], s[16:17], 0, v[138:139]
	s_add_i32 m0, s15, 0xe000
	s_nop 0
	global_load_lds_dwordx4 v[160:161], off
	s_waitcnt lgkmcnt(8)
	s_barrier
	s_waitcnt lgkmcnt(0)
	s_setprio 1
	s_waitcnt lgkmcnt(0)
	v_mfma_f32_16x16x32_bf16 v[126:129], v[140:143], v[184:187], v[126:129]
	v_mfma_f32_16x16x32_bf16 v[118:121], v[152:155], v[184:187], v[118:121]
	v_mfma_f32_16x16x32_bf16 v[110:113], v[140:143], v[192:195], v[110:113]
	v_mfma_f32_16x16x32_bf16 v[102:105], v[152:155], v[192:195], v[102:105]
	v_mfma_f32_16x16x32_bf16 v[94:97], v[140:143], v[200:203], v[94:97]
	v_mfma_f32_16x16x32_bf16 v[86:89], v[152:155], v[200:203], v[86:89]
	v_mfma_f32_16x16x32_bf16 v[78:81], v[140:143], v[208:211], v[78:81]
	v_mfma_f32_16x16x32_bf16 v[70:73], v[152:155], v[208:211], v[70:73]
	v_mfma_f32_16x16x32_bf16 v[126:129], v[148:151], v[188:191], v[126:129]
	v_mfma_f32_16x16x32_bf16 v[118:121], v[156:159], v[188:191], v[118:121]
	v_mfma_f32_16x16x32_bf16 v[110:113], v[148:151], v[196:199], v[110:113]
	v_mfma_f32_16x16x32_bf16 v[102:105], v[156:159], v[196:199], v[102:105]
	v_mfma_f32_16x16x32_bf16 v[94:97], v[148:151], v[204:207], v[94:97]
	v_mfma_f32_16x16x32_bf16 v[86:89], v[156:159], v[204:207], v[86:89]
	v_mfma_f32_16x16x32_bf16 v[78:81], v[148:151], v[224:227], v[78:81]
	v_mfma_f32_16x16x32_bf16 v[70:73], v[156:159], v[224:227], v[70:73]
	s_setprio 0
	s_barrier
	s_add_i32 s40, 0, 0x14000
	v_add_u32_e32 v160, s40, v145
	s_add_i32 s38, s38, s24
	ds_read_b128 v[228:231], v160
	ds_read_b128 v[232:235], v160 offset:1024
	ds_read_b128 v[236:239], v160 offset:2048
	ds_read_b128 v[240:243], v160 offset:3072
	v_lshl_add_u64 v[160:161], s[18:19], 0, v[0:1]
	s_mov_b32 m0, s38
	v_lshl_add_u64 v[212:213], s[18:19], 0, v[130:131]
	global_load_lds_dwordx4 v[160:161], off
	s_add_i32 m0, s38, 0x2000
	s_nop 0
	global_load_lds_dwordx4 v[212:213], off
	s_barrier
	s_waitcnt lgkmcnt(0)
	s_setprio 1
	s_waitcnt lgkmcnt(0)
	v_mfma_f32_16x16x32_bf16 v[122:125], v[228:231], v[184:187], v[122:125]
	v_mfma_f32_16x16x32_bf16 v[114:117], v[236:239], v[184:187], v[114:117]
	v_mfma_f32_16x16x32_bf16 v[106:109], v[228:231], v[192:195], v[106:109]
	v_mfma_f32_16x16x32_bf16 v[98:101], v[236:239], v[192:195], v[98:101]
	v_mfma_f32_16x16x32_bf16 v[90:93], v[228:231], v[200:203], v[90:93]
	v_mfma_f32_16x16x32_bf16 v[82:85], v[236:239], v[200:203], v[82:85]
	v_mfma_f32_16x16x32_bf16 v[74:77], v[228:231], v[208:211], v[74:77]
	v_mfma_f32_16x16x32_bf16 v[66:69], v[236:239], v[208:211], v[66:69]
	v_mfma_f32_16x16x32_bf16 v[122:125], v[232:235], v[188:191], v[122:125]
	v_mfma_f32_16x16x32_bf16 v[114:117], v[240:243], v[188:191], v[114:117]
	v_mfma_f32_16x16x32_bf16 v[106:109], v[232:235], v[196:199], v[106:109]
	v_mfma_f32_16x16x32_bf16 v[98:101], v[240:243], v[196:199], v[98:101]
	v_mfma_f32_16x16x32_bf16 v[90:93], v[232:235], v[204:207], v[90:93]
	v_mfma_f32_16x16x32_bf16 v[82:85], v[240:243], v[204:207], v[82:85]
	v_mfma_f32_16x16x32_bf16 v[74:77], v[232:235], v[224:227], v[74:77]
	v_mfma_f32_16x16x32_bf16 v[66:69], v[240:243], v[224:227], v[66:69]
	s_setprio 0
	s_mov_b32 m0, s15
	v_lshl_add_u64 v[218:219], s[20:21], 0, v[134:135]
	s_barrier
	ds_read_b128 v[184:187], v147 offset:16384
	ds_read_b128 v[188:191], v147 offset:17408
	ds_read_b128 v[192:195], v147 offset:18432
	ds_read_b128 v[196:199], v147 offset:19456
	ds_read_b128 v[200:203], v147 offset:20480
	ds_read_b128 v[204:207], v147 offset:21504
	ds_read_b128 v[208:211], v147 offset:22528
	ds_read_b128 v[224:227], v147 offset:23552
	global_load_lds_dwordx4 v[218:219], off
	v_lshl_add_u64 v[244:245], s[20:21], 0, v[132:133]
	s_mov_b32 m0, s28
	s_nop 0
	global_load_lds_dwordx4 v[244:245], off
	s_barrier
	s_waitcnt lgkmcnt(0)
	s_setprio 1
	s_waitcnt lgkmcnt(0)
	v_mfma_f32_16x16x32_bf16 v[62:65], v[140:143], v[184:187], v[62:65]
	v_mfma_f32_16x16x32_bf16 v[54:57], v[152:155], v[184:187], v[54:57]
	v_mfma_f32_16x16x32_bf16 v[46:49], v[140:143], v[192:195], v[46:49]
	v_mfma_f32_16x16x32_bf16 v[38:41], v[152:155], v[192:195], v[38:41]
	v_mfma_f32_16x16x32_bf16 v[30:33], v[140:143], v[200:203], v[30:33]
	v_mfma_f32_16x16x32_bf16 v[22:25], v[152:155], v[200:203], v[22:25]
	v_mfma_f32_16x16x32_bf16 v[14:17], v[140:143], v[208:211], v[14:17]
	v_mfma_f32_16x16x32_bf16 v[6:9], v[152:155], v[208:211], v[6:9]
	v_mfma_f32_16x16x32_bf16 v[62:65], v[148:151], v[188:191], v[62:65]
	v_mfma_f32_16x16x32_bf16 v[54:57], v[156:159], v[188:191], v[54:57]
	v_mfma_f32_16x16x32_bf16 v[46:49], v[148:151], v[196:199], v[46:49]
	v_mfma_f32_16x16x32_bf16 v[38:41], v[156:159], v[196:199], v[38:41]
	v_mfma_f32_16x16x32_bf16 v[30:33], v[148:151], v[204:207], v[30:33]
	v_mfma_f32_16x16x32_bf16 v[22:25], v[156:159], v[204:207], v[22:25]
	v_mfma_f32_16x16x32_bf16 v[14:17], v[148:151], v[224:227], v[14:17]
	v_mfma_f32_16x16x32_bf16 v[6:9], v[156:159], v[224:227], v[6:9]
	s_setprio 0
	s_barrier
; #define PG8_STAGE(bufoff, gbase, voff) do { _Pragma("unroll") for (int _i = 0; _i < 2; ++_i) \
;         __builtin_amdgcn_global_load_lds((const unsigned*)((const char*)(gbase) + (voff)[_i]), (LAS unsigned*)(lds + (bufoff) + ldsw + _i * 8192), 16, 0, 0); } while (0)
; #define PG8_LDA(dst, b, h) do { _Pragma("unroll") for (int m = 0; m < 4; ++m) _Pragma("unroll") for (int k = 0; k < 2; ++k) dst[m][k] = *(const LAS bf16x8*)(lds + PG8_SA(b, h) + aoff + m * 2048 + k * 1024); } while (0)
; #define PG8_LDB(dst, b, h) do { _Pragma("unroll") for (int n = 0; n < 2; ++n) _Pragma("unroll") for (int k = 0; k < 2; ++k) dst[n][k] = *(const LAS bf16x8*)(lds + PG8_SB(b, h) + boff + n * 2048 + k * 1024); } while (0)
; #define PG8_WAIT_V(n) asm volatile("s_waitcnt vmcnt(" #n ")" ::: "memory")
; #define PG8_WAIT_L(n) asm volatile("s_waitcnt lgkmcnt(" #n ")" ::: "memory")
; #define PG8_BAR __builtin_amdgcn_s_barrier()
; #define PG8_SCHED __builtin_amdgcn_sched_barrier(0)
; template <class Epi>
; __device__ __forceinline__ void gemm_phase(LAS unsigned char* lds, const Gemm g, const Order& S, KP kp, int code, int wv) {
;     ...
;             PG8_LDB(B0, 0, 0); PG8_SCHED; PG8_LDA(At, 0, 0); PG8_STAGE(PG8_SA(1, 1), a1 + hstepA, voffA);
;             PG8_WAIT_L(8); PG8_BAR; PG8_WAIT_L(0); PG8_MMA(0, 0, At, B0); PG8_BAR; PG8_SCHED;
;             PG8_LDB(B1, 0, 1); PG8_STAGE(PG8_SB(0, 0), b2, voffB);
;             PG8_BAR; PG8_WAIT_L(0); PG8_MMA(0, 1, At, B1); PG8_BAR;
;             PG8_LDA(At, 0, 1); PG8_STAGE(PG8_SA(0, 0), a2, voffA);
;             PG8_BAR; PG8_WAIT_L(0); PG8_MMA(1, 0, At, B0); PG8_BAR; PG8_SCHED;
;             PG8_STAGE(PG8_SB(0, 1), b2 + hstepB, voffB);
;             PG8_WAIT_V(6); PG8_BAR; PG8_MMA(1, 1, At, B1); PG8_BAR;
;             PG8_LDB(B0, 1, 0); PG8_SCHED; PG8_LDA(At, 1, 0); PG8_STAGE(PG8_SA(0, 1), a2 + hstepA, voffA);
;             PG8_WAIT_L(8); PG8_BAR; PG8_WAIT_L(0); PG8_MMA(0, 0, At, B0); PG8_BAR; PG8_SCHED;
;             PG8_LDB(B1, 1, 1); PG8_STAGE(PG8_SB(1, 0), b3, voffB);
;             PG8_BAR; PG8_WAIT_L(0); PG8_MMA(0, 1, At, B1); PG8_BAR;
;             PG8_LDA(At, 1, 1); PG8_STAGE(PG8_SA(1, 0), a3, voffA);
;             PG8_BAR; PG8_WAIT_L(0); PG8_MMA(1, 0, At, B0); PG8_BAR; PG8_SCHED;
;             PG8_STAGE(PG8_SB(1, 1), b3 + hstepB, voffB);
;             PG8_WAIT_V(6); PG8_BAR; PG8_MMA(1, 1, At, B1); PG8_BAR;
	s_add_u32 s38, s18, 0x80000
	s_addc_u32 s39, s19, 0
	s_add_i32 s40, s40, s24
	v_lshl_add_u64 v[140:141], s[38:39], 0, v[0:1]
	s_mov_b32 m0, s40
	s_nop 0
	global_load_lds_dwordx4 v[140:141], off
	v_lshl_add_u64 v[140:141], s[38:39], 0, v[130:131]
	s_add_i32 m0, s40, 0x2000
	s_nop 0
	global_load_lds_dwordx4 v[140:141], off
	s_waitcnt vmcnt(6)
	s_barrier
	s_setprio 1
	v_mfma_f32_16x16x32_bf16 v[58:61], v[228:231], v[184:187], v[58:61]
	v_mfma_f32_16x16x32_bf16 v[50:53], v[236:239], v[184:187], v[50:53]
	v_mfma_f32_16x16x32_bf16 v[42:45], v[228:231], v[192:195], v[42:45]
	v_mfma_f32_16x16x32_bf16 v[34:37], v[236:239], v[192:195], v[34:37]
	v_mfma_f32_16x16x32_bf16 v[26:29], v[228:231], v[200:203], v[26:29]
	v_mfma_f32_16x16x32_bf16 v[18:21], v[236:239], v[200:203], v[18:21]
	v_mfma_f32_16x16x32_bf16 v[10:13], v[228:231], v[208:211], v[10:13]
	v_mfma_f32_16x16x32_bf16 v[2:5], v[236:239], v[208:211], v[2:5]
	v_mfma_f32_16x16x32_bf16 v[58:61], v[232:235], v[188:191], v[58:61]
	v_mfma_f32_16x16x32_bf16 v[50:53], v[240:243], v[188:191], v[50:53]
	v_mfma_f32_16x16x32_bf16 v[42:45], v[232:235], v[196:199], v[42:45]
	v_mfma_f32_16x16x32_bf16 v[34:37], v[240:243], v[196:199], v[34:37]
	v_mfma_f32_16x16x32_bf16 v[26:29], v[232:235], v[204:207], v[26:29]
	v_mfma_f32_16x16x32_bf16 v[18:21], v[240:243], v[204:207], v[18:21]
	v_mfma_f32_16x16x32_bf16 v[10:13], v[232:235], v[224:227], v[10:13]
	v_mfma_f32_16x16x32_bf16 v[2:5], v[240:243], v[224:227], v[2:5]
	s_setprio 0
	s_add_i32 s38, 0, 0x18000
	v_add_u32_e32 v156, s38, v145
	s_barrier
	ds_read_b128 v[140:143], v156
	ds_read_b128 v[148:151], v156 offset:1024
	ds_read_b128 v[152:155], v156 offset:2048
	ds_read_b128 v[156:159], v156 offset:3072
	s_add_u32 s20, s20, 0x80000
	s_addc_u32 s21, s21, 0
	s_mov_b32 m0, s29
	v_lshl_add_u64 v[228:229], s[20:21], 0, v[134:135]
	ds_read_b128 v[184:187], v147 offset:32768
	ds_read_b128 v[188:191], v147 offset:33792
	ds_read_b128 v[192:195], v147 offset:34816
	ds_read_b128 v[196:199], v147 offset:35840
	ds_read_b128 v[200:203], v147 offset:36864
	ds_read_b128 v[204:207], v147 offset:37888
	ds_read_b128 v[208:211], v147 offset:38912
	ds_read_b128 v[224:227], v147 offset:39936
	global_load_lds_dwordx4 v[228:229], off
	v_lshl_add_u64 v[228:229], s[20:21], 0, v[132:133]
	s_mov_b32 m0, s30
	s_nop 0
	global_load_lds_dwordx4 v[228:229], off
	s_waitcnt lgkmcnt(8)
	s_barrier
	s_waitcnt lgkmcnt(0)
	s_setprio 1
	s_waitcnt lgkmcnt(0)
	v_mfma_f32_16x16x32_bf16 v[126:129], v[140:143], v[184:187], v[126:129]
	v_mfma_f32_16x16x32_bf16 v[118:121], v[152:155], v[184:187], v[118:121]
	v_mfma_f32_16x16x32_bf16 v[110:113], v[140:143], v[192:195], v[110:113]
	v_mfma_f32_16x16x32_bf16 v[102:105], v[152:155], v[192:195], v[102:105]
	v_mfma_f32_16x16x32_bf16 v[94:97], v[140:143], v[200:203], v[94:97]
	v_mfma_f32_16x16x32_bf16 v[86:89], v[152:155], v[200:203], v[86:89]
	v_mfma_f32_16x16x32_bf16 v[78:81], v[140:143], v[208:211], v[78:81]
	v_mfma_f32_16x16x32_bf16 v[70:73], v[152:155], v[208:211], v[70:73]
	v_mfma_f32_16x16x32_bf16 v[126:129], v[148:151], v[188:191], v[126:129]
	v_mfma_f32_16x16x32_bf16 v[118:121], v[156:159], v[188:191], v[118:121]
	v_mfma_f32_16x16x32_bf16 v[110:113], v[148:151], v[196:199], v[110:113]
	v_mfma_f32_16x16x32_bf16 v[102:105], v[156:159], v[196:199], v[102:105]
	v_mfma_f32_16x16x32_bf16 v[94:97], v[148:151], v[204:207], v[94:97]
	v_mfma_f32_16x16x32_bf16 v[86:89], v[156:159], v[204:207], v[86:89]
	v_mfma_f32_16x16x32_bf16 v[78:81], v[148:151], v[224:227], v[78:81]
	v_mfma_f32_16x16x32_bf16 v[70:73], v[156:159], v[224:227], v[70:73]
	s_setprio 0
	s_barrier
	s_add_i32 s20, 0, 0x1c000
	s_add_i32 s21, s38, s24
	v_add_u32_e32 v163, s20, v145
	v_lshl_add_u64 v[160:161], v[160:161], 0, s[70:71]
	s_mov_b32 m0, s21
	ds_read_b128 v[228:231], v163
	ds_read_b128 v[232:235], v163 offset:1024
	ds_read_b128 v[236:239], v163 offset:2048
	ds_read_b128 v[240:243], v163 offset:3072
	global_load_lds_dwordx4 v[160:161], off
	v_lshl_add_u64 v[160:161], v[212:213], 0, s[70:71]
	s_add_i32 m0, s21, 0x2000
	s_nop 0
	global_load_lds_dwordx4 v[160:161], off
	s_barrier
	s_waitcnt lgkmcnt(0)
	s_setprio 1
	s_waitcnt lgkmcnt(0)
	v_mfma_f32_16x16x32_bf16 v[122:125], v[228:231], v[184:187], v[122:125]
	v_mfma_f32_16x16x32_bf16 v[114:117], v[236:239], v[184:187], v[114:117]
	v_mfma_f32_16x16x32_bf16 v[106:109], v[228:231], v[192:195], v[106:109]
	v_mfma_f32_16x16x32_bf16 v[98:101], v[236:239], v[192:195], v[98:101]
	v_mfma_f32_16x16x32_bf16 v[90:93], v[228:231], v[200:203], v[90:93]
	v_mfma_f32_16x16x32_bf16 v[82:85], v[236:239], v[200:203], v[82:85]
	v_mfma_f32_16x16x32_bf16 v[74:77], v[228:231], v[208:211], v[74:77]
	v_mfma_f32_16x16x32_bf16 v[66:69], v[236:239], v[208:211], v[66:69]
	v_mfma_f32_16x16x32_bf16 v[122:125], v[232:235], v[188:191], v[122:125]
	v_mfma_f32_16x16x32_bf16 v[114:117], v[240:243], v[188:191], v[114:117]
	v_mfma_f32_16x16x32_bf16 v[106:109], v[232:235], v[196:199], v[106:109]
	v_mfma_f32_16x16x32_bf16 v[98:101], v[240:243], v[196:199], v[98:101]
	v_mfma_f32_16x16x32_bf16 v[90:93], v[232:235], v[204:207], v[90:93]
	v_mfma_f32_16x16x32_bf16 v[82:85], v[240:243], v[204:207], v[82:85]
	v_mfma_f32_16x16x32_bf16 v[74:77], v[232:235], v[224:227], v[74:77]
	v_mfma_f32_16x16x32_bf16 v[66:69], v[240:243], v[224:227], v[66:69]
	s_setprio 0
	s_mov_b32 m0, s31
	v_lshl_add_u64 v[160:161], v[218:219], 0, s[70:71]
	s_barrier
	ds_read_b128 v[184:187], v147 offset:49152
	ds_read_b128 v[188:191], v147 offset:50176
	ds_read_b128 v[192:195], v147 offset:51200
	ds_read_b128 v[196:199], v147 offset:52224
	ds_read_b128 v[200:203], v147 offset:53248
	ds_read_b128 v[204:207], v147 offset:54272
	ds_read_b128 v[208:211], v147 offset:55296
	ds_read_b128 v[224:227], v147 offset:56320
	global_load_lds_dwordx4 v[160:161], off
	v_lshl_add_u64 v[160:161], v[244:245], 0, s[70:71]
	s_mov_b32 m0, s34
	s_nop 0
	global_load_lds_dwordx4 v[160:161], off
	s_barrier
; __device__ __forceinline__ unsigned cvt_pk_bf16(float lo, float hi) { unsigned r; asm("v_cvt_pk_bf16_f32 %0, %1, %2" : "=v"(r) : "v"(lo), "v"(hi)); return r; }
; __device__ __forceinline__ float silu_fast(float x) { return x * __builtin_amdgcn_rcpf(1.0f + __expf(-x)); }
; #define PG8_STAGE(bufoff, gbase, voff) do { _Pragma("unroll") for (int _i = 0; _i < 2; ++_i) \
;         __builtin_amdgcn_global_load_lds((const unsigned*)((const char*)(gbase) + (voff)[_i]), (LAS unsigned*)(lds + (bufoff) + ldsw + _i * 8192), 16, 0, 0); } while (0)
;     __device__ __forceinline__ void operator()(const f32x4 (&acc)[2][2][4][2], const Unit& u, int wr, int wc, int fr, int fq) const {
;         const int row0 = u.pm * BM + wr * 64 + fr, col0 = u.pn * 128 + wc * 32 + 8 * fq;
; #pragma unroll
;         for (int ai = 0; ai < 2; ++ai)
; #pragma unroll
;             for (int m = 0; m < 4; ++m) {
;                 bf16_t* rowp = O + (size_t)(row0 + ai * HALF + m * 16) * DFF + col0;
;                 const f32x4 g0 = acc[ai][0][m][0], g1 = acc[ai][0][m][1], u0 = acc[ai][1][m][0], u1 = acc[ai][1][m][1];
;                 u32x4 w;
;                 w.x = cvt_pk_bf16(silu_fast(g0[0]) * u0[0], silu_fast(g0[1]) * u0[1]);
;                 w.y = cvt_pk_bf16(silu_fast(g0[2]) * u0[2], silu_fast(g0[3]) * u0[3]);
;                 w.z = cvt_pk_bf16(silu_fast(g1[0]) * u1[0], silu_fast(g1[1]) * u1[1]);
;                 w.w = cvt_pk_bf16(silu_fast(g1[2]) * u1[2], silu_fast(g1[3]) * u1[3]);
;                 *(u32x4*)rowp = w;
; template <class Epi>
; __device__ __forceinline__ void gemm_phase(LAS unsigned char* lds, const Gemm g, const Order& S, KP kp, int code, int wv) {
;     ...
;             PG8_WAIT_V(6); PG8_BAR; PG8_MMA(1, 1, At, B1); PG8_BAR;
;             PG8_LDB(B0, 1, 0); PG8_SCHED; PG8_LDA(At, 1, 0); PG8_STAGE(PG8_SA(0, 1), a2 + hstepA, voffA);
;             PG8_WAIT_L(8); PG8_BAR; PG8_WAIT_L(0); PG8_MMA(0, 0, At, B0); PG8_BAR; PG8_SCHED;
;             PG8_LDB(B1, 1, 1); PG8_STAGE(PG8_SB(1, 0), b3, voffB);
;             PG8_BAR; PG8_WAIT_L(0); PG8_MMA(0, 1, At, B1); PG8_BAR;
;             PG8_LDA(At, 1, 1); PG8_STAGE(PG8_SA(1, 0), a3, voffA);
;             PG8_BAR; PG8_WAIT_L(0); PG8_MMA(1, 0, At, B0); PG8_BAR; PG8_SCHED;
;             PG8_STAGE(PG8_SB(1, 1), b3 + hstepB, voffB);
;             PG8_WAIT_V(6); PG8_BAR; PG8_MMA(1, 1, At, B1); PG8_BAR;
	s_waitcnt lgkmcnt(0)
	s_setprio 1
	s_waitcnt lgkmcnt(0)
	v_mfma_f32_16x16x32_bf16 v[62:65], v[140:143], v[184:187], v[62:65]
	v_mfma_f32_16x16x32_bf16 v[54:57], v[152:155], v[184:187], v[54:57]
	v_mfma_f32_16x16x32_bf16 v[46:49], v[140:143], v[192:195], v[46:49]
	v_mfma_f32_16x16x32_bf16 v[38:41], v[152:155], v[192:195], v[38:41]
	v_mfma_f32_16x16x32_bf16 v[30:33], v[140:143], v[200:203], v[30:33]
	v_mfma_f32_16x16x32_bf16 v[22:25], v[152:155], v[200:203], v[22:25]
	v_mfma_f32_16x16x32_bf16 v[14:17], v[140:143], v[208:211], v[14:17]
	v_mfma_f32_16x16x32_bf16 v[6:9], v[152:155], v[208:211], v[6:9]
	v_mfma_f32_16x16x32_bf16 v[62:65], v[148:151], v[188:191], v[62:65]
	v_mfma_f32_16x16x32_bf16 v[54:57], v[156:159], v[188:191], v[54:57]
	v_mfma_f32_16x16x32_bf16 v[46:49], v[148:151], v[196:199], v[46:49]
	v_mfma_f32_16x16x32_bf16 v[38:41], v[156:159], v[196:199], v[38:41]
	v_mfma_f32_16x16x32_bf16 v[30:33], v[148:151], v[204:207], v[30:33]
	v_mfma_f32_16x16x32_bf16 v[22:25], v[156:159], v[204:207], v[22:25]
	v_mfma_f32_16x16x32_bf16 v[14:17], v[148:151], v[224:227], v[14:17]
	v_mfma_f32_16x16x32_bf16 v[6:9], v[156:159], v[224:227], v[6:9]
	s_setprio 0
	s_barrier
	s_add_u32 s18, s18, 0x80080
	s_addc_u32 s19, s19, 0
	s_add_i32 s20, s20, s24
	v_lshl_add_u64 v[140:141], s[18:19], 0, v[0:1]
	s_mov_b32 m0, s20
	s_nop 0
	global_load_lds_dwordx4 v[140:141], off
	v_lshl_add_u64 v[140:141], s[18:19], 0, v[130:131]
	s_add_i32 m0, s20, 0x2000
	s_nop 0
	global_load_lds_dwordx4 v[140:141], off
	s_waitcnt vmcnt(6)
	s_barrier
	s_setprio 1
	v_mfma_f32_16x16x32_bf16 v[58:61], v[228:231], v[184:187], v[58:61]
	v_mfma_f32_16x16x32_bf16 v[50:53], v[236:239], v[184:187], v[50:53]
	v_mfma_f32_16x16x32_bf16 v[42:45], v[228:231], v[192:195], v[42:45]
	v_mfma_f32_16x16x32_bf16 v[34:37], v[236:239], v[192:195], v[34:37]
	v_mfma_f32_16x16x32_bf16 v[26:29], v[228:231], v[200:203], v[26:29]
	v_mfma_f32_16x16x32_bf16 v[18:21], v[236:239], v[200:203], v[18:21]
	v_mfma_f32_16x16x32_bf16 v[10:13], v[228:231], v[208:211], v[10:13]
	v_mfma_f32_16x16x32_bf16 v[2:5], v[236:239], v[208:211], v[2:5]
	v_mfma_f32_16x16x32_bf16 v[58:61], v[232:235], v[188:191], v[58:61]
	v_mfma_f32_16x16x32_bf16 v[50:53], v[240:243], v[188:191], v[50:53]
	v_mfma_f32_16x16x32_bf16 v[42:45], v[232:235], v[196:199], v[42:45]
	v_mfma_f32_16x16x32_bf16 v[34:37], v[240:243], v[196:199], v[34:37]
	v_mfma_f32_16x16x32_bf16 v[26:29], v[232:235], v[204:207], v[26:29]
	v_mfma_f32_16x16x32_bf16 v[18:21], v[240:243], v[204:207], v[18:21]
	v_mfma_f32_16x16x32_bf16 v[10:13], v[232:235], v[224:227], v[10:13]
	v_mfma_f32_16x16x32_bf16 v[2:5], v[240:243], v[224:227], v[2:5]
	s_setprio 0
	s_add_i32 s37, s37, 2
	s_add_u32 s16, s16, 0x100
	s_addc_u32 s17, s17, 0
	s_add_u32 s11, s11, 0x100
	s_addc_u32 s36, s36, 0
	s_cmp_gt_u32 s37, 29
	s_barrier
	s_cbranch_scc0 .LBB0_550
	v_mul_f32_e32 v149, 0xbfb8aa3b, v126
	v_exp_f32_e32 v149, v149
	s_mov_b64 s[0:1], s[78:79]
	s_load_dwordx2 s[0:1], s[0:1], 0xc0
	v_add_f32_e32 v149, 1.0, v149
	v_rcp_f32_e32 v149, v149
	v_lshl_or_b32 v140, s10, 7, v146
	v_ashrrev_i32_e32 v141, 31, v140
	v_lshl_add_u32 v148, s14, 8, v144
	v_mul_f32_e32 v126, v126, v149
	v_mul_f32_e32 v122, v122, v126
	v_mul_f32_e32 v126, 0xbfb8aa3b, v127
	v_exp_f32_e32 v126, v126
	s_waitcnt lgkmcnt(0)
	v_lshl_add_u64 v[140:141], v[140:141], 1, s[0:1]
	s_mov_b64 s[0:1], 0x153b4000
	v_lshl_add_u64 v[140:141], v[140:141], 0, s[0:1]
	v_add_f32_e32 v126, 1.0, v126
	v_rcp_f32_e32 v126, v126
	v_mad_i64_i32 v[142:143], s[0:1], v148, s95, v[140:141]
	s_and_b64 vcc, exec, s[2:3]
	v_mul_f32_e32 v126, v127, v126
	v_mul_f32_e32 v123, v123, v126
	v_cvt_pk_bf16_f32 v122, v122, v123
	v_mul_f32_e32 v123, 0xbfb8aa3b, v128
	v_exp_f32_e32 v123, v123
	s_mov_b32 s10, s4
	s_mov_b32 s14, s6
	s_mov_b64 s[18:19], s[12:13]
	v_add_f32_e32 v123, 1.0, v123
	v_rcp_f32_e32 v123, v123
	s_mov_b64 s[16:17], s[8:9]
	v_mul_f32_e32 v123, v128, v123
	v_mul_f32_e32 v123, v124, v123
	v_mul_f32_e32 v124, 0xbfb8aa3b, v129
	v_exp_f32_e32 v124, v124
	s_nop 0
	v_add_f32_e32 v124, 1.0, v124
	v_rcp_f32_e32 v124, v124
	s_nop 0
	v_mul_f32_e32 v124, v129, v124
	v_mul_f32_e32 v124, v125, v124
	v_cvt_pk_bf16_f32 v123, v123, v124
	v_mul_f32_e32 v124, 0xbfb8aa3b, v118
	v_exp_f32_e32 v124, v124
	s_nop 0
	v_add_f32_e32 v124, 1.0, v124
	v_rcp_f32_e32 v124, v124
	s_nop 0
	v_mul_f32_e32 v118, v118, v124
	v_mul_f32_e32 v114, v114, v118
	v_mul_f32_e32 v118, 0xbfb8aa3b, v119
	v_exp_f32_e32 v118, v118
	s_nop 0
	v_add_f32_e32 v118, 1.0, v118
	v_rcp_f32_e32 v118, v118
	s_nop 0
	v_mul_f32_e32 v118, v119, v118
	v_mul_f32_e32 v115, v115, v118
	v_cvt_pk_bf16_f32 v124, v114, v115
	v_mul_f32_e32 v114, 0xbfb8aa3b, v120
	v_exp_f32_e32 v114, v114
	v_mul_f32_e32 v115, 0xbfb8aa3b, v121
	v_exp_f32_e32 v115, v115
	v_add_f32_e32 v114, 1.0, v114
	v_rcp_f32_e32 v114, v114
	v_add_f32_e32 v115, 1.0, v115
	v_rcp_f32_e32 v115, v115
	v_mul_f32_e32 v114, v120, v114
	v_mul_f32_e32 v114, v116, v114
	v_mul_f32_e32 v116, 0xbfb8aa3b, v110
	v_exp_f32_e32 v116, v116
	v_mul_f32_e32 v115, v121, v115
	v_mul_f32_e32 v115, v117, v115
	v_cvt_pk_bf16_f32 v125, v114, v115
	v_add_f32_e32 v116, 1.0, v116
	v_rcp_f32_e32 v116, v116
	v_or_b32_e32 v114, 16, v148
	v_mad_i64_i32 v[114:115], s[0:1], v114, s95, v[140:141]
	v_mul_f32_e32 v110, v110, v116
	v_mul_f32_e32 v106, v106, v110
	v_mul_f32_e32 v110, 0xbfb8aa3b, v111
	v_exp_f32_e32 v110, v110
	global_store_dwordx4 v[142:143], v[122:125], off
	v_add_f32_e32 v110, 1.0, v110
	v_rcp_f32_e32 v110, v110
	s_nop 0
	v_mul_f32_e32 v110, v111, v110
	v_mul_f32_e32 v107, v107, v110
	v_cvt_pk_bf16_f32 v106, v106, v107
	v_mul_f32_e32 v107, 0xbfb8aa3b, v112
	v_exp_f32_e32 v107, v107
	s_nop 0
; __device__ __forceinline__ unsigned cvt_pk_bf16(float lo, float hi) { unsigned r; asm("v_cvt_pk_bf16_f32 %0, %1, %2" : "=v"(r) : "v"(lo), "v"(hi)); return r; }
; __device__ __forceinline__ float silu_fast(float x) { return x * __builtin_amdgcn_rcpf(1.0f + __expf(-x)); }
;     __device__ __forceinline__ void operator()(const f32x4 (&acc)[2][2][4][2], const Unit& u, int wr, int wc, int fr, int fq) const {
;         const int row0 = u.pm * BM + wr * 64 + fr, col0 = u.pn * 128 + wc * 32 + 8 * fq;
; #pragma unroll
;         for (int ai = 0; ai < 2; ++ai)
; #pragma unroll
;             for (int m = 0; m < 4; ++m) {
;                 bf16_t* rowp = O + (size_t)(row0 + ai * HALF + m * 16) * DFF + col0;
;                 const f32x4 g0 = acc[ai][0][m][0], g1 = acc[ai][0][m][1], u0 = acc[ai][1][m][0], u1 = acc[ai][1][m][1];
;                 u32x4 w;
;                 w.x = cvt_pk_bf16(silu_fast(g0[0]) * u0[0], silu_fast(g0[1]) * u0[1]);
;                 w.y = cvt_pk_bf16(silu_fast(g0[2]) * u0[2], silu_fast(g0[3]) * u0[3]);
;                 w.z = cvt_pk_bf16(silu_fast(g1[0]) * u1[0], silu_fast(g1[1]) * u1[1]);
;                 w.w = cvt_pk_bf16(silu_fast(g1[2]) * u1[2], silu_fast(g1[3]) * u1[3]);
;                 *(u32x4*)rowp = w;
;             }
;     }
	v_add_f32_e32 v107, 1.0, v107
	v_rcp_f32_e32 v107, v107
	s_nop 0
	v_mul_f32_e32 v107, v112, v107
	v_mul_f32_e32 v107, v108, v107
	v_mul_f32_e32 v108, 0xbfb8aa3b, v113
	v_exp_f32_e32 v108, v108
	s_nop 0
	v_add_f32_e32 v108, 1.0, v108
	v_rcp_f32_e32 v108, v108
	s_nop 0
	v_mul_f32_e32 v108, v113, v108
	v_mul_f32_e32 v108, v109, v108
	v_cvt_pk_bf16_f32 v107, v107, v108
	v_mul_f32_e32 v108, 0xbfb8aa3b, v102
	v_exp_f32_e32 v108, v108
	s_nop 0
	v_add_f32_e32 v108, 1.0, v108
	v_rcp_f32_e32 v108, v108
	s_nop 0
	v_mul_f32_e32 v102, v102, v108
	v_mul_f32_e32 v98, v98, v102
	v_mul_f32_e32 v102, 0xbfb8aa3b, v103
	v_exp_f32_e32 v102, v102
	s_nop 0
	v_add_f32_e32 v102, 1.0, v102
	v_rcp_f32_e32 v102, v102
	s_nop 0
	v_mul_f32_e32 v102, v103, v102
	v_mul_f32_e32 v99, v99, v102
	v_cvt_pk_bf16_f32 v108, v98, v99
	v_mul_f32_e32 v98, 0xbfb8aa3b, v104
	v_exp_f32_e32 v98, v98
	v_mul_f32_e32 v99, 0xbfb8aa3b, v105
	v_exp_f32_e32 v99, v99
	v_add_f32_e32 v98, 1.0, v98
	v_rcp_f32_e32 v98, v98
	v_add_f32_e32 v99, 1.0, v99
	v_rcp_f32_e32 v99, v99
	v_mul_f32_e32 v98, v104, v98
	v_mul_f32_e32 v98, v100, v98
	v_mul_f32_e32 v100, 0xbfb8aa3b, v94
	v_exp_f32_e32 v100, v100
	v_mul_f32_e32 v99, v105, v99
	v_mul_f32_e32 v99, v101, v99
	v_cvt_pk_bf16_f32 v109, v98, v99
	v_add_f32_e32 v100, 1.0, v100
	v_rcp_f32_e32 v100, v100
	v_or_b32_e32 v98, 32, v148
	v_mad_i64_i32 v[98:99], s[0:1], v98, s95, v[140:141]
	v_mul_f32_e32 v94, v94, v100
	v_mul_f32_e32 v90, v90, v94
	v_mul_f32_e32 v94, 0xbfb8aa3b, v95
	v_exp_f32_e32 v94, v94
	global_store_dwordx4 v[114:115], v[106:109], off
	v_add_f32_e32 v94, 1.0, v94
	v_rcp_f32_e32 v94, v94
	s_nop 0
	v_mul_f32_e32 v94, v95, v94
	v_mul_f32_e32 v91, v91, v94
	v_cvt_pk_bf16_f32 v90, v90, v91
	v_mul_f32_e32 v91, 0xbfb8aa3b, v96
	v_exp_f32_e32 v91, v91
	s_nop 0
	v_add_f32_e32 v91, 1.0, v91
	v_rcp_f32_e32 v91, v91
	s_nop 0
	v_mul_f32_e32 v91, v96, v91
	v_mul_f32_e32 v91, v92, v91
	v_mul_f32_e32 v92, 0xbfb8aa3b, v97
	v_exp_f32_e32 v92, v92
	s_nop 0
	v_add_f32_e32 v92, 1.0, v92
	v_rcp_f32_e32 v92, v92
	s_nop 0
	v_mul_f32_e32 v92, v97, v92
	v_mul_f32_e32 v92, v93, v92
	v_cvt_pk_bf16_f32 v91, v91, v92
	v_mul_f32_e32 v92, 0xbfb8aa3b, v86
	v_exp_f32_e32 v92, v92
	s_nop 0
	v_add_f32_e32 v92, 1.0, v92
	v_rcp_f32_e32 v92, v92
	s_nop 0
	v_mul_f32_e32 v86, v86, v92
	v_mul_f32_e32 v82, v82, v86
	v_mul_f32_e32 v86, 0xbfb8aa3b, v87
	v_exp_f32_e32 v86, v86
	s_nop 0
	v_add_f32_e32 v86, 1.0, v86
	v_rcp_f32_e32 v86, v86
	s_nop 0
	v_mul_f32_e32 v86, v87, v86
	v_mul_f32_e32 v83, v83, v86
	v_cvt_pk_bf16_f32 v92, v82, v83
	v_mul_f32_e32 v82, 0xbfb8aa3b, v88
	v_exp_f32_e32 v82, v82
	v_mul_f32_e32 v83, 0xbfb8aa3b, v89
	v_exp_f32_e32 v83, v83
	v_add_f32_e32 v82, 1.0, v82
	v_rcp_f32_e32 v82, v82
	v_add_f32_e32 v83, 1.0, v83
	v_rcp_f32_e32 v83, v83
	v_mul_f32_e32 v82, v88, v82
	v_mul_f32_e32 v82, v84, v82
	v_mul_f32_e32 v84, 0xbfb8aa3b, v78
	v_exp_f32_e32 v84, v84
	v_mul_f32_e32 v83, v89, v83
	v_mul_f32_e32 v83, v85, v83
	v_cvt_pk_bf16_f32 v93, v82, v83
	v_add_f32_e32 v84, 1.0, v84
	v_rcp_f32_e32 v84, v84
	v_or_b32_e32 v82, 48, v148
	v_mad_i64_i32 v[82:83], s[0:1], v82, s95, v[140:141]
	v_mul_f32_e32 v78, v78, v84
	v_mul_f32_e32 v74, v74, v78
	v_mul_f32_e32 v78, 0xbfb8aa3b, v79
	v_exp_f32_e32 v78, v78
	global_store_dwordx4 v[98:99], v[90:93], off
	v_add_f32_e32 v78, 1.0, v78
	v_rcp_f32_e32 v78, v78
	s_nop 0
	v_mul_f32_e32 v78, v79, v78
	v_mul_f32_e32 v75, v75, v78
	v_cvt_pk_bf16_f32 v74, v74, v75
	v_mul_f32_e32 v75, 0xbfb8aa3b, v80
	v_exp_f32_e32 v75, v75
	s_nop 0
	v_add_f32_e32 v75, 1.0, v75
	v_rcp_f32_e32 v75, v75
	s_nop 0
	v_mul_f32_e32 v75, v80, v75
	v_mul_f32_e32 v75, v76, v75
	v_mul_f32_e32 v76, 0xbfb8aa3b, v81
	v_exp_f32_e32 v76, v76
	s_nop 0
	v_add_f32_e32 v76, 1.0, v76
	v_rcp_f32_e32 v76, v76
	s_nop 0
	v_mul_f32_e32 v76, v81, v76
	v_mul_f32_e32 v76, v77, v76
	v_cvt_pk_bf16_f32 v75, v75, v76
	v_mul_f32_e32 v76, 0xbfb8aa3b, v70
	v_exp_f32_e32 v76, v76
	s_nop 0
	v_add_f32_e32 v76, 1.0, v76
	v_rcp_f32_e32 v76, v76
	s_nop 0
	v_mul_f32_e32 v70, v70, v76
	v_mul_f32_e32 v66, v66, v70
	v_mul_f32_e32 v70, 0xbfb8aa3b, v71
	v_exp_f32_e32 v70, v70
	s_nop 0
	v_add_f32_e32 v70, 1.0, v70
	v_rcp_f32_e32 v70, v70
	s_nop 0
	v_mul_f32_e32 v70, v71, v70
	v_mul_f32_e32 v67, v67, v70
	v_cvt_pk_bf16_f32 v76, v66, v67
	v_mul_f32_e32 v66, 0xbfb8aa3b, v72
	v_exp_f32_e32 v66, v66
	v_mul_f32_e32 v67, 0xbfb8aa3b, v73
	v_exp_f32_e32 v67, v67
	v_add_f32_e32 v66, 1.0, v66
	v_rcp_f32_e32 v66, v66
	v_add_f32_e32 v67, 1.0, v67
	v_rcp_f32_e32 v67, v67
	v_mul_f32_e32 v66, v72, v66
	v_mul_f32_e32 v66, v68, v66
	v_mul_f32_e32 v68, 0xbfb8aa3b, v62
	v_exp_f32_e32 v68, v68
	v_mul_f32_e32 v67, v73, v67
	v_mul_f32_e32 v67, v69, v67
	v_cvt_pk_bf16_f32 v77, v66, v67
	v_add_f32_e32 v68, 1.0, v68
	v_rcp_f32_e32 v68, v68
	v_add_u32_e32 v66, 0x80, v148
	v_mad_i64_i32 v[66:67], s[0:1], v66, s95, v[140:141]
	v_mul_f32_e32 v62, v62, v68
	v_mul_f32_e32 v58, v58, v62
	v_mul_f32_e32 v62, 0xbfb8aa3b, v63
	v_exp_f32_e32 v62, v62
	global_store_dwordx4 v[82:83], v[74:77], off
	v_add_f32_e32 v62, 1.0, v62
	v_rcp_f32_e32 v62, v62
	s_nop 0
	v_mul_f32_e32 v62, v63, v62
	v_mul_f32_e32 v59, v59, v62
	v_cvt_pk_bf16_f32 v58, v58, v59
	v_mul_f32_e32 v59, 0xbfb8aa3b, v64
	v_exp_f32_e32 v59, v59
	s_nop 0
	v_add_f32_e32 v59, 1.0, v59
	v_rcp_f32_e32 v59, v59
	s_nop 0
	v_mul_f32_e32 v59, v64, v59
	v_mul_f32_e32 v59, v60, v59
	v_mul_f32_e32 v60, 0xbfb8aa3b, v65
	v_exp_f32_e32 v60, v60
	s_nop 0
	v_add_f32_e32 v60, 1.0, v60
	v_rcp_f32_e32 v60, v60
	s_nop 0
	v_mul_f32_e32 v60, v65, v60
	v_mul_f32_e32 v60, v61, v60
	v_cvt_pk_bf16_f32 v59, v59, v60
	v_mul_f32_e32 v60, 0xbfb8aa3b, v54
	v_exp_f32_e32 v60, v60
	s_nop 0
	v_add_f32_e32 v60, 1.0, v60
; __device__ __forceinline__ unsigned cvt_pk_bf16(float lo, float hi) { unsigned r; asm("v_cvt_pk_bf16_f32 %0, %1, %2" : "=v"(r) : "v"(lo), "v"(hi)); return r; }
; __device__ __forceinline__ float silu_fast(float x) { return x * __builtin_amdgcn_rcpf(1.0f + __expf(-x)); }
; #define PG8_WAIT_V(n) asm volatile("s_waitcnt vmcnt(" #n ")" ::: "memory")
; #define PG8_BAR __builtin_amdgcn_s_barrier()
;     __device__ __forceinline__ void operator()(const f32x4 (&acc)[2][2][4][2], const Unit& u, int wr, int wc, int fr, int fq) const {
;         const int row0 = u.pm * BM + wr * 64 + fr, col0 = u.pn * 128 + wc * 32 + 8 * fq;
; #pragma unroll
;         for (int ai = 0; ai < 2; ++ai)
; #pragma unroll
;             for (int m = 0; m < 4; ++m) {
;                 bf16_t* rowp = O + (size_t)(row0 + ai * HALF + m * 16) * DFF + col0;
;                 const f32x4 g0 = acc[ai][0][m][0], g1 = acc[ai][0][m][1], u0 = acc[ai][1][m][0], u1 = acc[ai][1][m][1];
;                 u32x4 w;
;                 w.x = cvt_pk_bf16(silu_fast(g0[0]) * u0[0], silu_fast(g0[1]) * u0[1]);
;                 w.y = cvt_pk_bf16(silu_fast(g0[2]) * u0[2], silu_fast(g0[3]) * u0[3]);
;                 w.z = cvt_pk_bf16(silu_fast(g1[0]) * u1[0], silu_fast(g1[1]) * u1[1]);
;                 w.w = cvt_pk_bf16(silu_fast(g1[2]) * u1[2], silu_fast(g1[3]) * u1[3]);
;                 *(u32x4*)rowp = w;
;             }
;     }
; template <class Epi>
; __device__ __forceinline__ void gemm_phase(LAS unsigned char* lds, const Gemm g, const Order& S, KP kp, int code, int wv) {
;     ...
;         if (!has_next) break;
; #pragma unroll
;         for (int a = 0; a < 2; ++a)
; #pragma unroll
;             for (int b = 0; b < 2; ++b)
; #pragma unroll
;                 for (int m = 0; m < 4; ++m)
; #pragma unroll
;                     for (int n = 0; n < 2; ++n) acc[a][b][m][n] = (f32x4){0.f, 0.f, 0.f, 0.f};
;         cur = nxt; cA = nA; cB = nB; ++ui;
;     }
;     PG8_WAIT_V(0);
;     if (wr == 0) PG8_BAR;
;     PG8_BAR;
	v_rcp_f32_e32 v60, v60
	s_nop 0
	v_mul_f32_e32 v54, v54, v60
	v_mul_f32_e32 v50, v50, v54
	v_mul_f32_e32 v54, 0xbfb8aa3b, v55
	v_exp_f32_e32 v54, v54
	s_nop 0
	v_add_f32_e32 v54, 1.0, v54
	v_rcp_f32_e32 v54, v54
	s_nop 0
	v_mul_f32_e32 v54, v55, v54
	v_mul_f32_e32 v51, v51, v54
	v_cvt_pk_bf16_f32 v60, v50, v51
	v_mul_f32_e32 v50, 0xbfb8aa3b, v56
	v_exp_f32_e32 v50, v50
	v_mul_f32_e32 v51, 0xbfb8aa3b, v57
	v_exp_f32_e32 v51, v51
	v_add_f32_e32 v50, 1.0, v50
	v_rcp_f32_e32 v50, v50
	v_add_f32_e32 v51, 1.0, v51
	v_rcp_f32_e32 v51, v51
	v_mul_f32_e32 v50, v56, v50
	v_mul_f32_e32 v50, v52, v50
	v_mul_f32_e32 v52, 0xbfb8aa3b, v46
	v_exp_f32_e32 v52, v52
	v_mul_f32_e32 v51, v57, v51
	v_mul_f32_e32 v51, v53, v51
	v_cvt_pk_bf16_f32 v61, v50, v51
	v_add_f32_e32 v52, 1.0, v52
	v_rcp_f32_e32 v52, v52
	v_add_u32_e32 v50, 0x90, v148
	v_mad_i64_i32 v[50:51], s[0:1], v50, s95, v[140:141]
	v_mul_f32_e32 v46, v46, v52
	v_mul_f32_e32 v42, v42, v46
	v_mul_f32_e32 v46, 0xbfb8aa3b, v47
	v_exp_f32_e32 v46, v46
	global_store_dwordx4 v[66:67], v[58:61], off
	v_add_f32_e32 v46, 1.0, v46
	v_rcp_f32_e32 v46, v46
	s_nop 0
	v_mul_f32_e32 v46, v47, v46
	v_mul_f32_e32 v43, v43, v46
	v_cvt_pk_bf16_f32 v42, v42, v43
	v_mul_f32_e32 v43, 0xbfb8aa3b, v48
	v_exp_f32_e32 v43, v43
	s_nop 0
	v_add_f32_e32 v43, 1.0, v43
	v_rcp_f32_e32 v43, v43
	s_nop 0
	v_mul_f32_e32 v43, v48, v43
	v_mul_f32_e32 v43, v44, v43
	v_mul_f32_e32 v44, 0xbfb8aa3b, v49
	v_exp_f32_e32 v44, v44
	s_nop 0
	v_add_f32_e32 v44, 1.0, v44
	v_rcp_f32_e32 v44, v44
	s_nop 0
	v_mul_f32_e32 v44, v49, v44
	v_mul_f32_e32 v44, v45, v44
	v_cvt_pk_bf16_f32 v43, v43, v44
	v_mul_f32_e32 v44, 0xbfb8aa3b, v38
	v_exp_f32_e32 v44, v44
	s_nop 0
	v_add_f32_e32 v44, 1.0, v44
	v_rcp_f32_e32 v44, v44
	s_nop 0
	v_mul_f32_e32 v38, v38, v44
	v_mul_f32_e32 v34, v34, v38
	v_mul_f32_e32 v38, 0xbfb8aa3b, v39
	v_exp_f32_e32 v38, v38
	s_nop 0
	v_add_f32_e32 v38, 1.0, v38
	v_rcp_f32_e32 v38, v38
	s_nop 0
	v_mul_f32_e32 v38, v39, v38
	v_mul_f32_e32 v35, v35, v38
	v_cvt_pk_bf16_f32 v44, v34, v35
	v_mul_f32_e32 v34, 0xbfb8aa3b, v40
	v_exp_f32_e32 v34, v34
	v_mul_f32_e32 v35, 0xbfb8aa3b, v41
	v_exp_f32_e32 v35, v35
	v_add_f32_e32 v34, 1.0, v34
	v_rcp_f32_e32 v34, v34
	v_add_f32_e32 v35, 1.0, v35
	v_rcp_f32_e32 v35, v35
	v_mul_f32_e32 v34, v40, v34
	v_mul_f32_e32 v34, v36, v34
	v_mul_f32_e32 v36, 0xbfb8aa3b, v30
	v_exp_f32_e32 v36, v36
	v_mul_f32_e32 v35, v41, v35
	v_mul_f32_e32 v35, v37, v35
	v_cvt_pk_bf16_f32 v45, v34, v35
	v_add_f32_e32 v36, 1.0, v36
	v_rcp_f32_e32 v36, v36
	v_add_u32_e32 v34, 0xa0, v148
	v_mad_i64_i32 v[34:35], s[0:1], v34, s95, v[140:141]
	v_mul_f32_e32 v30, v30, v36
	v_mul_f32_e32 v26, v26, v30
	v_mul_f32_e32 v30, 0xbfb8aa3b, v31
	v_exp_f32_e32 v30, v30
	global_store_dwordx4 v[50:51], v[42:45], off
	v_add_f32_e32 v30, 1.0, v30
	v_rcp_f32_e32 v30, v30
	s_nop 0
	v_mul_f32_e32 v30, v31, v30
	v_mul_f32_e32 v27, v27, v30
	v_cvt_pk_bf16_f32 v26, v26, v27
	v_mul_f32_e32 v27, 0xbfb8aa3b, v32
	v_exp_f32_e32 v27, v27
	s_nop 0
	v_add_f32_e32 v27, 1.0, v27
	v_rcp_f32_e32 v27, v27
	s_nop 0
	v_mul_f32_e32 v27, v32, v27
	v_mul_f32_e32 v27, v28, v27
	v_mul_f32_e32 v28, 0xbfb8aa3b, v33
	v_exp_f32_e32 v28, v28
	s_nop 0
	v_add_f32_e32 v28, 1.0, v28
	v_rcp_f32_e32 v28, v28
	s_nop 0
	v_mul_f32_e32 v28, v33, v28
	v_mul_f32_e32 v28, v29, v28
	v_cvt_pk_bf16_f32 v27, v27, v28
	v_mul_f32_e32 v28, 0xbfb8aa3b, v22
	v_exp_f32_e32 v28, v28
	s_nop 0
	v_add_f32_e32 v28, 1.0, v28
	v_rcp_f32_e32 v28, v28
	s_nop 0
	v_mul_f32_e32 v22, v22, v28
	v_mul_f32_e32 v18, v18, v22
	v_mul_f32_e32 v22, 0xbfb8aa3b, v23
	v_exp_f32_e32 v22, v22
	s_nop 0
	v_add_f32_e32 v22, 1.0, v22
	v_rcp_f32_e32 v22, v22
	s_nop 0
	v_mul_f32_e32 v22, v23, v22
	v_mul_f32_e32 v19, v19, v22
	v_cvt_pk_bf16_f32 v28, v18, v19
	v_mul_f32_e32 v18, 0xbfb8aa3b, v24
	v_exp_f32_e32 v18, v18
	v_mul_f32_e32 v19, 0xbfb8aa3b, v25
	v_exp_f32_e32 v19, v19
	v_add_f32_e32 v18, 1.0, v18
	v_rcp_f32_e32 v18, v18
	v_add_f32_e32 v19, 1.0, v19
	v_rcp_f32_e32 v19, v19
	v_mul_f32_e32 v18, v24, v18
	v_mul_f32_e32 v18, v20, v18
	v_mul_f32_e32 v20, 0xbfb8aa3b, v14
	v_exp_f32_e32 v20, v20
	v_mul_f32_e32 v19, v25, v19
	v_mul_f32_e32 v19, v21, v19
	v_cvt_pk_bf16_f32 v29, v18, v19
	v_add_f32_e32 v20, 1.0, v20
	v_rcp_f32_e32 v20, v20
	v_add_u32_e32 v18, 0xb0, v148
	v_mad_i64_i32 v[18:19], s[0:1], v18, s95, v[140:141]
	v_mul_f32_e32 v14, v14, v20
	v_mul_f32_e32 v10, v10, v14
	v_mul_f32_e32 v14, 0xbfb8aa3b, v15
	v_exp_f32_e32 v14, v14
	global_store_dwordx4 v[34:35], v[26:29], off
	v_add_f32_e32 v14, 1.0, v14
	v_rcp_f32_e32 v14, v14
	s_nop 0
	v_mul_f32_e32 v14, v15, v14
	v_mul_f32_e32 v11, v11, v14
	v_cvt_pk_bf16_f32 v10, v10, v11
	v_mul_f32_e32 v11, 0xbfb8aa3b, v16
	v_exp_f32_e32 v11, v11
	s_nop 0
	v_add_f32_e32 v11, 1.0, v11
	v_rcp_f32_e32 v11, v11
	s_nop 0
	v_mul_f32_e32 v11, v16, v11
	v_mul_f32_e32 v11, v12, v11
	v_mul_f32_e32 v12, 0xbfb8aa3b, v17
	v_exp_f32_e32 v12, v12
	s_nop 0
	v_add_f32_e32 v12, 1.0, v12
	v_rcp_f32_e32 v12, v12
	s_nop 0
	v_mul_f32_e32 v12, v17, v12
	v_mul_f32_e32 v12, v13, v12
	v_cvt_pk_bf16_f32 v11, v11, v12
	v_mul_f32_e32 v12, 0xbfb8aa3b, v6
	v_exp_f32_e32 v12, v12
	s_nop 0
	v_add_f32_e32 v12, 1.0, v12
	v_rcp_f32_e32 v12, v12
	s_nop 0
	v_mul_f32_e32 v6, v6, v12
	v_mul_f32_e32 v2, v2, v6
	v_mul_f32_e32 v6, 0xbfb8aa3b, v7
	v_exp_f32_e32 v6, v6
	s_nop 0
	v_add_f32_e32 v6, 1.0, v6
	v_rcp_f32_e32 v6, v6
	s_nop 0
	v_mul_f32_e32 v6, v7, v6
	v_mul_f32_e32 v3, v3, v6
	v_cvt_pk_bf16_f32 v12, v2, v3
	v_mul_f32_e32 v2, 0xbfb8aa3b, v8
	v_mul_f32_e32 v3, 0xbfb8aa3b, v9
	v_exp_f32_e32 v2, v2
	v_exp_f32_e32 v3, v3
	v_add_f32_e32 v2, 1.0, v2
	v_add_f32_e32 v3, 1.0, v3
	v_rcp_f32_e32 v2, v2
	v_rcp_f32_e32 v3, v3
	v_mul_f32_e32 v2, v8, v2
	v_mul_f32_e32 v3, v9, v3
	v_mul_f32_e32 v2, v4, v2
	v_mul_f32_e32 v3, v5, v3
	v_cvt_pk_bf16_f32 v13, v2, v3
	global_store_dwordx4 v[18:19], v[10:13], off
	s_cbranch_vccz .LBB0_547
	s_waitcnt vmcnt(0)
	s_cmpk_gt_u32 s23, 0xff
	s_mov_b32 s35, 0x3f2aaaab
	s_cbranch_scc1 .LBB0_554
	s_barrier

; __global__ void __launch_bounds__(512, 2) fwd_mega(Params p_unused) {
	.amdhsa_kernel _Z8fwd_mega6Params
		.amdhsa_group_segment_fixed_size 0
		.amdhsa_private_segment_fixed_size 0
		.amdhsa_kernarg_size 464
		.amdhsa_user_sgpr_count 2
		.amdhsa_user_sgpr_dispatch_ptr 0
		.amdhsa_user_sgpr_queue_ptr 0
		.amdhsa_user_sgpr_kernarg_segment_ptr 1
		.amdhsa_user_sgpr_dispatch_id 0
		.amdhsa_user_sgpr_kernarg_preload_length 0
		.amdhsa_user_sgpr_kernarg_preload_offset 0
		.amdhsa_user_sgpr_private_segment_size 0
		.amdhsa_uses_dynamic_stack 0
		.amdhsa_enable_private_segment 0
		.amdhsa_system_sgpr_workgroup_id_x 1
		.amdhsa_system_sgpr_workgroup_id_y 0
		.amdhsa_system_sgpr_workgroup_id_z 0
		.amdhsa_system_sgpr_workgroup_info 0
		.amdhsa_system_vgpr_workitem_id 2
		.amdhsa_next_free_vgpr 256
		.amdhsa_next_free_sgpr 102
		.amdhsa_accum_offset 256
		.amdhsa_reserve_vcc 1
		.amdhsa_float_round_mode_32 0
		.amdhsa_float_round_mode_16_64 0
		.amdhsa_float_denorm_mode_32 3
		.amdhsa_float_denorm_mode_16_64 3
		.amdhsa_dx10_clamp 1
		.amdhsa_ieee_mode 1
		.amdhsa_fp16_overflow 0
		.amdhsa_tg_split 0
		.amdhsa_exception_fp_ieee_invalid_op 0
		.amdhsa_exception_fp_denorm_src 0
		.amdhsa_exception_fp_ieee_div_zero 0
		.amdhsa_exception_fp_ieee_overflow 0
		.amdhsa_exception_fp_ieee_underflow 0
		.amdhsa_exception_fp_ieee_inexact 0
		.amdhsa_exception_int_div_zero 0
	.end_amdhsa_kernel

; __global__ void __launch_bounds__(512, 2) fwd_mega(Params p_unused) {
amdhsa.kernels:
  - .agpr_count:     0
    .args:
      - .offset:         0
        .size:           208
        .value_kind:     by_value
      - .offset:         208
        .size:           4
        .value_kind:     hidden_block_count_x
      - .offset:         212
        .size:           4
        .value_kind:     hidden_block_count_y
      - .offset:         216
        .size:           4
        .value_kind:     hidden_block_count_z
      - .offset:         220
        .size:           2
        .value_kind:     hidden_group_size_x
      - .offset:         222
        .size:           2
        .value_kind:     hidden_group_size_y
      - .offset:         224
        .size:           2
        .value_kind:     hidden_group_size_z
      - .offset:         226
        .size:           2
        .value_kind:     hidden_remainder_x
      - .offset:         228
        .size:           2
        .value_kind:     hidden_remainder_y
      - .offset:         230
        .size:           2
        .value_kind:     hidden_remainder_z
      - .offset:         248
        .size:           8
        .value_kind:     hidden_global_offset_x
      - .offset:         256
        .size:           8
        .value_kind:     hidden_global_offset_y
      - .offset:         264
        .size:           8
        .value_kind:     hidden_global_offset_z
      - .offset:         272
        .size:           2
        .value_kind:     hidden_grid_dims
      - .offset:         296
        .size:           8
        .value_kind:     hidden_multigrid_sync_arg
      - .offset:         328
        .size:           4
        .value_kind:     hidden_dynamic_lds_size
    .group_segment_fixed_size: 0
    .kernarg_segment_align: 8
    .kernarg_segment_size: 464
    .language:       OpenCL C
    .language_version:
      - 2
      - 0
    .max_flat_workgroup_size: 512
    .name:           _Z8fwd_mega6Params
    .private_segment_fixed_size: 0
    .sgpr_count:     108
    .sgpr_spill_count: 232
    .symbol:         _Z8fwd_mega6Params.kd
    .uniform_work_group_size: 1
    .uses_dynamic_stack: false
    .vgpr_count:     256
    .vgpr_spill_count: 0
    .wavefront_size: 64
